# drop the s_setprio 0/1 pair between the two 16-MFMA blocks of each MMA segment (priority stays 1 through the 32 MFMAs)
# baseline (speedup 1.0000x reference)
.LBB0_552:
	s_add_u32 s54, s44, 0xfff80080
	s_addc_u32 s55, s45, -1
	s_waitcnt lgkmcnt(0)
	s_add_i32 s82, 0, 0x10000
	s_cmp_eq_u32 s76, 28
	s_cselect_b32 s57, s41, s55
	s_cselect_b32 s56, s43, s54
	v_add_u32_e32 v161, s82, v159
	s_cselect_b32 s55, s35, s75
	s_cselect_b32 s54, s47, s74
	s_add_i32 vcc_lo, 0, 0x14000
	ds_read_b128 v[144:147], v161
	ds_read_b128 v[148:151], v161 offset:1024
	ds_read_b128 v[152:155], v161 offset:2048
	ds_read_b128 v[162:165], v161 offset:3072
	v_add_u32_e32 v161, vcc_lo, v159
	ds_read_b128 v[166:169], v161
	ds_read_b128 v[170:173], v161 offset:1024
	ds_read_b128 v[174:177], v161 offset:2048
	ds_read_b128 v[190:193], v161 offset:3072
	v_lshl_add_u64 v[178:179], s[44:45], 0, v[140:141]
	s_add_i32 m0, s58, 0xc000
	ds_read_b128 v[194:197], v160
	ds_read_b128 v[198:201], v160 offset:1024
	ds_read_b128 v[202:205], v160 offset:2048
	ds_read_b128 v[206:209], v160 offset:3072
	ds_read_b128 v[210:213], v160 offset:4096
	ds_read_b128 v[214:217], v160 offset:5120
	ds_read_b128 v[218:221], v160 offset:6144
	ds_read_b128 v[238:241], v160 offset:7168
	global_load_lds_dwordx4 v[178:179], off
	v_lshl_add_u64 v[178:179], s[44:45], 0, v[142:143]
	s_add_i32 m0, s58, 0xe000
	s_nop 0
	global_load_lds_dwordx4 v[178:179], off
	s_waitcnt vmcnt(8)
	s_waitcnt lgkmcnt(0)
	s_barrier
	s_setprio 1
	s_waitcnt lgkmcnt(0)
	v_mfma_f32_16x16x32_bf16 v[126:129], v[144:147], v[194:197], v[126:129]
	v_mfma_f32_16x16x32_bf16 v[122:125], v[152:155], v[194:197], v[122:125]
	v_mfma_f32_16x16x32_bf16 v[110:113], v[144:147], v[202:205], v[110:113]
	v_mfma_f32_16x16x32_bf16 v[106:109], v[152:155], v[202:205], v[106:109]
	v_mfma_f32_16x16x32_bf16 v[94:97], v[144:147], v[210:213], v[94:97]
	v_mfma_f32_16x16x32_bf16 v[90:93], v[152:155], v[210:213], v[90:93]
	v_mfma_f32_16x16x32_bf16 v[78:81], v[144:147], v[218:221], v[78:81]
	v_mfma_f32_16x16x32_bf16 v[74:77], v[152:155], v[218:221], v[74:77]
	v_mfma_f32_16x16x32_bf16 v[126:129], v[148:151], v[198:201], v[126:129]
	v_mfma_f32_16x16x32_bf16 v[122:125], v[162:165], v[198:201], v[122:125]
	v_mfma_f32_16x16x32_bf16 v[110:113], v[148:151], v[206:209], v[110:113]
	v_mfma_f32_16x16x32_bf16 v[106:109], v[162:165], v[206:209], v[106:109]
	v_mfma_f32_16x16x32_bf16 v[94:97], v[148:151], v[214:217], v[94:97]
	v_mfma_f32_16x16x32_bf16 v[90:93], v[162:165], v[214:217], v[90:93]
	v_mfma_f32_16x16x32_bf16 v[78:81], v[148:151], v[238:241], v[78:81]
	v_mfma_f32_16x16x32_bf16 v[74:77], v[162:165], v[238:241], v[74:77]
	v_mfma_f32_16x16x32_bf16 v[118:121], v[166:169], v[194:197], v[118:121]
	v_mfma_f32_16x16x32_bf16 v[114:117], v[174:177], v[194:197], v[114:117]
	v_mfma_f32_16x16x32_bf16 v[102:105], v[166:169], v[202:205], v[102:105]
	v_mfma_f32_16x16x32_bf16 v[98:101], v[174:177], v[202:205], v[98:101]
	v_mfma_f32_16x16x32_bf16 v[86:89], v[166:169], v[210:213], v[86:89]
	v_mfma_f32_16x16x32_bf16 v[82:85], v[174:177], v[210:213], v[82:85]
	v_mfma_f32_16x16x32_bf16 v[70:73], v[166:169], v[218:221], v[70:73]
	v_mfma_f32_16x16x32_bf16 v[66:69], v[174:177], v[218:221], v[66:69]
	v_mfma_f32_16x16x32_bf16 v[118:121], v[170:173], v[198:201], v[118:121]
	v_mfma_f32_16x16x32_bf16 v[114:117], v[190:193], v[198:201], v[114:117]
	v_mfma_f32_16x16x32_bf16 v[102:105], v[170:173], v[206:209], v[102:105]
	v_mfma_f32_16x16x32_bf16 v[98:101], v[190:193], v[206:209], v[98:101]
	v_mfma_f32_16x16x32_bf16 v[86:89], v[170:173], v[214:217], v[86:89]
	v_mfma_f32_16x16x32_bf16 v[82:85], v[190:193], v[214:217], v[82:85]
	v_mfma_f32_16x16x32_bf16 v[70:73], v[170:173], v[238:241], v[70:73]
	v_mfma_f32_16x16x32_bf16 v[66:69], v[190:193], v[238:241], v[66:69]
	s_setprio 0
	s_barrier
	s_add_i32 s82, s82, s9
	v_lshl_add_u64 v[178:179], s[54:55], 0, v[134:135]
	s_mov_b32 m0, s82
	ds_read_b128 v[194:197], v160 offset:16384
	ds_read_b128 v[198:201], v160 offset:17408
	ds_read_b128 v[202:205], v160 offset:18432
	ds_read_b128 v[206:209], v160 offset:19456
	ds_read_b128 v[210:213], v160 offset:20480
	ds_read_b128 v[214:217], v160 offset:21504
	ds_read_b128 v[218:221], v160 offset:22528
	ds_read_b128 v[238:241], v160 offset:23552
	global_load_lds_dwordx4 v[178:179], off
	s_add_i32 m0, s82, 0x2000
	s_add_u32 s82, s54, 0x80000
	v_lshl_add_u64 v[222:223], s[54:55], 0, v[138:139]
	s_addc_u32 s83, s55, 0
	s_add_i32 vcc_lo, vcc_lo, s9
	global_load_lds_dwordx4 v[222:223], off
	v_lshl_add_u64 v[242:243], s[82:83], 0, v[134:135]
	s_mov_b32 m0, vcc_lo
	v_lshl_add_u64 v[244:245], s[56:57], 0, v[136:137]
	global_load_lds_dwordx4 v[242:243], off
	v_lshl_add_u64 v[242:243], s[82:83], 0, v[138:139]
	s_add_i32 m0, vcc_lo, 0x2000
	s_nop 0
	global_load_lds_dwordx4 v[242:243], off
	v_lshl_add_u64 v[242:243], s[56:57], 0, v[132:133]
	s_mov_b32 m0, s58
	s_nop 0
	global_load_lds_dwordx4 v[242:243], off
	s_mov_b32 m0, s59
	s_nop 0
	global_load_lds_dwordx4 v[244:245], off
	s_waitcnt vmcnt(8)
	s_waitcnt lgkmcnt(0)
	s_barrier
	s_setprio 1
	s_waitcnt lgkmcnt(0)
	v_mfma_f32_16x16x32_bf16 v[62:65], v[144:147], v[194:197], v[62:65]
	v_mfma_f32_16x16x32_bf16 v[58:61], v[152:155], v[194:197], v[58:61]
	v_mfma_f32_16x16x32_bf16 v[46:49], v[144:147], v[202:205], v[46:49]
	v_mfma_f32_16x16x32_bf16 v[42:45], v[152:155], v[202:205], v[42:45]
	v_mfma_f32_16x16x32_bf16 v[30:33], v[144:147], v[210:213], v[30:33]
	v_mfma_f32_16x16x32_bf16 v[26:29], v[152:155], v[210:213], v[26:29]
	v_mfma_f32_16x16x32_bf16 v[14:17], v[144:147], v[218:221], v[14:17]
	v_mfma_f32_16x16x32_bf16 v[10:13], v[152:155], v[218:221], v[10:13]
	v_mfma_f32_16x16x32_bf16 v[62:65], v[148:151], v[198:201], v[62:65]
	v_mfma_f32_16x16x32_bf16 v[58:61], v[162:165], v[198:201], v[58:61]
	v_mfma_f32_16x16x32_bf16 v[46:49], v[148:151], v[206:209], v[46:49]
	v_mfma_f32_16x16x32_bf16 v[42:45], v[162:165], v[206:209], v[42:45]
	v_mfma_f32_16x16x32_bf16 v[30:33], v[148:151], v[214:217], v[30:33]
	v_mfma_f32_16x16x32_bf16 v[26:29], v[162:165], v[214:217], v[26:29]
	v_mfma_f32_16x16x32_bf16 v[14:17], v[148:151], v[238:241], v[14:17]
	v_mfma_f32_16x16x32_bf16 v[10:13], v[162:165], v[238:241], v[10:13]
	v_mfma_f32_16x16x32_bf16 v[54:57], v[166:169], v[194:197], v[54:57]
	v_mfma_f32_16x16x32_bf16 v[50:53], v[174:177], v[194:197], v[50:53]
	v_mfma_f32_16x16x32_bf16 v[38:41], v[166:169], v[202:205], v[38:41]
	v_mfma_f32_16x16x32_bf16 v[34:37], v[174:177], v[202:205], v[34:37]
	v_mfma_f32_16x16x32_bf16 v[22:25], v[166:169], v[210:213], v[22:25]
	v_mfma_f32_16x16x32_bf16 v[18:21], v[174:177], v[210:213], v[18:21]
	v_mfma_f32_16x16x32_bf16 v[6:9], v[166:169], v[218:221], v[6:9]
	v_mfma_f32_16x16x32_bf16 v[2:5], v[174:177], v[218:221], v[2:5]
	v_mfma_f32_16x16x32_bf16 v[54:57], v[170:173], v[198:201], v[54:57]
	v_mfma_f32_16x16x32_bf16 v[50:53], v[190:193], v[198:201], v[50:53]
	v_mfma_f32_16x16x32_bf16 v[38:41], v[170:173], v[206:209], v[38:41]
	v_mfma_f32_16x16x32_bf16 v[34:37], v[190:193], v[206:209], v[34:37]
	v_mfma_f32_16x16x32_bf16 v[22:25], v[170:173], v[214:217], v[22:25]
	v_mfma_f32_16x16x32_bf16 v[18:21], v[190:193], v[214:217], v[18:21]
	v_mfma_f32_16x16x32_bf16 v[6:9], v[170:173], v[238:241], v[6:9]
	v_mfma_f32_16x16x32_bf16 v[2:5], v[190:193], v[238:241], v[2:5]
	s_setprio 0
	s_barrier
	s_add_i32 s82, 0, 0x18000
	v_add_u32_e32 v161, s82, v159
	s_add_i32 s83, 0, 0x1c000
	ds_read_b128 v[144:147], v161
	ds_read_b128 v[148:151], v161 offset:1024
	ds_read_b128 v[152:155], v161 offset:2048
	ds_read_b128 v[162:165], v161 offset:3072
	v_add_u32_e32 v161, s83, v159
	ds_read_b128 v[166:169], v161
	ds_read_b128 v[170:173], v161 offset:1024
	ds_read_b128 v[174:177], v161 offset:2048
	ds_read_b128 v[190:193], v161 offset:3072
	s_add_u32 s56, s56, 0x80000
	s_addc_u32 s57, s57, 0
	s_mov_b32 m0, s60
	v_lshl_add_u64 v[246:247], s[56:57], 0, v[132:133]
	ds_read_b128 v[194:197], v160 offset:32768
	ds_read_b128 v[198:201], v160 offset:33792
	ds_read_b128 v[202:205], v160 offset:34816
	ds_read_b128 v[206:209], v160 offset:35840
	ds_read_b128 v[210:213], v160 offset:36864
	ds_read_b128 v[214:217], v160 offset:37888
	ds_read_b128 v[218:221], v160 offset:38912
	ds_read_b128 v[238:241], v160 offset:39936
	global_load_lds_dwordx4 v[246:247], off
	v_lshl_add_u64 v[246:247], s[56:57], 0, v[136:137]
	s_mov_b32 m0, s61
	s_nop 0
	global_load_lds_dwordx4 v[246:247], off
	s_waitcnt vmcnt(8)
	s_waitcnt lgkmcnt(0)
	s_barrier
	s_setprio 1
	s_waitcnt lgkmcnt(0)
	v_mfma_f32_16x16x32_bf16 v[126:129], v[144:147], v[194:197], v[126:129]
	v_mfma_f32_16x16x32_bf16 v[122:125], v[152:155], v[194:197], v[122:125]
	v_mfma_f32_16x16x32_bf16 v[110:113], v[144:147], v[202:205], v[110:113]
	v_mfma_f32_16x16x32_bf16 v[106:109], v[152:155], v[202:205], v[106:109]
	v_mfma_f32_16x16x32_bf16 v[94:97], v[144:147], v[210:213], v[94:97]
	v_mfma_f32_16x16x32_bf16 v[90:93], v[152:155], v[210:213], v[90:93]
	v_mfma_f32_16x16x32_bf16 v[78:81], v[144:147], v[218:221], v[78:81]
	v_mfma_f32_16x16x32_bf16 v[74:77], v[152:155], v[218:221], v[74:77]
	v_mfma_f32_16x16x32_bf16 v[126:129], v[148:151], v[198:201], v[126:129]
	v_mfma_f32_16x16x32_bf16 v[122:125], v[162:165], v[198:201], v[122:125]
	v_mfma_f32_16x16x32_bf16 v[110:113], v[148:151], v[206:209], v[110:113]
	v_mfma_f32_16x16x32_bf16 v[106:109], v[162:165], v[206:209], v[106:109]
	v_mfma_f32_16x16x32_bf16 v[94:97], v[148:151], v[214:217], v[94:97]
	v_mfma_f32_16x16x32_bf16 v[90:93], v[162:165], v[214:217], v[90:93]
	v_mfma_f32_16x16x32_bf16 v[78:81], v[148:151], v[238:241], v[78:81]
	v_mfma_f32_16x16x32_bf16 v[74:77], v[162:165], v[238:241], v[74:77]
	v_mfma_f32_16x16x32_bf16 v[118:121], v[166:169], v[194:197], v[118:121]
	v_mfma_f32_16x16x32_bf16 v[114:117], v[174:177], v[194:197], v[114:117]
	v_mfma_f32_16x16x32_bf16 v[102:105], v[166:169], v[202:205], v[102:105]
	v_mfma_f32_16x16x32_bf16 v[98:101], v[174:177], v[202:205], v[98:101]
	v_mfma_f32_16x16x32_bf16 v[86:89], v[166:169], v[210:213], v[86:89]
	v_mfma_f32_16x16x32_bf16 v[82:85], v[174:177], v[210:213], v[82:85]
	v_mfma_f32_16x16x32_bf16 v[70:73], v[166:169], v[218:221], v[70:73]
	v_mfma_f32_16x16x32_bf16 v[66:69], v[174:177], v[218:221], v[66:69]
	v_mfma_f32_16x16x32_bf16 v[118:121], v[170:173], v[198:201], v[118:121]
	v_mfma_f32_16x16x32_bf16 v[114:117], v[190:193], v[198:201], v[114:117]
	v_mfma_f32_16x16x32_bf16 v[102:105], v[170:173], v[206:209], v[102:105]
	v_mfma_f32_16x16x32_bf16 v[98:101], v[190:193], v[206:209], v[98:101]
	v_mfma_f32_16x16x32_bf16 v[86:89], v[170:173], v[214:217], v[86:89]
	v_mfma_f32_16x16x32_bf16 v[82:85], v[190:193], v[214:217], v[82:85]
	v_mfma_f32_16x16x32_bf16 v[70:73], v[170:173], v[238:241], v[70:73]
	v_mfma_f32_16x16x32_bf16 v[66:69], v[190:193], v[238:241], v[66:69]
	s_setprio 0
	s_barrier
	s_add_i32 s56, s82, s9
	v_lshl_add_u64 v[178:179], v[178:179], 0, s[16:17]
	s_mov_b32 m0, s56
	ds_read_b128 v[194:197], v160 offset:49152
	ds_read_b128 v[198:201], v160 offset:50176
	ds_read_b128 v[202:205], v160 offset:51200
	ds_read_b128 v[206:209], v160 offset:52224
	ds_read_b128 v[210:213], v160 offset:53248
	ds_read_b128 v[214:217], v160 offset:54272
	ds_read_b128 v[218:221], v160 offset:55296
	ds_read_b128 v[238:241], v160 offset:56320
	global_load_lds_dwordx4 v[178:179], off
	s_add_i32 m0, s56, 0x2000
	s_add_u32 s54, s54, 0x80080
	v_lshl_add_u64 v[178:179], v[222:223], 0, s[16:17]
	s_addc_u32 s55, s55, 0
	s_add_i32 s56, s83, s9
	global_load_lds_dwordx4 v[178:179], off
	v_lshl_add_u64 v[178:179], s[54:55], 0, v[134:135]
	s_mov_b32 m0, s56
	s_nop 0
	global_load_lds_dwordx4 v[178:179], off
	v_lshl_add_u64 v[178:179], s[54:55], 0, v[138:139]
	s_add_i32 m0, s56, 0x2000
	s_nop 0
	global_load_lds_dwordx4 v[178:179], off
	v_lshl_add_u64 v[178:179], v[242:243], 0, s[16:17]
	s_mov_b32 m0, s64
	s_nop 0
	global_load_lds_dwordx4 v[178:179], off
	v_lshl_add_u64 v[178:179], v[244:245], 0, s[16:17]
	s_mov_b32 m0, s69
	s_nop 0
	global_load_lds_dwordx4 v[178:179], off
	s_waitcnt vmcnt(8)
	s_waitcnt lgkmcnt(0)
	s_barrier
	s_setprio 1
	s_waitcnt lgkmcnt(0)
	v_mfma_f32_16x16x32_bf16 v[62:65], v[144:147], v[194:197], v[62:65]
	v_mfma_f32_16x16x32_bf16 v[58:61], v[152:155], v[194:197], v[58:61]
	v_mfma_f32_16x16x32_bf16 v[46:49], v[144:147], v[202:205], v[46:49]
	v_mfma_f32_16x16x32_bf16 v[42:45], v[152:155], v[202:205], v[42:45]
	v_mfma_f32_16x16x32_bf16 v[30:33], v[144:147], v[210:213], v[30:33]
	v_mfma_f32_16x16x32_bf16 v[26:29], v[152:155], v[210:213], v[26:29]
	v_mfma_f32_16x16x32_bf16 v[14:17], v[144:147], v[218:221], v[14:17]
	v_mfma_f32_16x16x32_bf16 v[10:13], v[152:155], v[218:221], v[10:13]
	v_mfma_f32_16x16x32_bf16 v[62:65], v[148:151], v[198:201], v[62:65]
	v_mfma_f32_16x16x32_bf16 v[58:61], v[162:165], v[198:201], v[58:61]
	v_mfma_f32_16x16x32_bf16 v[46:49], v[148:151], v[206:209], v[46:49]
	v_mfma_f32_16x16x32_bf16 v[42:45], v[162:165], v[206:209], v[42:45]
	v_mfma_f32_16x16x32_bf16 v[30:33], v[148:151], v[214:217], v[30:33]
	v_mfma_f32_16x16x32_bf16 v[26:29], v[162:165], v[214:217], v[26:29]
	v_mfma_f32_16x16x32_bf16 v[14:17], v[148:151], v[238:241], v[14:17]
	v_mfma_f32_16x16x32_bf16 v[10:13], v[162:165], v[238:241], v[10:13]
	v_mfma_f32_16x16x32_bf16 v[54:57], v[166:169], v[194:197], v[54:57]
	v_mfma_f32_16x16x32_bf16 v[50:53], v[174:177], v[194:197], v[50:53]
	v_mfma_f32_16x16x32_bf16 v[38:41], v[166:169], v[202:205], v[38:41]
	v_mfma_f32_16x16x32_bf16 v[34:37], v[174:177], v[202:205], v[34:37]
	v_mfma_f32_16x16x32_bf16 v[22:25], v[166:169], v[210:213], v[22:25]
	v_mfma_f32_16x16x32_bf16 v[18:21], v[174:177], v[210:213], v[18:21]
	v_mfma_f32_16x16x32_bf16 v[6:9], v[166:169], v[218:221], v[6:9]
	v_mfma_f32_16x16x32_bf16 v[2:5], v[174:177], v[218:221], v[2:5]
	v_mfma_f32_16x16x32_bf16 v[54:57], v[170:173], v[198:201], v[54:57]
	v_mfma_f32_16x16x32_bf16 v[50:53], v[190:193], v[198:201], v[50:53]
	v_mfma_f32_16x16x32_bf16 v[38:41], v[170:173], v[206:209], v[38:41]
	v_mfma_f32_16x16x32_bf16 v[34:37], v[190:193], v[206:209], v[34:37]
	v_mfma_f32_16x16x32_bf16 v[22:25], v[170:173], v[214:217], v[22:25]
	v_mfma_f32_16x16x32_bf16 v[18:21], v[190:193], v[214:217], v[18:21]
	v_mfma_f32_16x16x32_bf16 v[6:9], v[170:173], v[238:241], v[6:9]
	v_mfma_f32_16x16x32_bf16 v[2:5], v[190:193], v[238:241], v[2:5]
	s_setprio 0
	s_barrier
	s_add_i32 s76, s76, 2
	s_add_u32 s44, s44, 0x100
	s_addc_u32 s45, s45, 0
	s_add_u32 s74, s74, 0x100
	s_addc_u32 s75, s75, 0
	s_cmp_gt_u32 s76, 29
	s_cbranch_scc0 .LBB0_552
	s_and_b64 vcc, exec, s[30:31]
	s_cbranch_vccz .LBB0_555
	s_barrier

.LBB0_824:
	s_add_i32 s64, s40, 2
	s_add_u32 s69, s34, 0x80
	s_addc_u32 s41, s35, 0
	s_add_i32 s74, 0, 0x10000
	s_cmp_eq_u32 s57, s40
	s_cselect_b32 s41, s29, s41
	s_cselect_b32 s40, s28, s69
	v_add_u32_e32 v148, s74, v146
	s_cselect_b32 s71, s31, s63
	s_cselect_b32 s70, s30, s62
	s_add_i32 s69, 0, 0x14000
	ds_read_b128 v[154:157], v148
	ds_read_b128 v[158:161], v148 offset:1024
	ds_read_b128 v[162:165], v148 offset:2048
	ds_read_b128 v[166:169], v148 offset:3072
	v_add_u32_e32 v148, s69, v146
	ds_read_b128 v[170:173], v148
	ds_read_b128 v[174:177], v148 offset:1024
	ds_read_b128 v[190:193], v148 offset:2048
	ds_read_b128 v[194:197], v148 offset:3072
	v_lshl_add_u64 v[148:149], s[34:35], 0, v[140:141]
	s_add_i32 m0, s45, 0xc000
	ds_read_b128 v[198:201], v147
	ds_read_b128 v[202:205], v147 offset:1024
	ds_read_b128 v[206:209], v147 offset:2048
	ds_read_b128 v[210:213], v147 offset:3072
	ds_read_b128 v[214:217], v147 offset:4096
	ds_read_b128 v[218:221], v147 offset:5120
	ds_read_b128 v[238:241], v147 offset:6144
	ds_read_b128 v[242:245], v147 offset:7168
	global_load_lds_dwordx4 v[148:149], off
	v_lshl_add_u64 v[148:149], s[34:35], 0, v[142:143]
	s_add_i32 m0, s45, 0xe000
	s_nop 0
	global_load_lds_dwordx4 v[148:149], off
	s_waitcnt vmcnt(8)
	s_waitcnt lgkmcnt(0)
	s_barrier
	s_setprio 1
	s_waitcnt lgkmcnt(0)
	v_mfma_f32_16x16x32_bf16 v[126:129], v[154:157], v[198:201], v[126:129]
	v_mfma_f32_16x16x32_bf16 v[122:125], v[162:165], v[198:201], v[122:125]
	v_mfma_f32_16x16x32_bf16 v[110:113], v[154:157], v[206:209], v[110:113]
	v_mfma_f32_16x16x32_bf16 v[106:109], v[162:165], v[206:209], v[106:109]
	v_mfma_f32_16x16x32_bf16 v[94:97], v[154:157], v[214:217], v[94:97]
	v_mfma_f32_16x16x32_bf16 v[90:93], v[162:165], v[214:217], v[90:93]
	v_mfma_f32_16x16x32_bf16 v[78:81], v[154:157], v[238:241], v[78:81]
	v_mfma_f32_16x16x32_bf16 v[74:77], v[162:165], v[238:241], v[74:77]
	v_mfma_f32_16x16x32_bf16 v[126:129], v[158:161], v[202:205], v[126:129]
	v_mfma_f32_16x16x32_bf16 v[122:125], v[166:169], v[202:205], v[122:125]
	v_mfma_f32_16x16x32_bf16 v[110:113], v[158:161], v[210:213], v[110:113]
	v_mfma_f32_16x16x32_bf16 v[106:109], v[166:169], v[210:213], v[106:109]
	v_mfma_f32_16x16x32_bf16 v[94:97], v[158:161], v[218:221], v[94:97]
	v_mfma_f32_16x16x32_bf16 v[90:93], v[166:169], v[218:221], v[90:93]
	v_mfma_f32_16x16x32_bf16 v[78:81], v[158:161], v[242:245], v[78:81]
	v_mfma_f32_16x16x32_bf16 v[74:77], v[166:169], v[242:245], v[74:77]
	v_mfma_f32_16x16x32_bf16 v[118:121], v[170:173], v[198:201], v[118:121]
	v_mfma_f32_16x16x32_bf16 v[114:117], v[190:193], v[198:201], v[114:117]
	v_mfma_f32_16x16x32_bf16 v[102:105], v[170:173], v[206:209], v[102:105]
	v_mfma_f32_16x16x32_bf16 v[98:101], v[190:193], v[206:209], v[98:101]
	v_mfma_f32_16x16x32_bf16 v[86:89], v[170:173], v[214:217], v[86:89]
	v_mfma_f32_16x16x32_bf16 v[82:85], v[190:193], v[214:217], v[82:85]
	v_mfma_f32_16x16x32_bf16 v[70:73], v[170:173], v[238:241], v[70:73]
	v_mfma_f32_16x16x32_bf16 v[66:69], v[190:193], v[238:241], v[66:69]
	v_mfma_f32_16x16x32_bf16 v[118:121], v[174:177], v[202:205], v[118:121]
	v_mfma_f32_16x16x32_bf16 v[114:117], v[194:197], v[202:205], v[114:117]
	v_mfma_f32_16x16x32_bf16 v[102:105], v[174:177], v[210:213], v[102:105]
	v_mfma_f32_16x16x32_bf16 v[98:101], v[194:197], v[210:213], v[98:101]
	v_mfma_f32_16x16x32_bf16 v[86:89], v[174:177], v[218:221], v[86:89]
	v_mfma_f32_16x16x32_bf16 v[82:85], v[194:197], v[218:221], v[82:85]
	v_mfma_f32_16x16x32_bf16 v[70:73], v[174:177], v[242:245], v[70:73]
	v_mfma_f32_16x16x32_bf16 v[66:69], v[194:197], v[242:245], v[66:69]
	s_setprio 0
	s_barrier
	s_add_i32 s74, s74, s44
	v_lshl_add_u64 v[148:149], s[70:71], 0, v[136:137]
	s_mov_b32 m0, s74
	ds_read_b128 v[198:201], v147 offset:16384
	ds_read_b128 v[202:205], v147 offset:17408
	ds_read_b128 v[206:209], v147 offset:18432
	ds_read_b128 v[210:213], v147 offset:19456
	ds_read_b128 v[214:217], v147 offset:20480
	ds_read_b128 v[218:221], v147 offset:21504
	ds_read_b128 v[238:241], v147 offset:22528
	ds_read_b128 v[242:245], v147 offset:23552
	global_load_lds_dwordx4 v[148:149], off
	s_add_i32 m0, s74, 0x2000
	v_lshl_add_u64 v[178:179], s[70:71], 0, v[132:133]
	s_add_u32 s70, s70, s10
	s_addc_u32 s71, s71, s11
	s_add_i32 s69, s69, s44
	global_load_lds_dwordx4 v[178:179], off
	v_lshl_add_u64 v[222:223], s[70:71], 0, v[136:137]
	s_mov_b32 m0, s69
	v_lshl_add_u64 v[246:247], s[70:71], 0, v[132:133]
	global_load_lds_dwordx4 v[222:223], off
	s_add_i32 m0, s69, 0x2000
	v_lshl_add_u64 v[248:249], s[40:41], 0, v[138:139]
	global_load_lds_dwordx4 v[246:247], off
	s_mov_b32 m0, s45
	v_lshl_add_u64 v[250:251], s[40:41], 0, v[134:135]
	global_load_lds_dwordx4 v[248:249], off
	s_mov_b32 m0, s46
	s_nop 0
	global_load_lds_dwordx4 v[250:251], off
	s_waitcnt vmcnt(8)
	s_waitcnt lgkmcnt(0)
	s_barrier
	s_setprio 1
	s_waitcnt lgkmcnt(0)
	v_mfma_f32_16x16x32_bf16 v[62:65], v[154:157], v[198:201], v[62:65]
	v_mfma_f32_16x16x32_bf16 v[58:61], v[162:165], v[198:201], v[58:61]
	v_mfma_f32_16x16x32_bf16 v[46:49], v[154:157], v[206:209], v[46:49]
	v_mfma_f32_16x16x32_bf16 v[42:45], v[162:165], v[206:209], v[42:45]
	v_mfma_f32_16x16x32_bf16 v[30:33], v[154:157], v[214:217], v[30:33]
	v_mfma_f32_16x16x32_bf16 v[26:29], v[162:165], v[214:217], v[26:29]
	v_mfma_f32_16x16x32_bf16 v[14:17], v[154:157], v[238:241], v[14:17]
	v_mfma_f32_16x16x32_bf16 v[10:13], v[162:165], v[238:241], v[10:13]
	v_mfma_f32_16x16x32_bf16 v[62:65], v[158:161], v[202:205], v[62:65]
	v_mfma_f32_16x16x32_bf16 v[58:61], v[166:169], v[202:205], v[58:61]
	v_mfma_f32_16x16x32_bf16 v[46:49], v[158:161], v[210:213], v[46:49]
	v_mfma_f32_16x16x32_bf16 v[42:45], v[166:169], v[210:213], v[42:45]
	v_mfma_f32_16x16x32_bf16 v[30:33], v[158:161], v[218:221], v[30:33]
	v_mfma_f32_16x16x32_bf16 v[26:29], v[166:169], v[218:221], v[26:29]
	v_mfma_f32_16x16x32_bf16 v[14:17], v[158:161], v[242:245], v[14:17]
	v_mfma_f32_16x16x32_bf16 v[10:13], v[166:169], v[242:245], v[10:13]
	v_mfma_f32_16x16x32_bf16 v[54:57], v[170:173], v[198:201], v[54:57]
	v_mfma_f32_16x16x32_bf16 v[50:53], v[190:193], v[198:201], v[50:53]
	v_mfma_f32_16x16x32_bf16 v[38:41], v[170:173], v[206:209], v[38:41]
	v_mfma_f32_16x16x32_bf16 v[34:37], v[190:193], v[206:209], v[34:37]
	v_mfma_f32_16x16x32_bf16 v[22:25], v[170:173], v[214:217], v[22:25]
	v_mfma_f32_16x16x32_bf16 v[18:21], v[190:193], v[214:217], v[18:21]
	v_mfma_f32_16x16x32_bf16 v[6:9], v[170:173], v[238:241], v[6:9]
	v_mfma_f32_16x16x32_bf16 v[2:5], v[190:193], v[238:241], v[2:5]
	v_mfma_f32_16x16x32_bf16 v[54:57], v[174:177], v[202:205], v[54:57]
	v_mfma_f32_16x16x32_bf16 v[50:53], v[194:197], v[202:205], v[50:53]
	v_mfma_f32_16x16x32_bf16 v[38:41], v[174:177], v[210:213], v[38:41]
	v_mfma_f32_16x16x32_bf16 v[34:37], v[194:197], v[210:213], v[34:37]
	v_mfma_f32_16x16x32_bf16 v[22:25], v[174:177], v[218:221], v[22:25]
	v_mfma_f32_16x16x32_bf16 v[18:21], v[194:197], v[218:221], v[18:21]
	v_mfma_f32_16x16x32_bf16 v[6:9], v[174:177], v[242:245], v[6:9]
	v_mfma_f32_16x16x32_bf16 v[2:5], v[194:197], v[242:245], v[2:5]
	s_setprio 0
	s_barrier
	s_add_i32 s69, 0, 0x18000
	v_add_u32_e32 v151, s69, v146
	s_add_i32 s70, 0, 0x1c000
	ds_read_b128 v[154:157], v151
	ds_read_b128 v[158:161], v151 offset:1024
	ds_read_b128 v[162:165], v151 offset:2048
	ds_read_b128 v[166:169], v151 offset:3072
	v_add_u32_e32 v151, s70, v146
	ds_read_b128 v[170:173], v151
	ds_read_b128 v[174:177], v151 offset:1024
	ds_read_b128 v[190:193], v151 offset:2048
	ds_read_b128 v[194:197], v151 offset:3072
	s_add_u32 s40, s40, s10
	s_addc_u32 s41, s41, s11
	s_mov_b32 m0, s47
	v_lshl_add_u64 v[252:253], s[40:41], 0, v[138:139]
	ds_read_b128 v[198:201], v147 offset:32768
	ds_read_b128 v[202:205], v147 offset:33792
	ds_read_b128 v[206:209], v147 offset:34816
	ds_read_b128 v[210:213], v147 offset:35840
	ds_read_b128 v[214:217], v147 offset:36864
	ds_read_b128 v[218:221], v147 offset:37888
	ds_read_b128 v[238:241], v147 offset:38912
	ds_read_b128 v[242:245], v147 offset:39936
	global_load_lds_dwordx4 v[252:253], off
	v_lshl_add_u64 v[252:253], s[40:41], 0, v[134:135]
	s_mov_b32 m0, s48
	s_nop 0
	global_load_lds_dwordx4 v[252:253], off
	s_waitcnt vmcnt(8)
	s_waitcnt lgkmcnt(0)
	s_barrier
	s_setprio 1
	s_waitcnt lgkmcnt(0)
	v_mfma_f32_16x16x32_bf16 v[126:129], v[154:157], v[198:201], v[126:129]
	v_mfma_f32_16x16x32_bf16 v[122:125], v[162:165], v[198:201], v[122:125]
	v_mfma_f32_16x16x32_bf16 v[110:113], v[154:157], v[206:209], v[110:113]
	v_mfma_f32_16x16x32_bf16 v[106:109], v[162:165], v[206:209], v[106:109]
	v_mfma_f32_16x16x32_bf16 v[94:97], v[154:157], v[214:217], v[94:97]
	v_mfma_f32_16x16x32_bf16 v[90:93], v[162:165], v[214:217], v[90:93]
	v_mfma_f32_16x16x32_bf16 v[78:81], v[154:157], v[238:241], v[78:81]
	v_mfma_f32_16x16x32_bf16 v[74:77], v[162:165], v[238:241], v[74:77]
	v_mfma_f32_16x16x32_bf16 v[126:129], v[158:161], v[202:205], v[126:129]
	v_mfma_f32_16x16x32_bf16 v[122:125], v[166:169], v[202:205], v[122:125]
	v_mfma_f32_16x16x32_bf16 v[110:113], v[158:161], v[210:213], v[110:113]
	v_mfma_f32_16x16x32_bf16 v[106:109], v[166:169], v[210:213], v[106:109]
	v_mfma_f32_16x16x32_bf16 v[94:97], v[158:161], v[218:221], v[94:97]
	v_mfma_f32_16x16x32_bf16 v[90:93], v[166:169], v[218:221], v[90:93]
	v_mfma_f32_16x16x32_bf16 v[78:81], v[158:161], v[242:245], v[78:81]
	v_mfma_f32_16x16x32_bf16 v[74:77], v[166:169], v[242:245], v[74:77]
	v_mfma_f32_16x16x32_bf16 v[118:121], v[170:173], v[198:201], v[118:121]
	v_mfma_f32_16x16x32_bf16 v[114:117], v[190:193], v[198:201], v[114:117]
	v_mfma_f32_16x16x32_bf16 v[102:105], v[170:173], v[206:209], v[102:105]
	v_mfma_f32_16x16x32_bf16 v[98:101], v[190:193], v[206:209], v[98:101]
	v_mfma_f32_16x16x32_bf16 v[86:89], v[170:173], v[214:217], v[86:89]
	v_mfma_f32_16x16x32_bf16 v[82:85], v[190:193], v[214:217], v[82:85]
	v_mfma_f32_16x16x32_bf16 v[70:73], v[170:173], v[238:241], v[70:73]
	v_mfma_f32_16x16x32_bf16 v[66:69], v[190:193], v[238:241], v[66:69]
	v_mfma_f32_16x16x32_bf16 v[118:121], v[174:177], v[202:205], v[118:121]
	v_mfma_f32_16x16x32_bf16 v[114:117], v[194:197], v[202:205], v[114:117]
	v_mfma_f32_16x16x32_bf16 v[102:105], v[174:177], v[210:213], v[102:105]
	v_mfma_f32_16x16x32_bf16 v[98:101], v[194:197], v[210:213], v[98:101]
	v_mfma_f32_16x16x32_bf16 v[86:89], v[174:177], v[218:221], v[86:89]
	v_mfma_f32_16x16x32_bf16 v[82:85], v[194:197], v[218:221], v[82:85]
	v_mfma_f32_16x16x32_bf16 v[70:73], v[174:177], v[242:245], v[70:73]
	v_mfma_f32_16x16x32_bf16 v[66:69], v[194:197], v[242:245], v[66:69]
	s_setprio 0
	s_barrier
	s_add_i32 s40, s69, s44
	v_lshl_add_u64 v[148:149], v[148:149], 0, s[16:17]
	s_mov_b32 m0, s40
	ds_read_b128 v[198:201], v147 offset:49152
	ds_read_b128 v[202:205], v147 offset:50176
	ds_read_b128 v[206:209], v147 offset:51200
	ds_read_b128 v[210:213], v147 offset:52224
	ds_read_b128 v[214:217], v147 offset:53248
	ds_read_b128 v[218:221], v147 offset:54272
	ds_read_b128 v[238:241], v147 offset:55296
	ds_read_b128 v[242:245], v147 offset:56320
	global_load_lds_dwordx4 v[148:149], off
	v_lshl_add_u64 v[148:149], v[178:179], 0, s[16:17]
	s_add_i32 m0, s40, 0x2000
	s_add_i32 s40, s70, s44
	global_load_lds_dwordx4 v[148:149], off
	v_lshl_add_u64 v[148:149], v[222:223], 0, s[16:17]
	s_mov_b32 m0, s40
	s_nop 0
	global_load_lds_dwordx4 v[148:149], off
	v_lshl_add_u64 v[148:149], v[246:247], 0, s[16:17]
	s_add_i32 m0, s40, 0x2000
	s_nop 0
	global_load_lds_dwordx4 v[148:149], off
	v_lshl_add_u64 v[148:149], v[248:249], 0, s[16:17]
	s_mov_b32 m0, s49
	s_nop 0
	global_load_lds_dwordx4 v[148:149], off
	v_lshl_add_u64 v[148:149], v[250:251], 0, s[16:17]
	s_mov_b32 m0, s50
	s_nop 0
	global_load_lds_dwordx4 v[148:149], off
	s_waitcnt vmcnt(8)
	s_waitcnt lgkmcnt(0)
	s_barrier
	s_setprio 1
	s_waitcnt lgkmcnt(0)
	v_mfma_f32_16x16x32_bf16 v[62:65], v[154:157], v[198:201], v[62:65]
	v_mfma_f32_16x16x32_bf16 v[58:61], v[162:165], v[198:201], v[58:61]
	v_mfma_f32_16x16x32_bf16 v[46:49], v[154:157], v[206:209], v[46:49]
	v_mfma_f32_16x16x32_bf16 v[42:45], v[162:165], v[206:209], v[42:45]
	v_mfma_f32_16x16x32_bf16 v[30:33], v[154:157], v[214:217], v[30:33]
	v_mfma_f32_16x16x32_bf16 v[26:29], v[162:165], v[214:217], v[26:29]
	v_mfma_f32_16x16x32_bf16 v[14:17], v[154:157], v[238:241], v[14:17]
	v_mfma_f32_16x16x32_bf16 v[10:13], v[162:165], v[238:241], v[10:13]
	v_mfma_f32_16x16x32_bf16 v[62:65], v[158:161], v[202:205], v[62:65]
	v_mfma_f32_16x16x32_bf16 v[58:61], v[166:169], v[202:205], v[58:61]
	v_mfma_f32_16x16x32_bf16 v[46:49], v[158:161], v[210:213], v[46:49]
	v_mfma_f32_16x16x32_bf16 v[42:45], v[166:169], v[210:213], v[42:45]
	v_mfma_f32_16x16x32_bf16 v[30:33], v[158:161], v[218:221], v[30:33]
	v_mfma_f32_16x16x32_bf16 v[26:29], v[166:169], v[218:221], v[26:29]
	v_mfma_f32_16x16x32_bf16 v[14:17], v[158:161], v[242:245], v[14:17]
	v_mfma_f32_16x16x32_bf16 v[10:13], v[166:169], v[242:245], v[10:13]
	v_mfma_f32_16x16x32_bf16 v[54:57], v[170:173], v[198:201], v[54:57]
	v_mfma_f32_16x16x32_bf16 v[50:53], v[190:193], v[198:201], v[50:53]
	v_mfma_f32_16x16x32_bf16 v[38:41], v[170:173], v[206:209], v[38:41]
	v_mfma_f32_16x16x32_bf16 v[34:37], v[190:193], v[206:209], v[34:37]
	v_mfma_f32_16x16x32_bf16 v[22:25], v[170:173], v[214:217], v[22:25]
	v_mfma_f32_16x16x32_bf16 v[18:21], v[190:193], v[214:217], v[18:21]
	v_mfma_f32_16x16x32_bf16 v[6:9], v[170:173], v[238:241], v[6:9]
	v_mfma_f32_16x16x32_bf16 v[2:5], v[190:193], v[238:241], v[2:5]
	v_mfma_f32_16x16x32_bf16 v[54:57], v[174:177], v[202:205], v[54:57]
	v_mfma_f32_16x16x32_bf16 v[50:53], v[194:197], v[202:205], v[50:53]
	v_mfma_f32_16x16x32_bf16 v[38:41], v[174:177], v[210:213], v[38:41]
	v_mfma_f32_16x16x32_bf16 v[34:37], v[194:197], v[210:213], v[34:37]
	v_mfma_f32_16x16x32_bf16 v[22:25], v[174:177], v[218:221], v[22:25]
	v_mfma_f32_16x16x32_bf16 v[18:21], v[194:197], v[218:221], v[18:21]
	v_mfma_f32_16x16x32_bf16 v[6:9], v[174:177], v[242:245], v[6:9]
	v_mfma_f32_16x16x32_bf16 v[2:5], v[194:197], v[242:245], v[2:5]
	s_setprio 0
	s_barrier
	s_add_u32 s34, s34, 0x100
	s_addc_u32 s35, s35, 0
	s_add_u32 s62, s62, 0x100
	s_addc_u32 s63, s63, 0
	s_cmp_ge_i32 s64, s51
	s_mov_b32 s40, s64
	s_cbranch_scc0 .LBB0_824
	v_readlane_b32 s64, v255, 40
	s_mov_b32 s68, 0xff61b1e6
	s_mov_b32 s74, 0x24600000
	s_mov_b32 s69, 0xcf800000

.LBB0_937:
	s_add_u32 s34, s30, 0x100
	s_addc_u32 s35, s31, 0
	s_add_i32 s61, 0, 0x10000
	s_cmp_eq_u32 s60, 20
	s_cselect_b32 s43, s27, s35
	s_cselect_b32 s42, s26, s34
	s_cselect_b32 s41, s29, s59
	s_cselect_b32 s40, s28, s58
	s_add_i32 s62, 0, 0x14000
	v_add_u32_e32 v156, s61, v150
	v_add_u32_e32 v172, s62, v150
	ds_read_b128 v[140:143], v156
	ds_read_b128 v[144:147], v156 offset:1024
	ds_read_b128 v[152:155], v156 offset:2048
	ds_read_b128 v[156:159], v156 offset:3072
	ds_read_b128 v[160:163], v172
	ds_read_b128 v[164:167], v172 offset:1024
	ds_read_b128 v[168:171], v172 offset:2048
	ds_read_b128 v[172:175], v172 offset:3072
	v_lshl_add_u64 v[218:219], s[30:31], 0, v[136:137]
	s_add_i32 m0, s44, 0xc000
	ds_read_b128 v[176:179], v151
	ds_read_b128 v[190:193], v151 offset:1024
	ds_read_b128 v[194:197], v151 offset:2048
	ds_read_b128 v[198:201], v151 offset:3072
	ds_read_b128 v[202:205], v151 offset:4096
	ds_read_b128 v[206:209], v151 offset:5120
	ds_read_b128 v[210:213], v151 offset:6144
	ds_read_b128 v[214:217], v151 offset:7168
	global_load_lds_dwordx4 v[218:219], off
	v_lshl_add_u64 v[218:219], s[30:31], 0, v[138:139]
	s_add_i32 m0, s44, 0xe000
	s_nop 0
	global_load_lds_dwordx4 v[218:219], off
	s_waitcnt vmcnt(8)
	s_waitcnt lgkmcnt(0)
	s_barrier
	s_setprio 1
	s_waitcnt lgkmcnt(0)
	v_mfma_f32_16x16x32_bf16 v[126:129], v[140:143], v[176:179], v[126:129]
	v_mfma_f32_16x16x32_bf16 v[122:125], v[152:155], v[176:179], v[122:125]
	v_mfma_f32_16x16x32_bf16 v[110:113], v[140:143], v[194:197], v[110:113]
	v_mfma_f32_16x16x32_bf16 v[106:109], v[152:155], v[194:197], v[106:109]
	v_mfma_f32_16x16x32_bf16 v[94:97], v[140:143], v[202:205], v[94:97]
	v_mfma_f32_16x16x32_bf16 v[90:93], v[152:155], v[202:205], v[90:93]
	v_mfma_f32_16x16x32_bf16 v[78:81], v[140:143], v[210:213], v[78:81]
	v_mfma_f32_16x16x32_bf16 v[74:77], v[152:155], v[210:213], v[74:77]
	v_mfma_f32_16x16x32_bf16 v[126:129], v[144:147], v[190:193], v[126:129]
	v_mfma_f32_16x16x32_bf16 v[122:125], v[156:159], v[190:193], v[122:125]
	v_mfma_f32_16x16x32_bf16 v[110:113], v[144:147], v[198:201], v[110:113]
	v_mfma_f32_16x16x32_bf16 v[106:109], v[156:159], v[198:201], v[106:109]
	v_mfma_f32_16x16x32_bf16 v[94:97], v[144:147], v[206:209], v[94:97]
	v_mfma_f32_16x16x32_bf16 v[90:93], v[156:159], v[206:209], v[90:93]
	v_mfma_f32_16x16x32_bf16 v[78:81], v[144:147], v[214:217], v[78:81]
	v_mfma_f32_16x16x32_bf16 v[74:77], v[156:159], v[214:217], v[74:77]
	v_mfma_f32_16x16x32_bf16 v[118:121], v[160:163], v[176:179], v[118:121]
	v_mfma_f32_16x16x32_bf16 v[114:117], v[168:171], v[176:179], v[114:117]
	v_mfma_f32_16x16x32_bf16 v[102:105], v[160:163], v[194:197], v[102:105]
	v_mfma_f32_16x16x32_bf16 v[98:101], v[168:171], v[194:197], v[98:101]
	v_mfma_f32_16x16x32_bf16 v[86:89], v[160:163], v[202:205], v[86:89]
	v_mfma_f32_16x16x32_bf16 v[82:85], v[168:171], v[202:205], v[82:85]
	v_mfma_f32_16x16x32_bf16 v[70:73], v[160:163], v[210:213], v[70:73]
	v_mfma_f32_16x16x32_bf16 v[66:69], v[168:171], v[210:213], v[66:69]
	v_mfma_f32_16x16x32_bf16 v[118:121], v[164:167], v[190:193], v[118:121]
	v_mfma_f32_16x16x32_bf16 v[114:117], v[172:175], v[190:193], v[114:117]
	v_mfma_f32_16x16x32_bf16 v[102:105], v[164:167], v[198:201], v[102:105]
	v_mfma_f32_16x16x32_bf16 v[98:101], v[172:175], v[198:201], v[98:101]
	v_mfma_f32_16x16x32_bf16 v[86:89], v[164:167], v[206:209], v[86:89]
	v_mfma_f32_16x16x32_bf16 v[82:85], v[172:175], v[206:209], v[82:85]
	v_mfma_f32_16x16x32_bf16 v[70:73], v[164:167], v[214:217], v[70:73]
	v_mfma_f32_16x16x32_bf16 v[66:69], v[172:175], v[214:217], v[66:69]
	s_setprio 0
	s_barrier
	s_add_i32 s30, s61, s21
	v_lshl_add_u64 v[218:219], s[40:41], 0, v[180:181]
	s_mov_b32 m0, s30
	ds_read_b128 v[176:179], v151 offset:16384
	ds_read_b128 v[190:193], v151 offset:17408
	ds_read_b128 v[194:197], v151 offset:18432
	ds_read_b128 v[198:201], v151 offset:19456
	ds_read_b128 v[202:205], v151 offset:20480
	ds_read_b128 v[206:209], v151 offset:21504
	ds_read_b128 v[210:213], v151 offset:22528
	ds_read_b128 v[214:217], v151 offset:23552
	global_load_lds_dwordx4 v[218:219], off
	s_add_i32 m0, s30, 0x2000
	s_add_u32 s30, s40, 0x60000
	v_lshl_add_u64 v[220:221], s[40:41], 0, v[134:135]
	s_addc_u32 s31, s41, 0
	s_add_i32 s61, s62, s21
	global_load_lds_dwordx4 v[220:221], off
	v_lshl_add_u64 v[222:223], s[30:31], 0, v[180:181]
	s_mov_b32 m0, s61
	v_lshl_add_u64 v[238:239], s[42:43], 0, v[132:133]
	global_load_lds_dwordx4 v[222:223], off
	v_lshl_add_u64 v[222:223], s[30:31], 0, v[134:135]
	s_add_i32 m0, s61, 0x2000
	s_nop 0
	global_load_lds_dwordx4 v[222:223], off
	v_lshl_add_u64 v[222:223], s[42:43], 0, v[130:131]
	s_mov_b32 m0, s44
	s_nop 0
	global_load_lds_dwordx4 v[222:223], off
	s_mov_b32 m0, s45
	s_nop 0
	global_load_lds_dwordx4 v[238:239], off
	s_waitcnt vmcnt(8)
	s_waitcnt lgkmcnt(0)
	s_barrier
	s_setprio 1
	s_waitcnt lgkmcnt(0)
	v_mfma_f32_16x16x32_bf16 v[62:65], v[140:143], v[176:179], v[62:65]
	v_mfma_f32_16x16x32_bf16 v[58:61], v[152:155], v[176:179], v[58:61]
	v_mfma_f32_16x16x32_bf16 v[46:49], v[140:143], v[194:197], v[46:49]
	v_mfma_f32_16x16x32_bf16 v[42:45], v[152:155], v[194:197], v[42:45]
	v_mfma_f32_16x16x32_bf16 v[30:33], v[140:143], v[202:205], v[30:33]
	v_mfma_f32_16x16x32_bf16 v[26:29], v[152:155], v[202:205], v[26:29]
	v_mfma_f32_16x16x32_bf16 v[14:17], v[140:143], v[210:213], v[14:17]
	v_mfma_f32_16x16x32_bf16 v[10:13], v[152:155], v[210:213], v[10:13]
	v_mfma_f32_16x16x32_bf16 v[62:65], v[144:147], v[190:193], v[62:65]
	v_mfma_f32_16x16x32_bf16 v[58:61], v[156:159], v[190:193], v[58:61]
	v_mfma_f32_16x16x32_bf16 v[46:49], v[144:147], v[198:201], v[46:49]
	v_mfma_f32_16x16x32_bf16 v[42:45], v[156:159], v[198:201], v[42:45]
	v_mfma_f32_16x16x32_bf16 v[30:33], v[144:147], v[206:209], v[30:33]
	v_mfma_f32_16x16x32_bf16 v[26:29], v[156:159], v[206:209], v[26:29]
	v_mfma_f32_16x16x32_bf16 v[14:17], v[144:147], v[214:217], v[14:17]
	v_mfma_f32_16x16x32_bf16 v[10:13], v[156:159], v[214:217], v[10:13]
	v_mfma_f32_16x16x32_bf16 v[54:57], v[160:163], v[176:179], v[54:57]
	v_mfma_f32_16x16x32_bf16 v[50:53], v[168:171], v[176:179], v[50:53]
	v_mfma_f32_16x16x32_bf16 v[38:41], v[160:163], v[194:197], v[38:41]
	v_mfma_f32_16x16x32_bf16 v[34:37], v[168:171], v[194:197], v[34:37]
	v_mfma_f32_16x16x32_bf16 v[22:25], v[160:163], v[202:205], v[22:25]
	v_mfma_f32_16x16x32_bf16 v[18:21], v[168:171], v[202:205], v[18:21]
	v_mfma_f32_16x16x32_bf16 v[6:9], v[160:163], v[210:213], v[6:9]
	v_mfma_f32_16x16x32_bf16 v[2:5], v[168:171], v[210:213], v[2:5]
	v_mfma_f32_16x16x32_bf16 v[54:57], v[164:167], v[190:193], v[54:57]
	v_mfma_f32_16x16x32_bf16 v[50:53], v[172:175], v[190:193], v[50:53]
	v_mfma_f32_16x16x32_bf16 v[38:41], v[164:167], v[198:201], v[38:41]
	v_mfma_f32_16x16x32_bf16 v[34:37], v[172:175], v[198:201], v[34:37]
	v_mfma_f32_16x16x32_bf16 v[22:25], v[164:167], v[206:209], v[22:25]
	v_mfma_f32_16x16x32_bf16 v[18:21], v[172:175], v[206:209], v[18:21]
	v_mfma_f32_16x16x32_bf16 v[6:9], v[164:167], v[214:217], v[6:9]
	v_mfma_f32_16x16x32_bf16 v[2:5], v[172:175], v[214:217], v[2:5]
	s_setprio 0
	s_barrier
	s_add_i32 s61, 0, 0x18000
	s_add_i32 s62, 0, 0x1c000
	v_add_u32_e32 v156, s61, v150
	v_add_u32_e32 v172, s62, v150
	ds_read_b128 v[140:143], v156
	ds_read_b128 v[144:147], v156 offset:1024
	ds_read_b128 v[152:155], v156 offset:2048
	ds_read_b128 v[156:159], v156 offset:3072
	ds_read_b128 v[160:163], v172
	ds_read_b128 v[164:167], v172 offset:1024
	ds_read_b128 v[168:171], v172 offset:2048
	ds_read_b128 v[172:175], v172 offset:3072
	s_add_u32 s30, s42, 0x60000
	s_addc_u32 s31, s43, 0
	s_mov_b32 m0, s46
	v_lshl_add_u64 v[240:241], s[30:31], 0, v[130:131]
	ds_read_b128 v[176:179], v151 offset:32768
	ds_read_b128 v[190:193], v151 offset:33792
	ds_read_b128 v[194:197], v151 offset:34816
	ds_read_b128 v[198:201], v151 offset:35840
	ds_read_b128 v[202:205], v151 offset:36864
	ds_read_b128 v[206:209], v151 offset:37888
	ds_read_b128 v[210:213], v151 offset:38912
	ds_read_b128 v[214:217], v151 offset:39936
	global_load_lds_dwordx4 v[240:241], off
	v_lshl_add_u64 v[240:241], s[30:31], 0, v[132:133]
	s_mov_b32 m0, s47
	s_nop 0
	global_load_lds_dwordx4 v[240:241], off
	s_waitcnt vmcnt(8)
	s_waitcnt lgkmcnt(0)
	s_barrier
	s_setprio 1
	s_waitcnt lgkmcnt(0)
	v_mfma_f32_16x16x32_bf16 v[126:129], v[140:143], v[176:179], v[126:129]
	v_mfma_f32_16x16x32_bf16 v[122:125], v[152:155], v[176:179], v[122:125]
	v_mfma_f32_16x16x32_bf16 v[110:113], v[140:143], v[194:197], v[110:113]
	v_mfma_f32_16x16x32_bf16 v[106:109], v[152:155], v[194:197], v[106:109]
	v_mfma_f32_16x16x32_bf16 v[94:97], v[140:143], v[202:205], v[94:97]
	v_mfma_f32_16x16x32_bf16 v[90:93], v[152:155], v[202:205], v[90:93]
	v_mfma_f32_16x16x32_bf16 v[78:81], v[140:143], v[210:213], v[78:81]
	v_mfma_f32_16x16x32_bf16 v[74:77], v[152:155], v[210:213], v[74:77]
	v_mfma_f32_16x16x32_bf16 v[126:129], v[144:147], v[190:193], v[126:129]
	v_mfma_f32_16x16x32_bf16 v[122:125], v[156:159], v[190:193], v[122:125]
	v_mfma_f32_16x16x32_bf16 v[110:113], v[144:147], v[198:201], v[110:113]
	v_mfma_f32_16x16x32_bf16 v[106:109], v[156:159], v[198:201], v[106:109]
	v_mfma_f32_16x16x32_bf16 v[94:97], v[144:147], v[206:209], v[94:97]
	v_mfma_f32_16x16x32_bf16 v[90:93], v[156:159], v[206:209], v[90:93]
	v_mfma_f32_16x16x32_bf16 v[78:81], v[144:147], v[214:217], v[78:81]
	v_mfma_f32_16x16x32_bf16 v[74:77], v[156:159], v[214:217], v[74:77]
	v_mfma_f32_16x16x32_bf16 v[118:121], v[160:163], v[176:179], v[118:121]
	v_mfma_f32_16x16x32_bf16 v[114:117], v[168:171], v[176:179], v[114:117]
	v_mfma_f32_16x16x32_bf16 v[102:105], v[160:163], v[194:197], v[102:105]
	v_mfma_f32_16x16x32_bf16 v[98:101], v[168:171], v[194:197], v[98:101]
	v_mfma_f32_16x16x32_bf16 v[86:89], v[160:163], v[202:205], v[86:89]
	v_mfma_f32_16x16x32_bf16 v[82:85], v[168:171], v[202:205], v[82:85]
	v_mfma_f32_16x16x32_bf16 v[70:73], v[160:163], v[210:213], v[70:73]
	v_mfma_f32_16x16x32_bf16 v[66:69], v[168:171], v[210:213], v[66:69]
	v_mfma_f32_16x16x32_bf16 v[118:121], v[164:167], v[190:193], v[118:121]
	v_mfma_f32_16x16x32_bf16 v[114:117], v[172:175], v[190:193], v[114:117]
	v_mfma_f32_16x16x32_bf16 v[102:105], v[164:167], v[198:201], v[102:105]
	v_mfma_f32_16x16x32_bf16 v[98:101], v[172:175], v[198:201], v[98:101]
	v_mfma_f32_16x16x32_bf16 v[86:89], v[164:167], v[206:209], v[86:89]
	v_mfma_f32_16x16x32_bf16 v[82:85], v[172:175], v[206:209], v[82:85]
	v_mfma_f32_16x16x32_bf16 v[70:73], v[164:167], v[214:217], v[70:73]
	v_mfma_f32_16x16x32_bf16 v[66:69], v[172:175], v[214:217], v[66:69]
	s_setprio 0
	s_barrier
	s_add_i32 s30, s61, s21
	v_lshl_add_u64 v[218:219], v[218:219], 0, s[16:17]
	s_mov_b32 m0, s30
	ds_read_b128 v[176:179], v151 offset:49152
	ds_read_b128 v[190:193], v151 offset:50176
	ds_read_b128 v[194:197], v151 offset:51200
	ds_read_b128 v[198:201], v151 offset:52224
	ds_read_b128 v[202:205], v151 offset:53248
	ds_read_b128 v[206:209], v151 offset:54272
	ds_read_b128 v[210:213], v151 offset:55296
	ds_read_b128 v[214:217], v151 offset:56320
	global_load_lds_dwordx4 v[218:219], off
	s_add_i32 m0, s30, 0x2000
	s_add_u32 s30, s40, 0x60080
	v_lshl_add_u64 v[218:219], v[220:221], 0, s[16:17]
	s_addc_u32 s31, s41, 0
	s_add_i32 s40, s62, s21
	global_load_lds_dwordx4 v[218:219], off
	v_lshl_add_u64 v[218:219], s[30:31], 0, v[180:181]
	s_mov_b32 m0, s40
	s_nop 0
	global_load_lds_dwordx4 v[218:219], off
	v_lshl_add_u64 v[218:219], s[30:31], 0, v[134:135]
	s_add_i32 m0, s40, 0x2000
	s_nop 0
	global_load_lds_dwordx4 v[218:219], off
	v_lshl_add_u64 v[218:219], v[222:223], 0, s[16:17]
	s_mov_b32 m0, s49
	s_nop 0
	global_load_lds_dwordx4 v[218:219], off
	v_lshl_add_u64 v[218:219], v[238:239], 0, s[16:17]
	s_mov_b32 m0, s50
	s_nop 0
	global_load_lds_dwordx4 v[218:219], off
	s_waitcnt vmcnt(8)
	s_waitcnt lgkmcnt(0)
	s_barrier
	s_setprio 1
	s_waitcnt lgkmcnt(0)
	v_mfma_f32_16x16x32_bf16 v[62:65], v[140:143], v[176:179], v[62:65]
	v_mfma_f32_16x16x32_bf16 v[58:61], v[152:155], v[176:179], v[58:61]
	v_mfma_f32_16x16x32_bf16 v[46:49], v[140:143], v[194:197], v[46:49]
	v_mfma_f32_16x16x32_bf16 v[42:45], v[152:155], v[194:197], v[42:45]
	v_mfma_f32_16x16x32_bf16 v[30:33], v[140:143], v[202:205], v[30:33]
	v_mfma_f32_16x16x32_bf16 v[26:29], v[152:155], v[202:205], v[26:29]
	v_mfma_f32_16x16x32_bf16 v[14:17], v[140:143], v[210:213], v[14:17]
	v_mfma_f32_16x16x32_bf16 v[10:13], v[152:155], v[210:213], v[10:13]
	v_mfma_f32_16x16x32_bf16 v[62:65], v[144:147], v[190:193], v[62:65]
	v_mfma_f32_16x16x32_bf16 v[58:61], v[156:159], v[190:193], v[58:61]
	v_mfma_f32_16x16x32_bf16 v[46:49], v[144:147], v[198:201], v[46:49]
	v_mfma_f32_16x16x32_bf16 v[42:45], v[156:159], v[198:201], v[42:45]
	v_mfma_f32_16x16x32_bf16 v[30:33], v[144:147], v[206:209], v[30:33]
	v_mfma_f32_16x16x32_bf16 v[26:29], v[156:159], v[206:209], v[26:29]
	v_mfma_f32_16x16x32_bf16 v[14:17], v[144:147], v[214:217], v[14:17]
	v_mfma_f32_16x16x32_bf16 v[10:13], v[156:159], v[214:217], v[10:13]
	v_mfma_f32_16x16x32_bf16 v[54:57], v[160:163], v[176:179], v[54:57]
	v_mfma_f32_16x16x32_bf16 v[50:53], v[168:171], v[176:179], v[50:53]
	v_mfma_f32_16x16x32_bf16 v[38:41], v[160:163], v[194:197], v[38:41]
	v_mfma_f32_16x16x32_bf16 v[34:37], v[168:171], v[194:197], v[34:37]
	v_mfma_f32_16x16x32_bf16 v[22:25], v[160:163], v[202:205], v[22:25]
	v_mfma_f32_16x16x32_bf16 v[18:21], v[168:171], v[202:205], v[18:21]
	v_mfma_f32_16x16x32_bf16 v[6:9], v[160:163], v[210:213], v[6:9]
	v_mfma_f32_16x16x32_bf16 v[2:5], v[168:171], v[210:213], v[2:5]
	v_mfma_f32_16x16x32_bf16 v[54:57], v[164:167], v[190:193], v[54:57]
	v_mfma_f32_16x16x32_bf16 v[50:53], v[172:175], v[190:193], v[50:53]
	v_mfma_f32_16x16x32_bf16 v[38:41], v[164:167], v[198:201], v[38:41]
	v_mfma_f32_16x16x32_bf16 v[34:37], v[172:175], v[198:201], v[34:37]
	v_mfma_f32_16x16x32_bf16 v[22:25], v[164:167], v[206:209], v[22:25]
	v_mfma_f32_16x16x32_bf16 v[18:21], v[172:175], v[206:209], v[18:21]
	v_mfma_f32_16x16x32_bf16 v[6:9], v[164:167], v[214:217], v[6:9]
	v_mfma_f32_16x16x32_bf16 v[2:5], v[172:175], v[214:217], v[2:5]
	s_setprio 0
	s_barrier
	s_add_i32 s60, s60, 2
	s_add_u32 s58, s58, 0x100
	s_addc_u32 s59, s59, 0
	s_cmp_gt_u32 s60, 21
	s_mov_b64 s[30:31], s[34:35]
	s_cbranch_scc0 .LBB0_937
	s_and_b64 vcc, exec, s[24:25]
	s_cbranch_vccz .LBB0_940
	s_barrier

.LBB0_1018:
	s_add_u32 s40, s38, 0xfff80080
	s_addc_u32 s41, s39, -1
	s_add_i32 s51, 0, 0x10000
	s_cmp_eq_u32 s49, 28
	s_cselect_b32 s43, s11, s41
	s_cselect_b32 s42, s37, s40
	s_cselect_b32 s41, s44, s47
	s_cselect_b32 s40, s45, s46
	s_add_i32 s83, 0, 0x14000
	v_add_u32_e32 v154, s51, v159
	v_add_u32_e32 v161, s83, v159
	ds_read_b128 v[142:145], v154
	ds_read_b128 v[146:149], v154 offset:1024
	ds_read_b128 v[150:153], v154 offset:2048
	ds_read_b128 v[154:157], v154 offset:3072
	ds_read_b128 v[162:165], v161
	ds_read_b128 v[166:169], v161 offset:1024
	ds_read_b128 v[170:173], v161 offset:2048
	ds_read_b128 v[174:177], v161 offset:3072
	v_lshl_add_u64 v[178:179], s[38:39], 0, v[138:139]
	s_add_i32 m0, s61, 0xc000
	ds_read_b128 v[190:193], v160
	ds_read_b128 v[194:197], v160 offset:1024
	ds_read_b128 v[198:201], v160 offset:2048
	ds_read_b128 v[202:205], v160 offset:3072
	ds_read_b128 v[206:209], v160 offset:4096
	ds_read_b128 v[210:213], v160 offset:5120
	ds_read_b128 v[214:217], v160 offset:6144
	ds_read_b128 v[218:221], v160 offset:7168
	global_load_lds_dwordx4 v[178:179], off
	v_lshl_add_u64 v[178:179], s[38:39], 0, v[140:141]
	s_add_i32 m0, s61, 0xe000
	s_nop 0
	global_load_lds_dwordx4 v[178:179], off
	s_waitcnt vmcnt(8)
	s_waitcnt lgkmcnt(0)
	s_barrier
	s_setprio 1
	s_waitcnt lgkmcnt(0)
	v_mfma_f32_16x16x32_bf16 v[126:129], v[142:145], v[190:193], v[126:129]
	v_mfma_f32_16x16x32_bf16 v[122:125], v[150:153], v[190:193], v[122:125]
	v_mfma_f32_16x16x32_bf16 v[110:113], v[142:145], v[198:201], v[110:113]
	v_mfma_f32_16x16x32_bf16 v[106:109], v[150:153], v[198:201], v[106:109]
	v_mfma_f32_16x16x32_bf16 v[94:97], v[142:145], v[206:209], v[94:97]
	v_mfma_f32_16x16x32_bf16 v[90:93], v[150:153], v[206:209], v[90:93]
	v_mfma_f32_16x16x32_bf16 v[78:81], v[142:145], v[214:217], v[78:81]
	v_mfma_f32_16x16x32_bf16 v[74:77], v[150:153], v[214:217], v[74:77]
	v_mfma_f32_16x16x32_bf16 v[126:129], v[146:149], v[194:197], v[126:129]
	v_mfma_f32_16x16x32_bf16 v[122:125], v[154:157], v[194:197], v[122:125]
	v_mfma_f32_16x16x32_bf16 v[110:113], v[146:149], v[202:205], v[110:113]
	v_mfma_f32_16x16x32_bf16 v[106:109], v[154:157], v[202:205], v[106:109]
	v_mfma_f32_16x16x32_bf16 v[94:97], v[146:149], v[210:213], v[94:97]
	v_mfma_f32_16x16x32_bf16 v[90:93], v[154:157], v[210:213], v[90:93]
	v_mfma_f32_16x16x32_bf16 v[78:81], v[146:149], v[218:221], v[78:81]
	v_mfma_f32_16x16x32_bf16 v[74:77], v[154:157], v[218:221], v[74:77]
	v_mfma_f32_16x16x32_bf16 v[118:121], v[162:165], v[190:193], v[118:121]
	v_mfma_f32_16x16x32_bf16 v[114:117], v[170:173], v[190:193], v[114:117]
	v_mfma_f32_16x16x32_bf16 v[102:105], v[162:165], v[198:201], v[102:105]
	v_mfma_f32_16x16x32_bf16 v[98:101], v[170:173], v[198:201], v[98:101]
	v_mfma_f32_16x16x32_bf16 v[86:89], v[162:165], v[206:209], v[86:89]
	v_mfma_f32_16x16x32_bf16 v[82:85], v[170:173], v[206:209], v[82:85]
	v_mfma_f32_16x16x32_bf16 v[70:73], v[162:165], v[214:217], v[70:73]
	v_mfma_f32_16x16x32_bf16 v[66:69], v[170:173], v[214:217], v[66:69]
	v_mfma_f32_16x16x32_bf16 v[118:121], v[166:169], v[194:197], v[118:121]
	v_mfma_f32_16x16x32_bf16 v[114:117], v[174:177], v[194:197], v[114:117]
	v_mfma_f32_16x16x32_bf16 v[102:105], v[166:169], v[202:205], v[102:105]
	v_mfma_f32_16x16x32_bf16 v[98:101], v[174:177], v[202:205], v[98:101]
	v_mfma_f32_16x16x32_bf16 v[86:89], v[166:169], v[210:213], v[86:89]
	v_mfma_f32_16x16x32_bf16 v[82:85], v[174:177], v[210:213], v[82:85]
	v_mfma_f32_16x16x32_bf16 v[70:73], v[166:169], v[218:221], v[70:73]
	v_mfma_f32_16x16x32_bf16 v[66:69], v[174:177], v[218:221], v[66:69]
	s_setprio 0
	s_barrier
	s_add_i32 s51, s51, s60
	v_lshl_add_u64 v[178:179], s[40:41], 0, v[180:181]
	s_mov_b32 m0, s51
	ds_read_b128 v[190:193], v160 offset:16384
	ds_read_b128 v[194:197], v160 offset:17408
	ds_read_b128 v[198:201], v160 offset:18432
	ds_read_b128 v[202:205], v160 offset:19456
	ds_read_b128 v[206:209], v160 offset:20480
	ds_read_b128 v[210:213], v160 offset:21504
	ds_read_b128 v[214:217], v160 offset:22528
	ds_read_b128 v[218:221], v160 offset:23552
	global_load_lds_dwordx4 v[178:179], off
	s_add_i32 m0, s51, 0x2000
	s_add_u32 vcc_lo, s40, 0x80000
	v_lshl_add_u64 v[222:223], s[40:41], 0, v[136:137]
	s_addc_u32 vcc_hi, s41, 0
	s_add_i32 s51, s83, s60
	global_load_lds_dwordx4 v[222:223], off
	v_lshl_add_u64 v[238:239], vcc, 0, v[180:181]
	s_mov_b32 m0, s51
	v_lshl_add_u64 v[240:241], s[42:43], 0, v[134:135]
	global_load_lds_dwordx4 v[238:239], off
	v_lshl_add_u64 v[238:239], vcc, 0, v[136:137]
	s_add_i32 m0, s51, 0x2000
	s_nop 0
	global_load_lds_dwordx4 v[238:239], off
	v_lshl_add_u64 v[238:239], s[42:43], 0, v[132:133]
	s_mov_b32 m0, s61
	s_nop 0
	global_load_lds_dwordx4 v[238:239], off
	s_mov_b32 m0, s62
	s_nop 0
	global_load_lds_dwordx4 v[240:241], off
	s_waitcnt vmcnt(8)
	s_waitcnt lgkmcnt(0)
	s_barrier
	s_setprio 1
	s_waitcnt lgkmcnt(0)
	v_mfma_f32_16x16x32_bf16 v[62:65], v[142:145], v[190:193], v[62:65]
	v_mfma_f32_16x16x32_bf16 v[58:61], v[150:153], v[190:193], v[58:61]
	v_mfma_f32_16x16x32_bf16 v[46:49], v[142:145], v[198:201], v[46:49]
	v_mfma_f32_16x16x32_bf16 v[42:45], v[150:153], v[198:201], v[42:45]
	v_mfma_f32_16x16x32_bf16 v[30:33], v[142:145], v[206:209], v[30:33]
	v_mfma_f32_16x16x32_bf16 v[26:29], v[150:153], v[206:209], v[26:29]
	v_mfma_f32_16x16x32_bf16 v[14:17], v[142:145], v[214:217], v[14:17]
	v_mfma_f32_16x16x32_bf16 v[10:13], v[150:153], v[214:217], v[10:13]
	v_mfma_f32_16x16x32_bf16 v[62:65], v[146:149], v[194:197], v[62:65]
	v_mfma_f32_16x16x32_bf16 v[58:61], v[154:157], v[194:197], v[58:61]
	v_mfma_f32_16x16x32_bf16 v[46:49], v[146:149], v[202:205], v[46:49]
	v_mfma_f32_16x16x32_bf16 v[42:45], v[154:157], v[202:205], v[42:45]
	v_mfma_f32_16x16x32_bf16 v[30:33], v[146:149], v[210:213], v[30:33]
	v_mfma_f32_16x16x32_bf16 v[26:29], v[154:157], v[210:213], v[26:29]
	v_mfma_f32_16x16x32_bf16 v[14:17], v[146:149], v[218:221], v[14:17]
	v_mfma_f32_16x16x32_bf16 v[10:13], v[154:157], v[218:221], v[10:13]
	v_mfma_f32_16x16x32_bf16 v[54:57], v[162:165], v[190:193], v[54:57]
	v_mfma_f32_16x16x32_bf16 v[50:53], v[170:173], v[190:193], v[50:53]
	v_mfma_f32_16x16x32_bf16 v[38:41], v[162:165], v[198:201], v[38:41]
	v_mfma_f32_16x16x32_bf16 v[34:37], v[170:173], v[198:201], v[34:37]
	v_mfma_f32_16x16x32_bf16 v[22:25], v[162:165], v[206:209], v[22:25]
	v_mfma_f32_16x16x32_bf16 v[18:21], v[170:173], v[206:209], v[18:21]
	v_mfma_f32_16x16x32_bf16 v[6:9], v[162:165], v[214:217], v[6:9]
	v_mfma_f32_16x16x32_bf16 v[2:5], v[170:173], v[214:217], v[2:5]
	v_mfma_f32_16x16x32_bf16 v[54:57], v[166:169], v[194:197], v[54:57]
	v_mfma_f32_16x16x32_bf16 v[50:53], v[174:177], v[194:197], v[50:53]
	v_mfma_f32_16x16x32_bf16 v[38:41], v[166:169], v[202:205], v[38:41]
	v_mfma_f32_16x16x32_bf16 v[34:37], v[174:177], v[202:205], v[34:37]
	v_mfma_f32_16x16x32_bf16 v[22:25], v[166:169], v[210:213], v[22:25]
	v_mfma_f32_16x16x32_bf16 v[18:21], v[174:177], v[210:213], v[18:21]
	v_mfma_f32_16x16x32_bf16 v[6:9], v[166:169], v[218:221], v[6:9]
	v_mfma_f32_16x16x32_bf16 v[2:5], v[174:177], v[218:221], v[2:5]
	s_setprio 0
	s_barrier
	s_add_i32 s51, 0, 0x18000
	s_add_i32 s83, 0, 0x1c000
	v_add_u32_e32 v154, s51, v159
	v_add_u32_e32 v161, s83, v159
	ds_read_b128 v[142:145], v154
	ds_read_b128 v[146:149], v154 offset:1024
	ds_read_b128 v[150:153], v154 offset:2048
	ds_read_b128 v[154:157], v154 offset:3072
	ds_read_b128 v[162:165], v161
	ds_read_b128 v[166:169], v161 offset:1024
	ds_read_b128 v[170:173], v161 offset:2048
	ds_read_b128 v[174:177], v161 offset:3072
	s_add_u32 s42, s42, 0x80000
	s_addc_u32 s43, s43, 0
	s_mov_b32 m0, s63
	v_lshl_add_u64 v[242:243], s[42:43], 0, v[132:133]
	ds_read_b128 v[190:193], v160 offset:32768
	ds_read_b128 v[194:197], v160 offset:33792
	ds_read_b128 v[198:201], v160 offset:34816
	ds_read_b128 v[202:205], v160 offset:35840
	ds_read_b128 v[206:209], v160 offset:36864
	ds_read_b128 v[210:213], v160 offset:37888
	ds_read_b128 v[214:217], v160 offset:38912
	ds_read_b128 v[218:221], v160 offset:39936
	global_load_lds_dwordx4 v[242:243], off
	v_lshl_add_u64 v[242:243], s[42:43], 0, v[134:135]
	s_mov_b32 m0, s64
	s_nop 0
	global_load_lds_dwordx4 v[242:243], off
	s_waitcnt vmcnt(8)
	s_waitcnt lgkmcnt(0)
	s_barrier
	s_setprio 1
	s_waitcnt lgkmcnt(0)
	v_mfma_f32_16x16x32_bf16 v[126:129], v[142:145], v[190:193], v[126:129]
	v_mfma_f32_16x16x32_bf16 v[122:125], v[150:153], v[190:193], v[122:125]
	v_mfma_f32_16x16x32_bf16 v[110:113], v[142:145], v[198:201], v[110:113]
	v_mfma_f32_16x16x32_bf16 v[106:109], v[150:153], v[198:201], v[106:109]
	v_mfma_f32_16x16x32_bf16 v[94:97], v[142:145], v[206:209], v[94:97]
	v_mfma_f32_16x16x32_bf16 v[90:93], v[150:153], v[206:209], v[90:93]
	v_mfma_f32_16x16x32_bf16 v[78:81], v[142:145], v[214:217], v[78:81]
	v_mfma_f32_16x16x32_bf16 v[74:77], v[150:153], v[214:217], v[74:77]
	v_mfma_f32_16x16x32_bf16 v[126:129], v[146:149], v[194:197], v[126:129]
	v_mfma_f32_16x16x32_bf16 v[122:125], v[154:157], v[194:197], v[122:125]
	v_mfma_f32_16x16x32_bf16 v[110:113], v[146:149], v[202:205], v[110:113]
	v_mfma_f32_16x16x32_bf16 v[106:109], v[154:157], v[202:205], v[106:109]
	v_mfma_f32_16x16x32_bf16 v[94:97], v[146:149], v[210:213], v[94:97]
	v_mfma_f32_16x16x32_bf16 v[90:93], v[154:157], v[210:213], v[90:93]
	v_mfma_f32_16x16x32_bf16 v[78:81], v[146:149], v[218:221], v[78:81]
	v_mfma_f32_16x16x32_bf16 v[74:77], v[154:157], v[218:221], v[74:77]
	v_mfma_f32_16x16x32_bf16 v[118:121], v[162:165], v[190:193], v[118:121]
	v_mfma_f32_16x16x32_bf16 v[114:117], v[170:173], v[190:193], v[114:117]
	v_mfma_f32_16x16x32_bf16 v[102:105], v[162:165], v[198:201], v[102:105]
	v_mfma_f32_16x16x32_bf16 v[98:101], v[170:173], v[198:201], v[98:101]
	v_mfma_f32_16x16x32_bf16 v[86:89], v[162:165], v[206:209], v[86:89]
	v_mfma_f32_16x16x32_bf16 v[82:85], v[170:173], v[206:209], v[82:85]
	v_mfma_f32_16x16x32_bf16 v[70:73], v[162:165], v[214:217], v[70:73]
	v_mfma_f32_16x16x32_bf16 v[66:69], v[170:173], v[214:217], v[66:69]
	v_mfma_f32_16x16x32_bf16 v[118:121], v[166:169], v[194:197], v[118:121]
	v_mfma_f32_16x16x32_bf16 v[114:117], v[174:177], v[194:197], v[114:117]
	v_mfma_f32_16x16x32_bf16 v[102:105], v[166:169], v[202:205], v[102:105]
	v_mfma_f32_16x16x32_bf16 v[98:101], v[174:177], v[202:205], v[98:101]
	v_mfma_f32_16x16x32_bf16 v[86:89], v[166:169], v[210:213], v[86:89]
	v_mfma_f32_16x16x32_bf16 v[82:85], v[174:177], v[210:213], v[82:85]
	v_mfma_f32_16x16x32_bf16 v[70:73], v[166:169], v[218:221], v[70:73]
	v_mfma_f32_16x16x32_bf16 v[66:69], v[174:177], v[218:221], v[66:69]
	s_setprio 0
	s_barrier
	s_add_i32 s42, s51, s60
	v_lshl_add_u64 v[178:179], v[178:179], 0, s[16:17]
	s_mov_b32 m0, s42
	ds_read_b128 v[190:193], v160 offset:49152
	ds_read_b128 v[194:197], v160 offset:50176
	ds_read_b128 v[198:201], v160 offset:51200
	ds_read_b128 v[202:205], v160 offset:52224
	ds_read_b128 v[206:209], v160 offset:53248
	ds_read_b128 v[210:213], v160 offset:54272
	ds_read_b128 v[214:217], v160 offset:55296
	ds_read_b128 v[218:221], v160 offset:56320
	global_load_lds_dwordx4 v[178:179], off
	s_add_i32 m0, s42, 0x2000
	s_add_u32 s40, s40, 0x80080
	v_lshl_add_u64 v[178:179], v[222:223], 0, s[16:17]
	s_addc_u32 s41, s41, 0
	s_add_i32 s42, s83, s60
	global_load_lds_dwordx4 v[178:179], off
	v_lshl_add_u64 v[178:179], s[40:41], 0, v[180:181]
	s_mov_b32 m0, s42
	s_nop 0
	global_load_lds_dwordx4 v[178:179], off
	v_lshl_add_u64 v[178:179], s[40:41], 0, v[136:137]
	s_add_i32 m0, s42, 0x2000
	s_nop 0
	global_load_lds_dwordx4 v[178:179], off
	v_lshl_add_u64 v[178:179], v[238:239], 0, s[16:17]
	s_mov_b32 m0, s74
	s_nop 0
	global_load_lds_dwordx4 v[178:179], off
	v_lshl_add_u64 v[178:179], v[240:241], 0, s[16:17]
	s_mov_b32 m0, s75
	s_nop 0
	global_load_lds_dwordx4 v[178:179], off
	s_waitcnt vmcnt(8)
	s_waitcnt lgkmcnt(0)
	s_barrier
	s_setprio 1
	s_waitcnt lgkmcnt(0)
	v_mfma_f32_16x16x32_bf16 v[62:65], v[142:145], v[190:193], v[62:65]
	v_mfma_f32_16x16x32_bf16 v[58:61], v[150:153], v[190:193], v[58:61]
	v_mfma_f32_16x16x32_bf16 v[46:49], v[142:145], v[198:201], v[46:49]
	v_mfma_f32_16x16x32_bf16 v[42:45], v[150:153], v[198:201], v[42:45]
	v_mfma_f32_16x16x32_bf16 v[30:33], v[142:145], v[206:209], v[30:33]
	v_mfma_f32_16x16x32_bf16 v[26:29], v[150:153], v[206:209], v[26:29]
	v_mfma_f32_16x16x32_bf16 v[14:17], v[142:145], v[214:217], v[14:17]
	v_mfma_f32_16x16x32_bf16 v[10:13], v[150:153], v[214:217], v[10:13]
	v_mfma_f32_16x16x32_bf16 v[62:65], v[146:149], v[194:197], v[62:65]
	v_mfma_f32_16x16x32_bf16 v[58:61], v[154:157], v[194:197], v[58:61]
	v_mfma_f32_16x16x32_bf16 v[46:49], v[146:149], v[202:205], v[46:49]
	v_mfma_f32_16x16x32_bf16 v[42:45], v[154:157], v[202:205], v[42:45]
	v_mfma_f32_16x16x32_bf16 v[30:33], v[146:149], v[210:213], v[30:33]
	v_mfma_f32_16x16x32_bf16 v[26:29], v[154:157], v[210:213], v[26:29]
	v_mfma_f32_16x16x32_bf16 v[14:17], v[146:149], v[218:221], v[14:17]
	v_mfma_f32_16x16x32_bf16 v[10:13], v[154:157], v[218:221], v[10:13]
	v_mfma_f32_16x16x32_bf16 v[54:57], v[162:165], v[190:193], v[54:57]
	v_mfma_f32_16x16x32_bf16 v[50:53], v[170:173], v[190:193], v[50:53]
	v_mfma_f32_16x16x32_bf16 v[38:41], v[162:165], v[198:201], v[38:41]
	v_mfma_f32_16x16x32_bf16 v[34:37], v[170:173], v[198:201], v[34:37]
	v_mfma_f32_16x16x32_bf16 v[22:25], v[162:165], v[206:209], v[22:25]
	v_mfma_f32_16x16x32_bf16 v[18:21], v[170:173], v[206:209], v[18:21]
	v_mfma_f32_16x16x32_bf16 v[6:9], v[162:165], v[214:217], v[6:9]
	v_mfma_f32_16x16x32_bf16 v[2:5], v[170:173], v[214:217], v[2:5]
	v_mfma_f32_16x16x32_bf16 v[54:57], v[166:169], v[194:197], v[54:57]
	v_mfma_f32_16x16x32_bf16 v[50:53], v[174:177], v[194:197], v[50:53]
	v_mfma_f32_16x16x32_bf16 v[38:41], v[166:169], v[202:205], v[38:41]
	v_mfma_f32_16x16x32_bf16 v[34:37], v[174:177], v[202:205], v[34:37]
	v_mfma_f32_16x16x32_bf16 v[22:25], v[166:169], v[210:213], v[22:25]
	v_mfma_f32_16x16x32_bf16 v[18:21], v[174:177], v[210:213], v[18:21]
	v_mfma_f32_16x16x32_bf16 v[6:9], v[166:169], v[218:221], v[6:9]
	v_mfma_f32_16x16x32_bf16 v[2:5], v[174:177], v[218:221], v[2:5]
	s_setprio 0
	s_barrier
	s_add_i32 s49, s49, 2
	s_add_u32 s38, s38, 0x100
	s_addc_u32 s39, s39, 0
	s_add_u32 s46, s46, 0x100
	s_addc_u32 s47, s47, 0
	s_cmp_gt_u32 s49, 29
	s_cbranch_scc0 .LBB0_1018
	s_and_b64 vcc, exec, s[34:35]
	s_cbranch_vccz .LBB0_1021
	s_barrier

.LBB0_1230:
	s_add_u32 s38, s36, 0xfff80080
	s_addc_u32 s39, s37, -1
	s_add_i32 s64, 0, 0x10000
	s_cmp_eq_u32 s63, 28
	s_cselect_b32 s41, s57, s39
	s_cselect_b32 s40, s58, s38
	v_add_u32_e32 v155, s64, v153
	s_cselect_b32 s39, s59, s62
	s_cselect_b32 s38, s60, s61
	s_add_i32 s74, 0, 0x14000
	ds_read_b128 v[140:143], v155
	ds_read_b128 v[144:147], v155 offset:1024
	ds_read_b128 v[148:151], v155 offset:2048
	ds_read_b128 v[156:159], v155 offset:3072
	v_add_u32_e32 v155, s74, v153
	ds_read_b128 v[160:163], v155
	ds_read_b128 v[164:167], v155 offset:1024
	ds_read_b128 v[168:171], v155 offset:2048
	ds_read_b128 v[172:175], v155 offset:3072
	v_lshl_add_u64 v[218:219], s[36:37], 0, v[136:137]
	s_add_i32 m0, s11, 0xc000
	ds_read_b128 v[176:179], v154
	ds_read_b128 v[190:193], v154 offset:1024
	ds_read_b128 v[194:197], v154 offset:2048
	ds_read_b128 v[198:201], v154 offset:3072
	ds_read_b128 v[202:205], v154 offset:4096
	ds_read_b128 v[206:209], v154 offset:5120
	ds_read_b128 v[210:213], v154 offset:6144
	ds_read_b128 v[214:217], v154 offset:7168
	global_load_lds_dwordx4 v[218:219], off
	v_lshl_add_u64 v[218:219], s[36:37], 0, v[138:139]
	s_add_i32 m0, s11, 0xe000
	s_nop 0
	global_load_lds_dwordx4 v[218:219], off
	s_waitcnt vmcnt(8)
	s_waitcnt lgkmcnt(0)
	s_barrier
	s_setprio 1
	s_waitcnt lgkmcnt(0)
	v_mfma_f32_16x16x32_bf16 v[126:129], v[140:143], v[176:179], v[126:129]
	v_mfma_f32_16x16x32_bf16 v[122:125], v[148:151], v[176:179], v[122:125]
	v_mfma_f32_16x16x32_bf16 v[110:113], v[140:143], v[194:197], v[110:113]
	v_mfma_f32_16x16x32_bf16 v[106:109], v[148:151], v[194:197], v[106:109]
	v_mfma_f32_16x16x32_bf16 v[94:97], v[140:143], v[202:205], v[94:97]
	v_mfma_f32_16x16x32_bf16 v[90:93], v[148:151], v[202:205], v[90:93]
	v_mfma_f32_16x16x32_bf16 v[78:81], v[140:143], v[210:213], v[78:81]
	v_mfma_f32_16x16x32_bf16 v[74:77], v[148:151], v[210:213], v[74:77]
	v_mfma_f32_16x16x32_bf16 v[126:129], v[144:147], v[190:193], v[126:129]
	v_mfma_f32_16x16x32_bf16 v[122:125], v[156:159], v[190:193], v[122:125]
	v_mfma_f32_16x16x32_bf16 v[110:113], v[144:147], v[198:201], v[110:113]
	v_mfma_f32_16x16x32_bf16 v[106:109], v[156:159], v[198:201], v[106:109]
	v_mfma_f32_16x16x32_bf16 v[94:97], v[144:147], v[206:209], v[94:97]
	v_mfma_f32_16x16x32_bf16 v[90:93], v[156:159], v[206:209], v[90:93]
	v_mfma_f32_16x16x32_bf16 v[78:81], v[144:147], v[214:217], v[78:81]
	v_mfma_f32_16x16x32_bf16 v[74:77], v[156:159], v[214:217], v[74:77]
	v_mfma_f32_16x16x32_bf16 v[118:121], v[160:163], v[176:179], v[118:121]
	v_mfma_f32_16x16x32_bf16 v[114:117], v[168:171], v[176:179], v[114:117]
	v_mfma_f32_16x16x32_bf16 v[102:105], v[160:163], v[194:197], v[102:105]
	v_mfma_f32_16x16x32_bf16 v[98:101], v[168:171], v[194:197], v[98:101]
	v_mfma_f32_16x16x32_bf16 v[86:89], v[160:163], v[202:205], v[86:89]
	v_mfma_f32_16x16x32_bf16 v[82:85], v[168:171], v[202:205], v[82:85]
	v_mfma_f32_16x16x32_bf16 v[70:73], v[160:163], v[210:213], v[70:73]
	v_mfma_f32_16x16x32_bf16 v[66:69], v[168:171], v[210:213], v[66:69]
	v_mfma_f32_16x16x32_bf16 v[118:121], v[164:167], v[190:193], v[118:121]
	v_mfma_f32_16x16x32_bf16 v[114:117], v[172:175], v[190:193], v[114:117]
	v_mfma_f32_16x16x32_bf16 v[102:105], v[164:167], v[198:201], v[102:105]
	v_mfma_f32_16x16x32_bf16 v[98:101], v[172:175], v[198:201], v[98:101]
	v_mfma_f32_16x16x32_bf16 v[86:89], v[164:167], v[206:209], v[86:89]
	v_mfma_f32_16x16x32_bf16 v[82:85], v[172:175], v[206:209], v[82:85]
	v_mfma_f32_16x16x32_bf16 v[70:73], v[164:167], v[214:217], v[70:73]
	v_mfma_f32_16x16x32_bf16 v[66:69], v[172:175], v[214:217], v[66:69]
	s_setprio 0
	s_barrier
	s_add_i32 s64, s64, s43
	v_lshl_add_u64 v[218:219], s[38:39], 0, v[134:135]
	s_mov_b32 m0, s64
	ds_read_b128 v[176:179], v154 offset:16384
	ds_read_b128 v[190:193], v154 offset:17408
	ds_read_b128 v[194:197], v154 offset:18432
	ds_read_b128 v[198:201], v154 offset:19456
	ds_read_b128 v[202:205], v154 offset:20480
	ds_read_b128 v[206:209], v154 offset:21504
	ds_read_b128 v[210:213], v154 offset:22528
	ds_read_b128 v[214:217], v154 offset:23552
	global_load_lds_dwordx4 v[218:219], off
	s_add_i32 m0, s64, 0x2000
	s_add_u32 s70, s38, 0x80000
	v_lshl_add_u64 v[220:221], s[38:39], 0, v[132:133]
	s_addc_u32 s71, s39, 0
	s_add_i32 s64, s74, s43
	global_load_lds_dwordx4 v[220:221], off
	v_lshl_add_u64 v[222:223], s[70:71], 0, v[134:135]
	s_mov_b32 m0, s64
	v_lshl_add_u64 v[238:239], s[40:41], 0, v[132:133]
	global_load_lds_dwordx4 v[222:223], off
	v_lshl_add_u64 v[222:223], s[70:71], 0, v[132:133]
	s_add_i32 m0, s64, 0x2000
	s_nop 0
	global_load_lds_dwordx4 v[222:223], off
	v_lshl_add_u64 v[222:223], s[40:41], 0, v[134:135]
	s_mov_b32 m0, s11
	s_nop 0
	global_load_lds_dwordx4 v[222:223], off
	s_mov_b32 m0, s45
	s_nop 0
	global_load_lds_dwordx4 v[238:239], off
	s_waitcnt vmcnt(8)
	s_waitcnt lgkmcnt(0)
	s_barrier
	s_setprio 1
	s_waitcnt lgkmcnt(0)
	v_mfma_f32_16x16x32_bf16 v[62:65], v[140:143], v[176:179], v[62:65]
	v_mfma_f32_16x16x32_bf16 v[58:61], v[148:151], v[176:179], v[58:61]
	v_mfma_f32_16x16x32_bf16 v[46:49], v[140:143], v[194:197], v[46:49]
	v_mfma_f32_16x16x32_bf16 v[42:45], v[148:151], v[194:197], v[42:45]
	v_mfma_f32_16x16x32_bf16 v[30:33], v[140:143], v[202:205], v[30:33]
	v_mfma_f32_16x16x32_bf16 v[26:29], v[148:151], v[202:205], v[26:29]
	v_mfma_f32_16x16x32_bf16 v[14:17], v[140:143], v[210:213], v[14:17]
	v_mfma_f32_16x16x32_bf16 v[10:13], v[148:151], v[210:213], v[10:13]
	v_mfma_f32_16x16x32_bf16 v[62:65], v[144:147], v[190:193], v[62:65]
	v_mfma_f32_16x16x32_bf16 v[58:61], v[156:159], v[190:193], v[58:61]
	v_mfma_f32_16x16x32_bf16 v[46:49], v[144:147], v[198:201], v[46:49]
	v_mfma_f32_16x16x32_bf16 v[42:45], v[156:159], v[198:201], v[42:45]
	v_mfma_f32_16x16x32_bf16 v[30:33], v[144:147], v[206:209], v[30:33]
	v_mfma_f32_16x16x32_bf16 v[26:29], v[156:159], v[206:209], v[26:29]
	v_mfma_f32_16x16x32_bf16 v[14:17], v[144:147], v[214:217], v[14:17]
	v_mfma_f32_16x16x32_bf16 v[10:13], v[156:159], v[214:217], v[10:13]
	v_mfma_f32_16x16x32_bf16 v[54:57], v[160:163], v[176:179], v[54:57]
	v_mfma_f32_16x16x32_bf16 v[50:53], v[168:171], v[176:179], v[50:53]
	v_mfma_f32_16x16x32_bf16 v[38:41], v[160:163], v[194:197], v[38:41]
	v_mfma_f32_16x16x32_bf16 v[34:37], v[168:171], v[194:197], v[34:37]
	v_mfma_f32_16x16x32_bf16 v[22:25], v[160:163], v[202:205], v[22:25]
	v_mfma_f32_16x16x32_bf16 v[18:21], v[168:171], v[202:205], v[18:21]
	v_mfma_f32_16x16x32_bf16 v[6:9], v[160:163], v[210:213], v[6:9]
	v_mfma_f32_16x16x32_bf16 v[2:5], v[168:171], v[210:213], v[2:5]
	v_mfma_f32_16x16x32_bf16 v[54:57], v[164:167], v[190:193], v[54:57]
	v_mfma_f32_16x16x32_bf16 v[50:53], v[172:175], v[190:193], v[50:53]
	v_mfma_f32_16x16x32_bf16 v[38:41], v[164:167], v[198:201], v[38:41]
	v_mfma_f32_16x16x32_bf16 v[34:37], v[172:175], v[198:201], v[34:37]
	v_mfma_f32_16x16x32_bf16 v[22:25], v[164:167], v[206:209], v[22:25]
	v_mfma_f32_16x16x32_bf16 v[18:21], v[172:175], v[206:209], v[18:21]
	v_mfma_f32_16x16x32_bf16 v[6:9], v[164:167], v[214:217], v[6:9]
	v_mfma_f32_16x16x32_bf16 v[2:5], v[172:175], v[214:217], v[2:5]
	s_setprio 0
	s_barrier
	s_add_i32 s64, 0, 0x18000
	v_add_u32_e32 v155, s64, v153
	s_add_i32 s70, 0, 0x1c000
	ds_read_b128 v[140:143], v155
	ds_read_b128 v[144:147], v155 offset:1024
	ds_read_b128 v[148:151], v155 offset:2048
	ds_read_b128 v[156:159], v155 offset:3072
	v_add_u32_e32 v155, s70, v153
	ds_read_b128 v[160:163], v155
	ds_read_b128 v[164:167], v155 offset:1024
	ds_read_b128 v[168:171], v155 offset:2048
	ds_read_b128 v[172:175], v155 offset:3072
	s_add_u32 s40, s40, 0x80000
	s_addc_u32 s41, s41, 0
	s_mov_b32 m0, s46
	v_lshl_add_u64 v[240:241], s[40:41], 0, v[134:135]
	ds_read_b128 v[176:179], v154 offset:32768
	ds_read_b128 v[190:193], v154 offset:33792
	ds_read_b128 v[194:197], v154 offset:34816
	ds_read_b128 v[198:201], v154 offset:35840
	ds_read_b128 v[202:205], v154 offset:36864
	ds_read_b128 v[206:209], v154 offset:37888
	ds_read_b128 v[210:213], v154 offset:38912
	ds_read_b128 v[214:217], v154 offset:39936
	global_load_lds_dwordx4 v[240:241], off
	v_lshl_add_u64 v[240:241], s[40:41], 0, v[132:133]
	s_mov_b32 m0, s47
	s_nop 0
	global_load_lds_dwordx4 v[240:241], off
	s_waitcnt vmcnt(8)
	s_waitcnt lgkmcnt(0)
	s_barrier
	s_setprio 1
	s_waitcnt lgkmcnt(0)
	v_mfma_f32_16x16x32_bf16 v[126:129], v[140:143], v[176:179], v[126:129]
	v_mfma_f32_16x16x32_bf16 v[122:125], v[148:151], v[176:179], v[122:125]
	v_mfma_f32_16x16x32_bf16 v[110:113], v[140:143], v[194:197], v[110:113]
	v_mfma_f32_16x16x32_bf16 v[106:109], v[148:151], v[194:197], v[106:109]
	v_mfma_f32_16x16x32_bf16 v[94:97], v[140:143], v[202:205], v[94:97]
	v_mfma_f32_16x16x32_bf16 v[90:93], v[148:151], v[202:205], v[90:93]
	v_mfma_f32_16x16x32_bf16 v[78:81], v[140:143], v[210:213], v[78:81]
	v_mfma_f32_16x16x32_bf16 v[74:77], v[148:151], v[210:213], v[74:77]
	v_mfma_f32_16x16x32_bf16 v[126:129], v[144:147], v[190:193], v[126:129]
	v_mfma_f32_16x16x32_bf16 v[122:125], v[156:159], v[190:193], v[122:125]
	v_mfma_f32_16x16x32_bf16 v[110:113], v[144:147], v[198:201], v[110:113]
	v_mfma_f32_16x16x32_bf16 v[106:109], v[156:159], v[198:201], v[106:109]
	v_mfma_f32_16x16x32_bf16 v[94:97], v[144:147], v[206:209], v[94:97]
	v_mfma_f32_16x16x32_bf16 v[90:93], v[156:159], v[206:209], v[90:93]
	v_mfma_f32_16x16x32_bf16 v[78:81], v[144:147], v[214:217], v[78:81]
	v_mfma_f32_16x16x32_bf16 v[74:77], v[156:159], v[214:217], v[74:77]
	v_mfma_f32_16x16x32_bf16 v[118:121], v[160:163], v[176:179], v[118:121]
	v_mfma_f32_16x16x32_bf16 v[114:117], v[168:171], v[176:179], v[114:117]
	v_mfma_f32_16x16x32_bf16 v[102:105], v[160:163], v[194:197], v[102:105]
	v_mfma_f32_16x16x32_bf16 v[98:101], v[168:171], v[194:197], v[98:101]
	v_mfma_f32_16x16x32_bf16 v[86:89], v[160:163], v[202:205], v[86:89]
	v_mfma_f32_16x16x32_bf16 v[82:85], v[168:171], v[202:205], v[82:85]
	v_mfma_f32_16x16x32_bf16 v[70:73], v[160:163], v[210:213], v[70:73]
	v_mfma_f32_16x16x32_bf16 v[66:69], v[168:171], v[210:213], v[66:69]
	v_mfma_f32_16x16x32_bf16 v[118:121], v[164:167], v[190:193], v[118:121]
	v_mfma_f32_16x16x32_bf16 v[114:117], v[172:175], v[190:193], v[114:117]
	v_mfma_f32_16x16x32_bf16 v[102:105], v[164:167], v[198:201], v[102:105]
	v_mfma_f32_16x16x32_bf16 v[98:101], v[172:175], v[198:201], v[98:101]
	v_mfma_f32_16x16x32_bf16 v[86:89], v[164:167], v[206:209], v[86:89]
	v_mfma_f32_16x16x32_bf16 v[82:85], v[172:175], v[206:209], v[82:85]
	v_mfma_f32_16x16x32_bf16 v[70:73], v[164:167], v[214:217], v[70:73]
	v_mfma_f32_16x16x32_bf16 v[66:69], v[172:175], v[214:217], v[66:69]
	s_setprio 0
	s_barrier
	s_add_i32 s40, s64, s43
	v_lshl_add_u64 v[218:219], v[218:219], 0, s[16:17]
	s_mov_b32 m0, s40
	ds_read_b128 v[176:179], v154 offset:49152
	ds_read_b128 v[190:193], v154 offset:50176
	ds_read_b128 v[194:197], v154 offset:51200
	ds_read_b128 v[198:201], v154 offset:52224
	ds_read_b128 v[202:205], v154 offset:53248
	ds_read_b128 v[206:209], v154 offset:54272
	ds_read_b128 v[210:213], v154 offset:55296
	ds_read_b128 v[214:217], v154 offset:56320
	global_load_lds_dwordx4 v[218:219], off
	s_add_i32 m0, s40, 0x2000
	s_add_u32 s38, s38, 0x80080
	v_lshl_add_u64 v[218:219], v[220:221], 0, s[16:17]
	s_addc_u32 s39, s39, 0
	s_add_i32 s40, s70, s43
	global_load_lds_dwordx4 v[218:219], off
	v_lshl_add_u64 v[218:219], s[38:39], 0, v[134:135]
	s_mov_b32 m0, s40
	s_nop 0
	global_load_lds_dwordx4 v[218:219], off
	v_lshl_add_u64 v[218:219], s[38:39], 0, v[132:133]
	s_add_i32 m0, s40, 0x2000
	s_nop 0
	global_load_lds_dwordx4 v[218:219], off
	v_lshl_add_u64 v[218:219], v[222:223], 0, s[16:17]
	s_mov_b32 m0, s50
	s_nop 0
	global_load_lds_dwordx4 v[218:219], off
	v_lshl_add_u64 v[218:219], v[238:239], 0, s[16:17]
	s_mov_b32 m0, s51
	s_nop 0
	global_load_lds_dwordx4 v[218:219], off
	s_waitcnt vmcnt(8)
	s_waitcnt lgkmcnt(0)
	s_barrier
	s_setprio 1
	s_waitcnt lgkmcnt(0)
	v_mfma_f32_16x16x32_bf16 v[62:65], v[140:143], v[176:179], v[62:65]
	v_mfma_f32_16x16x32_bf16 v[58:61], v[148:151], v[176:179], v[58:61]
	v_mfma_f32_16x16x32_bf16 v[46:49], v[140:143], v[194:197], v[46:49]
	v_mfma_f32_16x16x32_bf16 v[42:45], v[148:151], v[194:197], v[42:45]
	v_mfma_f32_16x16x32_bf16 v[30:33], v[140:143], v[202:205], v[30:33]
	v_mfma_f32_16x16x32_bf16 v[26:29], v[148:151], v[202:205], v[26:29]
	v_mfma_f32_16x16x32_bf16 v[14:17], v[140:143], v[210:213], v[14:17]
	v_mfma_f32_16x16x32_bf16 v[10:13], v[148:151], v[210:213], v[10:13]
	v_mfma_f32_16x16x32_bf16 v[62:65], v[144:147], v[190:193], v[62:65]
	v_mfma_f32_16x16x32_bf16 v[58:61], v[156:159], v[190:193], v[58:61]
	v_mfma_f32_16x16x32_bf16 v[46:49], v[144:147], v[198:201], v[46:49]
	v_mfma_f32_16x16x32_bf16 v[42:45], v[156:159], v[198:201], v[42:45]
	v_mfma_f32_16x16x32_bf16 v[30:33], v[144:147], v[206:209], v[30:33]
	v_mfma_f32_16x16x32_bf16 v[26:29], v[156:159], v[206:209], v[26:29]
	v_mfma_f32_16x16x32_bf16 v[14:17], v[144:147], v[214:217], v[14:17]
	v_mfma_f32_16x16x32_bf16 v[10:13], v[156:159], v[214:217], v[10:13]
	v_mfma_f32_16x16x32_bf16 v[54:57], v[160:163], v[176:179], v[54:57]
	v_mfma_f32_16x16x32_bf16 v[50:53], v[168:171], v[176:179], v[50:53]
	v_mfma_f32_16x16x32_bf16 v[38:41], v[160:163], v[194:197], v[38:41]
	v_mfma_f32_16x16x32_bf16 v[34:37], v[168:171], v[194:197], v[34:37]
	v_mfma_f32_16x16x32_bf16 v[22:25], v[160:163], v[202:205], v[22:25]
	v_mfma_f32_16x16x32_bf16 v[18:21], v[168:171], v[202:205], v[18:21]
	v_mfma_f32_16x16x32_bf16 v[6:9], v[160:163], v[210:213], v[6:9]
	v_mfma_f32_16x16x32_bf16 v[2:5], v[168:171], v[210:213], v[2:5]
	v_mfma_f32_16x16x32_bf16 v[54:57], v[164:167], v[190:193], v[54:57]
	v_mfma_f32_16x16x32_bf16 v[50:53], v[172:175], v[190:193], v[50:53]
	v_mfma_f32_16x16x32_bf16 v[38:41], v[164:167], v[198:201], v[38:41]
	v_mfma_f32_16x16x32_bf16 v[34:37], v[172:175], v[198:201], v[34:37]
	v_mfma_f32_16x16x32_bf16 v[22:25], v[164:167], v[206:209], v[22:25]
	v_mfma_f32_16x16x32_bf16 v[18:21], v[172:175], v[206:209], v[18:21]
	v_mfma_f32_16x16x32_bf16 v[6:9], v[164:167], v[214:217], v[6:9]
	v_mfma_f32_16x16x32_bf16 v[2:5], v[172:175], v[214:217], v[2:5]
	s_setprio 0
	s_barrier
	s_add_i32 s63, s63, 2
	s_add_u32 s36, s36, 0x100
	s_addc_u32 s37, s37, 0
	s_add_u32 s61, s61, 0x100
	s_addc_u32 s62, s62, 0
	s_cmp_gt_u32 s63, 29
	s_cbranch_scc0 .LBB0_1230
	s_and_b64 vcc, exec, s[30:31]
	s_cbranch_vccz .LBB0_1233
	s_barrier

.LBB0_1583:
	s_add_u32 s46, s48, 0xfff80080
	s_addc_u32 s47, s49, -1
	s_add_i32 s68, 0, 0x10000
	s_cmp_eq_u32 s67, 28
	s_cselect_b32 s51, s35, s47
	s_cselect_b32 s50, s39, s46
	s_cselect_b32 s47, s31, s66
	s_cselect_b32 s46, s45, s64
	s_add_i32 s70, 0, 0x14000
	v_add_u32_e32 v162, s68, v152
	v_add_u32_e32 v178, s70, v152
	ds_read_b128 v[144:147], v162
	ds_read_b128 v[154:157], v162 offset:1024
	ds_read_b128 v[158:161], v162 offset:2048
	ds_read_b128 v[162:165], v162 offset:3072
	ds_read_b128 v[166:169], v178
	ds_read_b128 v[170:173], v178 offset:1024
	ds_read_b128 v[174:177], v178 offset:2048
	ds_read_b128 v[190:193], v178 offset:3072
	v_lshl_add_u64 v[178:179], s[48:49], 0, v[140:141]
	s_add_i32 m0, s56, 0xc000
	ds_read_b128 v[194:197], v153
	ds_read_b128 v[198:201], v153 offset:1024
	ds_read_b128 v[202:205], v153 offset:2048
	ds_read_b128 v[206:209], v153 offset:3072
	ds_read_b128 v[210:213], v153 offset:4096
	ds_read_b128 v[214:217], v153 offset:5120
	ds_read_b128 v[218:221], v153 offset:6144
	ds_read_b128 v[238:241], v153 offset:7168
	global_load_lds_dwordx4 v[178:179], off
	v_lshl_add_u64 v[178:179], s[48:49], 0, v[142:143]
	s_add_i32 m0, s56, 0xe000
	s_nop 0
	global_load_lds_dwordx4 v[178:179], off
	s_waitcnt vmcnt(8)
	s_waitcnt lgkmcnt(0)
	s_barrier
	s_setprio 1
	s_waitcnt lgkmcnt(0)
	v_mfma_f32_16x16x32_bf16 v[126:129], v[144:147], v[194:197], v[126:129]
	v_mfma_f32_16x16x32_bf16 v[114:117], v[158:161], v[194:197], v[114:117]
	v_mfma_f32_16x16x32_bf16 v[106:109], v[144:147], v[202:205], v[106:109]
	v_mfma_f32_16x16x32_bf16 v[98:101], v[158:161], v[202:205], v[98:101]
	v_mfma_f32_16x16x32_bf16 v[90:93], v[144:147], v[210:213], v[90:93]
	v_mfma_f32_16x16x32_bf16 v[82:85], v[158:161], v[210:213], v[82:85]
	v_mfma_f32_16x16x32_bf16 v[74:77], v[144:147], v[218:221], v[74:77]
	v_mfma_f32_16x16x32_bf16 v[54:57], v[158:161], v[218:221], v[54:57]
	v_mfma_f32_16x16x32_bf16 v[126:129], v[154:157], v[198:201], v[126:129]
	v_mfma_f32_16x16x32_bf16 v[114:117], v[162:165], v[198:201], v[114:117]
	v_mfma_f32_16x16x32_bf16 v[106:109], v[154:157], v[206:209], v[106:109]
	v_mfma_f32_16x16x32_bf16 v[98:101], v[162:165], v[206:209], v[98:101]
	v_mfma_f32_16x16x32_bf16 v[90:93], v[154:157], v[214:217], v[90:93]
	v_mfma_f32_16x16x32_bf16 v[82:85], v[162:165], v[214:217], v[82:85]
	v_mfma_f32_16x16x32_bf16 v[74:77], v[154:157], v[238:241], v[74:77]
	v_mfma_f32_16x16x32_bf16 v[54:57], v[162:165], v[238:241], v[54:57]
	v_mfma_f32_16x16x32_bf16 v[118:121], v[166:169], v[194:197], v[118:121]
	v_mfma_f32_16x16x32_bf16 v[122:125], v[174:177], v[194:197], v[122:125]
	v_mfma_f32_16x16x32_bf16 v[102:105], v[166:169], v[202:205], v[102:105]
	v_mfma_f32_16x16x32_bf16 v[110:113], v[174:177], v[202:205], v[110:113]
	v_mfma_f32_16x16x32_bf16 v[86:89], v[166:169], v[210:213], v[86:89]
	v_mfma_f32_16x16x32_bf16 v[94:97], v[174:177], v[210:213], v[94:97]
	v_mfma_f32_16x16x32_bf16 v[70:73], v[166:169], v[218:221], v[70:73]
	v_mfma_f32_16x16x32_bf16 v[78:81], v[174:177], v[218:221], v[78:81]
	v_mfma_f32_16x16x32_bf16 v[118:121], v[170:173], v[198:201], v[118:121]
	v_mfma_f32_16x16x32_bf16 v[122:125], v[190:193], v[198:201], v[122:125]
	v_mfma_f32_16x16x32_bf16 v[102:105], v[170:173], v[206:209], v[102:105]
	v_mfma_f32_16x16x32_bf16 v[110:113], v[190:193], v[206:209], v[110:113]
	v_mfma_f32_16x16x32_bf16 v[86:89], v[170:173], v[214:217], v[86:89]
	v_mfma_f32_16x16x32_bf16 v[94:97], v[190:193], v[214:217], v[94:97]
	v_mfma_f32_16x16x32_bf16 v[70:73], v[170:173], v[238:241], v[70:73]
	v_mfma_f32_16x16x32_bf16 v[78:81], v[190:193], v[238:241], v[78:81]
	s_setprio 0
	s_barrier
	s_add_i32 s68, s68, s8
	v_lshl_add_u64 v[178:179], s[46:47], 0, v[134:135]
	s_mov_b32 m0, s68
	ds_read_b128 v[194:197], v153 offset:16384
	ds_read_b128 v[198:201], v153 offset:17408
	ds_read_b128 v[202:205], v153 offset:18432
	ds_read_b128 v[206:209], v153 offset:19456
	ds_read_b128 v[210:213], v153 offset:20480
	ds_read_b128 v[214:217], v153 offset:21504
	ds_read_b128 v[218:221], v153 offset:22528
	ds_read_b128 v[238:241], v153 offset:23552
	global_load_lds_dwordx4 v[178:179], off
	s_add_i32 m0, s68, 0x2000
	s_add_u32 s68, s46, 0x80000
	v_lshl_add_u64 v[222:223], s[46:47], 0, v[138:139]
	s_addc_u32 s69, s47, 0
	s_add_i32 s70, s70, s8
	global_load_lds_dwordx4 v[222:223], off
	v_lshl_add_u64 v[242:243], s[68:69], 0, v[134:135]
	s_mov_b32 m0, s70
	v_lshl_add_u64 v[244:245], s[50:51], 0, v[136:137]
	global_load_lds_dwordx4 v[242:243], off
	v_lshl_add_u64 v[242:243], s[68:69], 0, v[138:139]
	s_add_i32 m0, s70, 0x2000
	s_nop 0
	global_load_lds_dwordx4 v[242:243], off
	v_lshl_add_u64 v[242:243], s[50:51], 0, v[132:133]
	s_mov_b32 m0, s56
	s_nop 0
	global_load_lds_dwordx4 v[242:243], off
	s_mov_b32 m0, s57
	s_nop 0
	global_load_lds_dwordx4 v[244:245], off
	s_waitcnt vmcnt(8)
	s_waitcnt lgkmcnt(0)
	s_barrier
	s_setprio 1
	s_waitcnt lgkmcnt(0)
	v_mfma_f32_16x16x32_bf16 v[50:53], v[144:147], v[194:197], v[50:53]
	v_mfma_f32_16x16x32_bf16 v[38:41], v[158:161], v[194:197], v[38:41]
	v_mfma_f32_16x16x32_bf16 v[22:25], v[144:147], v[202:205], v[22:25]
	v_mfma_f32_16x16x32_bf16 v[42:45], v[158:161], v[202:205], v[42:45]
	v_mfma_f32_16x16x32_bf16 v[30:33], v[144:147], v[210:213], v[30:33]
	v_mfma_f32_16x16x32_bf16 v[18:21], v[158:161], v[210:213], v[18:21]
	v_mfma_f32_16x16x32_bf16 v[10:13], v[144:147], v[218:221], v[10:13]
	v_mfma_f32_16x16x32_bf16 v[2:5], v[158:161], v[218:221], v[2:5]
	v_mfma_f32_16x16x32_bf16 v[50:53], v[154:157], v[198:201], v[50:53]
	v_mfma_f32_16x16x32_bf16 v[38:41], v[162:165], v[198:201], v[38:41]
	v_mfma_f32_16x16x32_bf16 v[22:25], v[154:157], v[206:209], v[22:25]
	v_mfma_f32_16x16x32_bf16 v[42:45], v[162:165], v[206:209], v[42:45]
	v_mfma_f32_16x16x32_bf16 v[30:33], v[154:157], v[214:217], v[30:33]
	v_mfma_f32_16x16x32_bf16 v[18:21], v[162:165], v[214:217], v[18:21]
	v_mfma_f32_16x16x32_bf16 v[10:13], v[154:157], v[238:241], v[10:13]
	v_mfma_f32_16x16x32_bf16 v[2:5], v[162:165], v[238:241], v[2:5]
	v_mfma_f32_16x16x32_bf16 v[46:49], v[166:169], v[194:197], v[46:49]
	v_mfma_f32_16x16x32_bf16 v[58:61], v[174:177], v[194:197], v[58:61]
	v_mfma_f32_16x16x32_bf16 v[62:65], v[166:169], v[202:205], v[62:65]
	v_mfma_f32_16x16x32_bf16 v[66:69], v[174:177], v[202:205], v[66:69]
	v_mfma_f32_16x16x32_bf16 v[26:29], v[166:169], v[210:213], v[26:29]
	v_mfma_f32_16x16x32_bf16 v[34:37], v[174:177], v[210:213], v[34:37]
	v_mfma_f32_16x16x32_bf16 v[6:9], v[166:169], v[218:221], v[6:9]
	v_mfma_f32_16x16x32_bf16 v[14:17], v[174:177], v[218:221], v[14:17]
	v_mfma_f32_16x16x32_bf16 v[46:49], v[170:173], v[198:201], v[46:49]
	v_mfma_f32_16x16x32_bf16 v[58:61], v[190:193], v[198:201], v[58:61]
	v_mfma_f32_16x16x32_bf16 v[62:65], v[170:173], v[206:209], v[62:65]
	v_mfma_f32_16x16x32_bf16 v[66:69], v[190:193], v[206:209], v[66:69]
	v_mfma_f32_16x16x32_bf16 v[26:29], v[170:173], v[214:217], v[26:29]
	v_mfma_f32_16x16x32_bf16 v[34:37], v[190:193], v[214:217], v[34:37]
	v_mfma_f32_16x16x32_bf16 v[6:9], v[170:173], v[238:241], v[6:9]
	v_mfma_f32_16x16x32_bf16 v[14:17], v[190:193], v[238:241], v[14:17]
	s_setprio 0
	s_barrier
	s_add_i32 s68, 0, 0x18000
	s_add_i32 s69, 0, 0x1c000
	v_add_u32_e32 v162, s68, v152
	v_add_u32_e32 v190, s69, v152
	ds_read_b128 v[144:147], v162
	ds_read_b128 v[154:157], v162 offset:1024
	ds_read_b128 v[158:161], v162 offset:2048
	ds_read_b128 v[162:165], v162 offset:3072
	ds_read_b128 v[166:169], v190
	ds_read_b128 v[170:173], v190 offset:1024
	ds_read_b128 v[174:177], v190 offset:2048
	ds_read_b128 v[190:193], v190 offset:3072
	s_add_u32 s50, s50, 0x80000
	s_addc_u32 s51, s51, 0
	s_mov_b32 m0, s58
	v_lshl_add_u64 v[246:247], s[50:51], 0, v[132:133]
	ds_read_b128 v[194:197], v153 offset:32768
	ds_read_b128 v[198:201], v153 offset:33792
	ds_read_b128 v[202:205], v153 offset:34816
	ds_read_b128 v[206:209], v153 offset:35840
	ds_read_b128 v[210:213], v153 offset:36864
	ds_read_b128 v[214:217], v153 offset:37888
	ds_read_b128 v[218:221], v153 offset:38912
	ds_read_b128 v[238:241], v153 offset:39936
	global_load_lds_dwordx4 v[246:247], off
	v_lshl_add_u64 v[246:247], s[50:51], 0, v[136:137]
	s_mov_b32 m0, s59
	s_nop 0
	global_load_lds_dwordx4 v[246:247], off
	s_waitcnt vmcnt(8)
	s_waitcnt lgkmcnt(0)
	s_barrier
	s_setprio 1
	s_waitcnt lgkmcnt(0)
	v_mfma_f32_16x16x32_bf16 v[126:129], v[144:147], v[194:197], v[126:129]
	v_mfma_f32_16x16x32_bf16 v[114:117], v[158:161], v[194:197], v[114:117]
	v_mfma_f32_16x16x32_bf16 v[106:109], v[144:147], v[202:205], v[106:109]
	v_mfma_f32_16x16x32_bf16 v[98:101], v[158:161], v[202:205], v[98:101]
	v_mfma_f32_16x16x32_bf16 v[90:93], v[144:147], v[210:213], v[90:93]
	v_mfma_f32_16x16x32_bf16 v[82:85], v[158:161], v[210:213], v[82:85]
	v_mfma_f32_16x16x32_bf16 v[74:77], v[144:147], v[218:221], v[74:77]
	v_mfma_f32_16x16x32_bf16 v[54:57], v[158:161], v[218:221], v[54:57]
	v_mfma_f32_16x16x32_bf16 v[126:129], v[154:157], v[198:201], v[126:129]
	v_mfma_f32_16x16x32_bf16 v[114:117], v[162:165], v[198:201], v[114:117]
	v_mfma_f32_16x16x32_bf16 v[106:109], v[154:157], v[206:209], v[106:109]
	v_mfma_f32_16x16x32_bf16 v[98:101], v[162:165], v[206:209], v[98:101]
	v_mfma_f32_16x16x32_bf16 v[90:93], v[154:157], v[214:217], v[90:93]
	v_mfma_f32_16x16x32_bf16 v[82:85], v[162:165], v[214:217], v[82:85]
	v_mfma_f32_16x16x32_bf16 v[74:77], v[154:157], v[238:241], v[74:77]
	v_mfma_f32_16x16x32_bf16 v[54:57], v[162:165], v[238:241], v[54:57]
	v_mfma_f32_16x16x32_bf16 v[118:121], v[166:169], v[194:197], v[118:121]
	v_mfma_f32_16x16x32_bf16 v[122:125], v[174:177], v[194:197], v[122:125]
	v_mfma_f32_16x16x32_bf16 v[102:105], v[166:169], v[202:205], v[102:105]
	v_mfma_f32_16x16x32_bf16 v[110:113], v[174:177], v[202:205], v[110:113]
	v_mfma_f32_16x16x32_bf16 v[86:89], v[166:169], v[210:213], v[86:89]
	v_mfma_f32_16x16x32_bf16 v[94:97], v[174:177], v[210:213], v[94:97]
	v_mfma_f32_16x16x32_bf16 v[70:73], v[166:169], v[218:221], v[70:73]
	v_mfma_f32_16x16x32_bf16 v[78:81], v[174:177], v[218:221], v[78:81]
	v_mfma_f32_16x16x32_bf16 v[118:121], v[170:173], v[198:201], v[118:121]
	v_mfma_f32_16x16x32_bf16 v[122:125], v[190:193], v[198:201], v[122:125]
	v_mfma_f32_16x16x32_bf16 v[102:105], v[170:173], v[206:209], v[102:105]
	v_mfma_f32_16x16x32_bf16 v[110:113], v[190:193], v[206:209], v[110:113]
	v_mfma_f32_16x16x32_bf16 v[86:89], v[170:173], v[214:217], v[86:89]
	v_mfma_f32_16x16x32_bf16 v[94:97], v[190:193], v[214:217], v[94:97]
	v_mfma_f32_16x16x32_bf16 v[70:73], v[170:173], v[238:241], v[70:73]
	v_mfma_f32_16x16x32_bf16 v[78:81], v[190:193], v[238:241], v[78:81]
	s_setprio 0
	s_barrier
	s_add_i32 s50, s68, s8
	v_lshl_add_u64 v[178:179], v[178:179], 0, s[16:17]
	s_mov_b32 m0, s50
	ds_read_b128 v[194:197], v153 offset:49152
	ds_read_b128 v[198:201], v153 offset:50176
	ds_read_b128 v[202:205], v153 offset:51200
	ds_read_b128 v[206:209], v153 offset:52224
	ds_read_b128 v[210:213], v153 offset:53248
	ds_read_b128 v[214:217], v153 offset:54272
	ds_read_b128 v[218:221], v153 offset:55296
	ds_read_b128 v[238:241], v153 offset:56320
	global_load_lds_dwordx4 v[178:179], off
	s_add_i32 m0, s50, 0x2000
	s_add_u32 s46, s46, 0x80080
	v_lshl_add_u64 v[178:179], v[222:223], 0, s[16:17]
	s_addc_u32 s47, s47, 0
	s_add_i32 s50, s69, s8
	global_load_lds_dwordx4 v[178:179], off
	v_lshl_add_u64 v[178:179], s[46:47], 0, v[134:135]
	s_mov_b32 m0, s50
	s_nop 0
	global_load_lds_dwordx4 v[178:179], off
	v_lshl_add_u64 v[178:179], s[46:47], 0, v[138:139]
	s_add_i32 m0, s50, 0x2000
	s_nop 0
	global_load_lds_dwordx4 v[178:179], off
	v_lshl_add_u64 v[178:179], v[242:243], 0, s[16:17]
	s_mov_b32 m0, s60
	s_nop 0
	global_load_lds_dwordx4 v[178:179], off
	v_lshl_add_u64 v[178:179], v[244:245], 0, s[16:17]
	s_mov_b32 m0, s61
	s_nop 0
	global_load_lds_dwordx4 v[178:179], off
	s_waitcnt vmcnt(8)
	s_waitcnt lgkmcnt(0)
	s_barrier
	s_setprio 1
	s_waitcnt lgkmcnt(0)
	v_mfma_f32_16x16x32_bf16 v[50:53], v[144:147], v[194:197], v[50:53]
	v_mfma_f32_16x16x32_bf16 v[38:41], v[158:161], v[194:197], v[38:41]
	v_mfma_f32_16x16x32_bf16 v[22:25], v[144:147], v[202:205], v[22:25]
	v_mfma_f32_16x16x32_bf16 v[42:45], v[158:161], v[202:205], v[42:45]
	v_mfma_f32_16x16x32_bf16 v[30:33], v[144:147], v[210:213], v[30:33]
	v_mfma_f32_16x16x32_bf16 v[18:21], v[158:161], v[210:213], v[18:21]
	v_mfma_f32_16x16x32_bf16 v[10:13], v[144:147], v[218:221], v[10:13]
	v_mfma_f32_16x16x32_bf16 v[2:5], v[158:161], v[218:221], v[2:5]
	v_mfma_f32_16x16x32_bf16 v[50:53], v[154:157], v[198:201], v[50:53]
	v_mfma_f32_16x16x32_bf16 v[38:41], v[162:165], v[198:201], v[38:41]
	v_mfma_f32_16x16x32_bf16 v[22:25], v[154:157], v[206:209], v[22:25]
	v_mfma_f32_16x16x32_bf16 v[42:45], v[162:165], v[206:209], v[42:45]
	v_mfma_f32_16x16x32_bf16 v[30:33], v[154:157], v[214:217], v[30:33]
	v_mfma_f32_16x16x32_bf16 v[18:21], v[162:165], v[214:217], v[18:21]
	v_mfma_f32_16x16x32_bf16 v[10:13], v[154:157], v[238:241], v[10:13]
	v_mfma_f32_16x16x32_bf16 v[2:5], v[162:165], v[238:241], v[2:5]
	v_mfma_f32_16x16x32_bf16 v[46:49], v[166:169], v[194:197], v[46:49]
	v_mfma_f32_16x16x32_bf16 v[58:61], v[174:177], v[194:197], v[58:61]
	v_mfma_f32_16x16x32_bf16 v[62:65], v[166:169], v[202:205], v[62:65]
	v_mfma_f32_16x16x32_bf16 v[66:69], v[174:177], v[202:205], v[66:69]
	v_mfma_f32_16x16x32_bf16 v[26:29], v[166:169], v[210:213], v[26:29]
	v_mfma_f32_16x16x32_bf16 v[34:37], v[174:177], v[210:213], v[34:37]
	v_mfma_f32_16x16x32_bf16 v[6:9], v[166:169], v[218:221], v[6:9]
	v_mfma_f32_16x16x32_bf16 v[14:17], v[174:177], v[218:221], v[14:17]
	v_mfma_f32_16x16x32_bf16 v[46:49], v[170:173], v[198:201], v[46:49]
	v_mfma_f32_16x16x32_bf16 v[58:61], v[190:193], v[198:201], v[58:61]
	v_mfma_f32_16x16x32_bf16 v[62:65], v[170:173], v[206:209], v[62:65]
	v_mfma_f32_16x16x32_bf16 v[66:69], v[190:193], v[206:209], v[66:69]
	v_mfma_f32_16x16x32_bf16 v[26:29], v[170:173], v[214:217], v[26:29]
	v_mfma_f32_16x16x32_bf16 v[34:37], v[190:193], v[214:217], v[34:37]
	v_mfma_f32_16x16x32_bf16 v[6:9], v[170:173], v[238:241], v[6:9]
	v_mfma_f32_16x16x32_bf16 v[14:17], v[190:193], v[238:241], v[14:17]
	s_setprio 0
	s_barrier
	s_add_i32 s67, s67, 2
	s_add_u32 s48, s48, 0x100
	s_addc_u32 s49, s49, 0
	s_add_u32 s64, s64, 0x100
	s_addc_u32 s66, s66, 0
	s_cmp_gt_u32 s67, 29
	s_cbranch_scc0 .LBB0_1583
	s_and_b64 vcc, exec, s[28:29]
	s_cbranch_vccz .LBB0_1586
	s_barrier

.LBB0_1685:
	s_add_u32 s42, s40, 0xfff80080
	s_addc_u32 s43, s41, -1
	s_and_b64 s[26:27], s[26:27], exec
	s_cselect_b32 s43, s19, s43
	s_cselect_b32 s42, s45, s42
	s_cselect_b32 s27, s50, s39
	s_cselect_b32 s26, s51, s37
	s_add_i32 s47, 0, 0x10000
	s_add_i32 s69, 0, 0x14000
	v_add_u32_e32 v146, s47, v239
	v_add_u32_e32 v162, s69, v239
	ds_read_b128 v[114:117], v146
	ds_read_b128 v[118:121], v146 offset:1024
	ds_read_b128 v[122:125], v146 offset:2048
	ds_read_b128 v[146:149], v146 offset:3072
	ds_read_b128 v[150:153], v162
	ds_read_b128 v[154:157], v162 offset:1024
	ds_read_b128 v[158:161], v162 offset:2048
	ds_read_b128 v[162:165], v162 offset:3072
	v_lshl_add_u64 v[178:179], s[40:41], 0, v[202:203]
	s_add_i32 m0, s6, 0xc000
	ds_read_b128 v[166:169], v240
	ds_read_b128 v[170:173], v240 offset:1024
	ds_read_b128 v[174:177], v240 offset:2048
	ds_read_b128 v[206:209], v240 offset:3072
	ds_read_b128 v[210:213], v240 offset:4096
	ds_read_b128 v[214:217], v240 offset:5120
	ds_read_b128 v[218:221], v240 offset:6144
	ds_read_b128 v[242:245], v240 offset:7168
	global_load_lds_dwordx4 v[178:179], off
	v_lshl_add_u64 v[178:179], s[40:41], 0, v[204:205]
	s_add_i32 m0, s6, 0xe000
	s_nop 0
	global_load_lds_dwordx4 v[178:179], off
	s_waitcnt vmcnt(8)
	s_waitcnt lgkmcnt(0)
	s_barrier
	s_setprio 1
	s_waitcnt lgkmcnt(0)
	v_mfma_f32_16x16x32_bf16 v[142:145], v[114:117], v[166:169], v[142:145]
	v_mfma_f32_16x16x32_bf16 v[62:65], v[122:125], v[166:169], v[62:65]
	v_mfma_f32_16x16x32_bf16 v[134:137], v[114:117], v[174:177], v[134:137]
	v_mfma_f32_16x16x32_bf16 v[54:57], v[122:125], v[174:177], v[54:57]
	v_mfma_f32_16x16x32_bf16 v[126:129], v[114:117], v[210:213], v[126:129]
	v_mfma_f32_16x16x32_bf16 v[46:49], v[122:125], v[210:213], v[46:49]
	v_mfma_f32_16x16x32_bf16 v[102:105], v[114:117], v[218:221], v[102:105]
	v_mfma_f32_16x16x32_bf16 v[38:41], v[122:125], v[218:221], v[38:41]
	v_mfma_f32_16x16x32_bf16 v[142:145], v[118:121], v[170:173], v[142:145]
	v_mfma_f32_16x16x32_bf16 v[62:65], v[146:149], v[170:173], v[62:65]
	v_mfma_f32_16x16x32_bf16 v[134:137], v[118:121], v[206:209], v[134:137]
	v_mfma_f32_16x16x32_bf16 v[54:57], v[146:149], v[206:209], v[54:57]
	v_mfma_f32_16x16x32_bf16 v[126:129], v[118:121], v[214:217], v[126:129]
	v_mfma_f32_16x16x32_bf16 v[46:49], v[146:149], v[214:217], v[46:49]
	v_mfma_f32_16x16x32_bf16 v[102:105], v[118:121], v[242:245], v[102:105]
	v_mfma_f32_16x16x32_bf16 v[38:41], v[146:149], v[242:245], v[38:41]
	v_mfma_f32_16x16x32_bf16 v[138:141], v[150:153], v[166:169], v[138:141]
	v_mfma_f32_16x16x32_bf16 v[58:61], v[158:161], v[166:169], v[58:61]
	v_mfma_f32_16x16x32_bf16 v[130:133], v[150:153], v[174:177], v[130:133]
	v_mfma_f32_16x16x32_bf16 v[50:53], v[158:161], v[174:177], v[50:53]
	v_mfma_f32_16x16x32_bf16 v[106:109], v[150:153], v[210:213], v[106:109]
	v_mfma_f32_16x16x32_bf16 v[42:45], v[158:161], v[210:213], v[42:45]
	v_mfma_f32_16x16x32_bf16 v[98:101], v[150:153], v[218:221], v[98:101]
	v_mfma_f32_16x16x32_bf16 v[34:37], v[158:161], v[218:221], v[34:37]
	v_mfma_f32_16x16x32_bf16 v[138:141], v[154:157], v[170:173], v[138:141]
	v_mfma_f32_16x16x32_bf16 v[58:61], v[162:165], v[170:173], v[58:61]
	v_mfma_f32_16x16x32_bf16 v[130:133], v[154:157], v[206:209], v[130:133]
	v_mfma_f32_16x16x32_bf16 v[50:53], v[162:165], v[206:209], v[50:53]
	v_mfma_f32_16x16x32_bf16 v[106:109], v[154:157], v[214:217], v[106:109]
	v_mfma_f32_16x16x32_bf16 v[42:45], v[162:165], v[214:217], v[42:45]
	v_mfma_f32_16x16x32_bf16 v[98:101], v[154:157], v[242:245], v[98:101]
	v_mfma_f32_16x16x32_bf16 v[34:37], v[162:165], v[242:245], v[34:37]
	s_setprio 0
	s_barrier
	s_add_i32 s47, s47, s23
	v_lshl_add_u64 v[178:179], s[26:27], 0, v[180:181]
	s_mov_b32 m0, s47
	ds_read_b128 v[166:169], v240 offset:16384
	ds_read_b128 v[170:173], v240 offset:17408
	ds_read_b128 v[174:177], v240 offset:18432
	ds_read_b128 v[206:209], v240 offset:19456
	ds_read_b128 v[210:213], v240 offset:20480
	ds_read_b128 v[214:217], v240 offset:21504
	ds_read_b128 v[218:221], v240 offset:22528
	ds_read_b128 v[242:245], v240 offset:23552
	global_load_lds_dwordx4 v[178:179], off
	s_add_i32 m0, s47, 0x2000
	s_add_u32 s48, s26, 0x80000
	v_lshl_add_u64 v[222:223], s[26:27], 0, v[196:197]
	s_addc_u32 s49, s27, 0
	s_add_i32 s47, s69, s23
	global_load_lds_dwordx4 v[222:223], off
	v_lshl_add_u64 v[246:247], s[48:49], 0, v[180:181]
	s_mov_b32 m0, s47
	v_lshl_add_u64 v[248:249], s[42:43], 0, v[194:195]
	global_load_lds_dwordx4 v[246:247], off
	v_lshl_add_u64 v[246:247], s[48:49], 0, v[196:197]
	s_add_i32 m0, s47, 0x2000
	s_nop 0
	global_load_lds_dwordx4 v[246:247], off
	v_lshl_add_u64 v[246:247], s[42:43], 0, v[192:193]
	s_mov_b32 m0, s6
	s_nop 0
	global_load_lds_dwordx4 v[246:247], off
	s_mov_b32 m0, s9
	s_nop 0
	global_load_lds_dwordx4 v[248:249], off
	s_waitcnt vmcnt(8)
	s_waitcnt lgkmcnt(0)
	s_barrier
	s_setprio 1
	s_waitcnt lgkmcnt(0)
	v_mfma_f32_16x16x32_bf16 v[94:97], v[114:117], v[166:169], v[94:97]
	v_mfma_f32_16x16x32_bf16 v[30:33], v[122:125], v[166:169], v[30:33]
	v_mfma_f32_16x16x32_bf16 v[86:89], v[114:117], v[174:177], v[86:89]
	v_mfma_f32_16x16x32_bf16 v[22:25], v[122:125], v[174:177], v[22:25]
	v_mfma_f32_16x16x32_bf16 v[78:81], v[114:117], v[210:213], v[78:81]
	v_mfma_f32_16x16x32_bf16 v[14:17], v[122:125], v[210:213], v[14:17]
	v_mfma_f32_16x16x32_bf16 v[70:73], v[114:117], v[218:221], v[70:73]
	v_mfma_f32_16x16x32_bf16 v[6:9], v[122:125], v[218:221], v[6:9]
	v_mfma_f32_16x16x32_bf16 v[94:97], v[118:121], v[170:173], v[94:97]
	v_mfma_f32_16x16x32_bf16 v[30:33], v[146:149], v[170:173], v[30:33]
	v_mfma_f32_16x16x32_bf16 v[86:89], v[118:121], v[206:209], v[86:89]
	v_mfma_f32_16x16x32_bf16 v[22:25], v[146:149], v[206:209], v[22:25]
	v_mfma_f32_16x16x32_bf16 v[78:81], v[118:121], v[214:217], v[78:81]
	v_mfma_f32_16x16x32_bf16 v[14:17], v[146:149], v[214:217], v[14:17]
	v_mfma_f32_16x16x32_bf16 v[70:73], v[118:121], v[242:245], v[70:73]
	v_mfma_f32_16x16x32_bf16 v[6:9], v[146:149], v[242:245], v[6:9]
	v_mfma_f32_16x16x32_bf16 v[90:93], v[150:153], v[166:169], v[90:93]
	v_mfma_f32_16x16x32_bf16 v[26:29], v[158:161], v[166:169], v[26:29]
	v_mfma_f32_16x16x32_bf16 v[82:85], v[150:153], v[174:177], v[82:85]
	v_mfma_f32_16x16x32_bf16 v[18:21], v[158:161], v[174:177], v[18:21]
	v_mfma_f32_16x16x32_bf16 v[74:77], v[150:153], v[210:213], v[74:77]
	v_mfma_f32_16x16x32_bf16 v[10:13], v[158:161], v[210:213], v[10:13]
	v_mfma_f32_16x16x32_bf16 v[66:69], v[150:153], v[218:221], v[66:69]
	v_mfma_f32_16x16x32_bf16 v[2:5], v[158:161], v[218:221], v[2:5]
	v_mfma_f32_16x16x32_bf16 v[90:93], v[154:157], v[170:173], v[90:93]
	v_mfma_f32_16x16x32_bf16 v[26:29], v[162:165], v[170:173], v[26:29]
	v_mfma_f32_16x16x32_bf16 v[82:85], v[154:157], v[206:209], v[82:85]
	v_mfma_f32_16x16x32_bf16 v[18:21], v[162:165], v[206:209], v[18:21]
	v_mfma_f32_16x16x32_bf16 v[74:77], v[154:157], v[214:217], v[74:77]
	v_mfma_f32_16x16x32_bf16 v[10:13], v[162:165], v[214:217], v[10:13]
	v_mfma_f32_16x16x32_bf16 v[66:69], v[154:157], v[242:245], v[66:69]
	v_mfma_f32_16x16x32_bf16 v[2:5], v[162:165], v[242:245], v[2:5]
	s_setprio 0
	s_barrier
	s_add_i32 s47, 0, 0x18000
	s_add_i32 s48, 0, 0x1c000
	v_add_u32_e32 v146, s47, v239
	v_add_u32_e32 v162, s48, v239
	ds_read_b128 v[114:117], v146
	ds_read_b128 v[118:121], v146 offset:1024
	ds_read_b128 v[122:125], v146 offset:2048
	ds_read_b128 v[146:149], v146 offset:3072
	ds_read_b128 v[150:153], v162
	ds_read_b128 v[154:157], v162 offset:1024
	ds_read_b128 v[158:161], v162 offset:2048
	ds_read_b128 v[162:165], v162 offset:3072
	s_add_u32 s42, s42, 0x80000
	s_addc_u32 s43, s43, 0
	s_mov_b32 m0, s21
	v_lshl_add_u64 v[250:251], s[42:43], 0, v[192:193]
	ds_read_b128 v[166:169], v240 offset:32768
	ds_read_b128 v[170:173], v240 offset:33792
	ds_read_b128 v[174:177], v240 offset:34816
	ds_read_b128 v[206:209], v240 offset:35840
	ds_read_b128 v[210:213], v240 offset:36864
	ds_read_b128 v[214:217], v240 offset:37888
	ds_read_b128 v[218:221], v240 offset:38912
	ds_read_b128 v[242:245], v240 offset:39936
	global_load_lds_dwordx4 v[250:251], off
	v_lshl_add_u64 v[250:251], s[42:43], 0, v[194:195]
	s_mov_b32 m0, s7
	s_nop 0
	global_load_lds_dwordx4 v[250:251], off
	s_waitcnt vmcnt(8)
	s_waitcnt lgkmcnt(0)
	s_barrier
	s_setprio 1
	s_waitcnt lgkmcnt(0)
	v_mfma_f32_16x16x32_bf16 v[142:145], v[114:117], v[166:169], v[142:145]
	v_mfma_f32_16x16x32_bf16 v[62:65], v[122:125], v[166:169], v[62:65]
	v_mfma_f32_16x16x32_bf16 v[134:137], v[114:117], v[174:177], v[134:137]
	v_mfma_f32_16x16x32_bf16 v[54:57], v[122:125], v[174:177], v[54:57]
	v_mfma_f32_16x16x32_bf16 v[126:129], v[114:117], v[210:213], v[126:129]
	v_mfma_f32_16x16x32_bf16 v[46:49], v[122:125], v[210:213], v[46:49]
	v_mfma_f32_16x16x32_bf16 v[102:105], v[114:117], v[218:221], v[102:105]
	v_mfma_f32_16x16x32_bf16 v[38:41], v[122:125], v[218:221], v[38:41]
	v_mfma_f32_16x16x32_bf16 v[142:145], v[118:121], v[170:173], v[142:145]
	v_mfma_f32_16x16x32_bf16 v[62:65], v[146:149], v[170:173], v[62:65]
	v_mfma_f32_16x16x32_bf16 v[134:137], v[118:121], v[206:209], v[134:137]
	v_mfma_f32_16x16x32_bf16 v[54:57], v[146:149], v[206:209], v[54:57]
	v_mfma_f32_16x16x32_bf16 v[126:129], v[118:121], v[214:217], v[126:129]
	v_mfma_f32_16x16x32_bf16 v[46:49], v[146:149], v[214:217], v[46:49]
	v_mfma_f32_16x16x32_bf16 v[102:105], v[118:121], v[242:245], v[102:105]
	v_mfma_f32_16x16x32_bf16 v[38:41], v[146:149], v[242:245], v[38:41]
	v_mfma_f32_16x16x32_bf16 v[138:141], v[150:153], v[166:169], v[138:141]
	v_mfma_f32_16x16x32_bf16 v[58:61], v[158:161], v[166:169], v[58:61]
	v_mfma_f32_16x16x32_bf16 v[130:133], v[150:153], v[174:177], v[130:133]
	v_mfma_f32_16x16x32_bf16 v[50:53], v[158:161], v[174:177], v[50:53]
	v_mfma_f32_16x16x32_bf16 v[106:109], v[150:153], v[210:213], v[106:109]
	v_mfma_f32_16x16x32_bf16 v[42:45], v[158:161], v[210:213], v[42:45]
	v_mfma_f32_16x16x32_bf16 v[98:101], v[150:153], v[218:221], v[98:101]
	v_mfma_f32_16x16x32_bf16 v[34:37], v[158:161], v[218:221], v[34:37]
	v_mfma_f32_16x16x32_bf16 v[138:141], v[154:157], v[170:173], v[138:141]
	v_mfma_f32_16x16x32_bf16 v[58:61], v[162:165], v[170:173], v[58:61]
	v_mfma_f32_16x16x32_bf16 v[130:133], v[154:157], v[206:209], v[130:133]
	v_mfma_f32_16x16x32_bf16 v[50:53], v[162:165], v[206:209], v[50:53]
	v_mfma_f32_16x16x32_bf16 v[106:109], v[154:157], v[214:217], v[106:109]
	v_mfma_f32_16x16x32_bf16 v[42:45], v[162:165], v[214:217], v[42:45]
	v_mfma_f32_16x16x32_bf16 v[98:101], v[154:157], v[242:245], v[98:101]
	v_mfma_f32_16x16x32_bf16 v[34:37], v[162:165], v[242:245], v[34:37]
	s_setprio 0
	s_barrier
	s_add_i32 s42, s47, s23
	v_lshl_add_u64 v[178:179], v[178:179], 0, s[16:17]
	s_mov_b32 m0, s42
	ds_read_b128 v[166:169], v240 offset:49152
	ds_read_b128 v[170:173], v240 offset:50176
	ds_read_b128 v[174:177], v240 offset:51200
	ds_read_b128 v[206:209], v240 offset:52224
	ds_read_b128 v[210:213], v240 offset:53248
	ds_read_b128 v[214:217], v240 offset:54272
	ds_read_b128 v[218:221], v240 offset:55296
	ds_read_b128 v[242:245], v240 offset:56320
	global_load_lds_dwordx4 v[178:179], off
	s_add_i32 m0, s42, 0x2000
	s_add_u32 s26, s26, 0x80080
	v_lshl_add_u64 v[178:179], v[222:223], 0, s[16:17]
	s_addc_u32 s27, s27, 0
	s_add_i32 s42, s48, s23
	global_load_lds_dwordx4 v[178:179], off
	v_lshl_add_u64 v[178:179], s[26:27], 0, v[180:181]
	s_mov_b32 m0, s42
	s_nop 0
	global_load_lds_dwordx4 v[178:179], off
	v_lshl_add_u64 v[178:179], s[26:27], 0, v[196:197]
	s_add_i32 m0, s42, 0x2000
	s_nop 0
	global_load_lds_dwordx4 v[178:179], off
	v_lshl_add_u64 v[178:179], v[246:247], 0, s[16:17]
	s_mov_b32 m0, s54
	s_nop 0
	global_load_lds_dwordx4 v[178:179], off
	v_lshl_add_u64 v[178:179], v[248:249], 0, s[16:17]
	s_mov_b32 m0, s55
	s_nop 0
	global_load_lds_dwordx4 v[178:179], off
	s_waitcnt vmcnt(8)
	s_waitcnt lgkmcnt(0)
	s_barrier
	s_setprio 1
	s_waitcnt lgkmcnt(0)
	v_mfma_f32_16x16x32_bf16 v[94:97], v[114:117], v[166:169], v[94:97]
	v_mfma_f32_16x16x32_bf16 v[30:33], v[122:125], v[166:169], v[30:33]
	v_mfma_f32_16x16x32_bf16 v[86:89], v[114:117], v[174:177], v[86:89]
	v_mfma_f32_16x16x32_bf16 v[22:25], v[122:125], v[174:177], v[22:25]
	v_mfma_f32_16x16x32_bf16 v[78:81], v[114:117], v[210:213], v[78:81]
	v_mfma_f32_16x16x32_bf16 v[14:17], v[122:125], v[210:213], v[14:17]
	v_mfma_f32_16x16x32_bf16 v[70:73], v[114:117], v[218:221], v[70:73]
	v_mfma_f32_16x16x32_bf16 v[6:9], v[122:125], v[218:221], v[6:9]
	v_mfma_f32_16x16x32_bf16 v[94:97], v[118:121], v[170:173], v[94:97]
	v_mfma_f32_16x16x32_bf16 v[30:33], v[146:149], v[170:173], v[30:33]
	v_mfma_f32_16x16x32_bf16 v[86:89], v[118:121], v[206:209], v[86:89]
	v_mfma_f32_16x16x32_bf16 v[22:25], v[146:149], v[206:209], v[22:25]
	v_mfma_f32_16x16x32_bf16 v[78:81], v[118:121], v[214:217], v[78:81]
	v_mfma_f32_16x16x32_bf16 v[14:17], v[146:149], v[214:217], v[14:17]
	v_mfma_f32_16x16x32_bf16 v[70:73], v[118:121], v[242:245], v[70:73]
	v_mfma_f32_16x16x32_bf16 v[6:9], v[146:149], v[242:245], v[6:9]
	v_mfma_f32_16x16x32_bf16 v[90:93], v[150:153], v[166:169], v[90:93]
	v_mfma_f32_16x16x32_bf16 v[26:29], v[158:161], v[166:169], v[26:29]
	v_mfma_f32_16x16x32_bf16 v[82:85], v[150:153], v[174:177], v[82:85]
	v_mfma_f32_16x16x32_bf16 v[18:21], v[158:161], v[174:177], v[18:21]
	v_mfma_f32_16x16x32_bf16 v[74:77], v[150:153], v[210:213], v[74:77]
	v_mfma_f32_16x16x32_bf16 v[10:13], v[158:161], v[210:213], v[10:13]
	v_mfma_f32_16x16x32_bf16 v[66:69], v[150:153], v[218:221], v[66:69]
	v_mfma_f32_16x16x32_bf16 v[2:5], v[158:161], v[218:221], v[2:5]
	v_mfma_f32_16x16x32_bf16 v[90:93], v[154:157], v[170:173], v[90:93]
	v_mfma_f32_16x16x32_bf16 v[26:29], v[162:165], v[170:173], v[26:29]
	v_mfma_f32_16x16x32_bf16 v[82:85], v[154:157], v[206:209], v[82:85]
	v_mfma_f32_16x16x32_bf16 v[18:21], v[162:165], v[206:209], v[18:21]
	v_mfma_f32_16x16x32_bf16 v[74:77], v[154:157], v[214:217], v[74:77]
	v_mfma_f32_16x16x32_bf16 v[10:13], v[162:165], v[214:217], v[10:13]
	v_mfma_f32_16x16x32_bf16 v[66:69], v[154:157], v[242:245], v[66:69]
	v_mfma_f32_16x16x32_bf16 v[2:5], v[162:165], v[242:245], v[2:5]
	s_setprio 0
	s_barrier
	s_add_i32 s46, s46, 2
	s_add_u32 s40, s40, 0x100
	s_addc_u32 s41, s41, 0
	s_add_u32 s37, s37, 0x100
	s_addc_u32 s39, s39, 0
	s_cmp_gt_u32 s46, 29
	s_cbranch_scc1 .LBB0_1688

.LBB0_1761:
	s_add_u32 s26, s38, 0xfff80080
	s_addc_u32 s27, s39, -1
	s_add_i32 s64, 0, 0x10000
	s_cmp_eq_u32 s63, 28
	s_cselect_b32 s41, s57, s27
	s_cselect_b32 s40, s58, s26
	v_add_u32_e32 v155, s64, v153
	s_cselect_b32 s27, s59, s62
	s_cselect_b32 s26, s60, s61
	s_add_i32 s68, 0, 0x14000
	ds_read_b128 v[138:141], v155
	ds_read_b128 v[142:145], v155 offset:1024
	ds_read_b128 v[146:149], v155 offset:2048
	ds_read_b128 v[156:159], v155 offset:3072
	v_add_u32_e32 v155, s68, v153
	ds_read_b128 v[160:163], v155
	ds_read_b128 v[164:167], v155 offset:1024
	ds_read_b128 v[168:171], v155 offset:2048
	ds_read_b128 v[172:175], v155 offset:3072
	v_lshl_add_u64 v[220:221], s[38:39], 0, v[134:135]
	s_add_i32 m0, s3, 0xc000
	ds_read_b128 v[176:179], v154
	ds_read_b128 v[192:195], v154 offset:1024
	ds_read_b128 v[196:199], v154 offset:2048
	ds_read_b128 v[200:203], v154 offset:3072
	ds_read_b128 v[204:207], v154 offset:4096
	ds_read_b128 v[208:211], v154 offset:5120
	ds_read_b128 v[212:215], v154 offset:6144
	ds_read_b128 v[216:219], v154 offset:7168
	global_load_lds_dwordx4 v[220:221], off
	v_lshl_add_u64 v[220:221], s[38:39], 0, v[136:137]
	s_add_i32 m0, s3, 0xe000
	s_nop 0
	global_load_lds_dwordx4 v[220:221], off
	s_waitcnt vmcnt(8)
	s_waitcnt lgkmcnt(0)
	s_barrier
	s_setprio 1
	s_waitcnt lgkmcnt(0)
	v_mfma_f32_16x16x32_bf16 v[126:129], v[138:141], v[176:179], v[126:129]
	v_mfma_f32_16x16x32_bf16 v[122:125], v[146:149], v[176:179], v[122:125]
	v_mfma_f32_16x16x32_bf16 v[110:113], v[138:141], v[196:199], v[110:113]
	v_mfma_f32_16x16x32_bf16 v[106:109], v[146:149], v[196:199], v[106:109]
	v_mfma_f32_16x16x32_bf16 v[94:97], v[138:141], v[204:207], v[94:97]
	v_mfma_f32_16x16x32_bf16 v[90:93], v[146:149], v[204:207], v[90:93]
	v_mfma_f32_16x16x32_bf16 v[78:81], v[138:141], v[212:215], v[78:81]
	v_mfma_f32_16x16x32_bf16 v[74:77], v[146:149], v[212:215], v[74:77]
	v_mfma_f32_16x16x32_bf16 v[126:129], v[142:145], v[192:195], v[126:129]
	v_mfma_f32_16x16x32_bf16 v[122:125], v[156:159], v[192:195], v[122:125]
	v_mfma_f32_16x16x32_bf16 v[110:113], v[142:145], v[200:203], v[110:113]
	v_mfma_f32_16x16x32_bf16 v[106:109], v[156:159], v[200:203], v[106:109]
	v_mfma_f32_16x16x32_bf16 v[94:97], v[142:145], v[208:211], v[94:97]
	v_mfma_f32_16x16x32_bf16 v[90:93], v[156:159], v[208:211], v[90:93]
	v_mfma_f32_16x16x32_bf16 v[78:81], v[142:145], v[216:219], v[78:81]
	v_mfma_f32_16x16x32_bf16 v[74:77], v[156:159], v[216:219], v[74:77]
	v_mfma_f32_16x16x32_bf16 v[118:121], v[160:163], v[176:179], v[118:121]
	v_mfma_f32_16x16x32_bf16 v[114:117], v[168:171], v[176:179], v[114:117]
	v_mfma_f32_16x16x32_bf16 v[102:105], v[160:163], v[196:199], v[102:105]
	v_mfma_f32_16x16x32_bf16 v[98:101], v[168:171], v[196:199], v[98:101]
	v_mfma_f32_16x16x32_bf16 v[86:89], v[160:163], v[204:207], v[86:89]
	v_mfma_f32_16x16x32_bf16 v[82:85], v[168:171], v[204:207], v[82:85]
	v_mfma_f32_16x16x32_bf16 v[70:73], v[160:163], v[212:215], v[70:73]
	v_mfma_f32_16x16x32_bf16 v[66:69], v[168:171], v[212:215], v[66:69]
	v_mfma_f32_16x16x32_bf16 v[118:121], v[164:167], v[192:195], v[118:121]
	v_mfma_f32_16x16x32_bf16 v[114:117], v[172:175], v[192:195], v[114:117]
	v_mfma_f32_16x16x32_bf16 v[102:105], v[164:167], v[200:203], v[102:105]
	v_mfma_f32_16x16x32_bf16 v[98:101], v[172:175], v[200:203], v[98:101]
	v_mfma_f32_16x16x32_bf16 v[86:89], v[164:167], v[208:211], v[86:89]
	v_mfma_f32_16x16x32_bf16 v[82:85], v[172:175], v[208:211], v[82:85]
	v_mfma_f32_16x16x32_bf16 v[70:73], v[164:167], v[216:219], v[70:73]
	v_mfma_f32_16x16x32_bf16 v[66:69], v[172:175], v[216:219], v[66:69]
	s_setprio 0
	s_barrier
	s_add_i32 s64, s64, s43
	v_lshl_add_u64 v[220:221], s[26:27], 0, v[132:133]
	s_mov_b32 m0, s64
	ds_read_b128 v[176:179], v154 offset:16384
	ds_read_b128 v[192:195], v154 offset:17408
	ds_read_b128 v[196:199], v154 offset:18432
	ds_read_b128 v[200:203], v154 offset:19456
	ds_read_b128 v[204:207], v154 offset:20480
	ds_read_b128 v[208:211], v154 offset:21504
	ds_read_b128 v[212:215], v154 offset:22528
	ds_read_b128 v[216:219], v154 offset:23552
	global_load_lds_dwordx4 v[220:221], off
	s_add_i32 m0, s64, 0x2000
	s_add_u32 s66, s26, 0x80000
	v_lshl_add_u64 v[222:223], s[26:27], 0, v[130:131]
	s_addc_u32 s67, s27, 0
	s_add_i32 s64, s68, s43
	global_load_lds_dwordx4 v[222:223], off
	v_lshl_add_u64 v[238:239], s[66:67], 0, v[132:133]
	s_mov_b32 m0, s64
	v_lshl_add_u64 v[240:241], s[40:41], 0, v[130:131]
	global_load_lds_dwordx4 v[238:239], off
	v_lshl_add_u64 v[238:239], s[66:67], 0, v[130:131]
	s_add_i32 m0, s64, 0x2000
	s_nop 0
	global_load_lds_dwordx4 v[238:239], off
	v_lshl_add_u64 v[238:239], s[40:41], 0, v[132:133]
	s_mov_b32 m0, s3
	s_nop 0
	global_load_lds_dwordx4 v[238:239], off
	s_mov_b32 m0, s45
	s_nop 0
	global_load_lds_dwordx4 v[240:241], off
	s_waitcnt vmcnt(8)
	s_waitcnt lgkmcnt(0)
	s_barrier
	s_setprio 1
	s_waitcnt lgkmcnt(0)
	v_mfma_f32_16x16x32_bf16 v[62:65], v[138:141], v[176:179], v[62:65]
	v_mfma_f32_16x16x32_bf16 v[58:61], v[146:149], v[176:179], v[58:61]
	v_mfma_f32_16x16x32_bf16 v[46:49], v[138:141], v[196:199], v[46:49]
	v_mfma_f32_16x16x32_bf16 v[42:45], v[146:149], v[196:199], v[42:45]
	v_mfma_f32_16x16x32_bf16 v[30:33], v[138:141], v[204:207], v[30:33]
	v_mfma_f32_16x16x32_bf16 v[26:29], v[146:149], v[204:207], v[26:29]
	v_mfma_f32_16x16x32_bf16 v[14:17], v[138:141], v[212:215], v[14:17]
	v_mfma_f32_16x16x32_bf16 v[10:13], v[146:149], v[212:215], v[10:13]
	v_mfma_f32_16x16x32_bf16 v[62:65], v[142:145], v[192:195], v[62:65]
	v_mfma_f32_16x16x32_bf16 v[58:61], v[156:159], v[192:195], v[58:61]
	v_mfma_f32_16x16x32_bf16 v[46:49], v[142:145], v[200:203], v[46:49]
	v_mfma_f32_16x16x32_bf16 v[42:45], v[156:159], v[200:203], v[42:45]
	v_mfma_f32_16x16x32_bf16 v[30:33], v[142:145], v[208:211], v[30:33]
	v_mfma_f32_16x16x32_bf16 v[26:29], v[156:159], v[208:211], v[26:29]
	v_mfma_f32_16x16x32_bf16 v[14:17], v[142:145], v[216:219], v[14:17]
	v_mfma_f32_16x16x32_bf16 v[10:13], v[156:159], v[216:219], v[10:13]
	v_mfma_f32_16x16x32_bf16 v[54:57], v[160:163], v[176:179], v[54:57]
	v_mfma_f32_16x16x32_bf16 v[50:53], v[168:171], v[176:179], v[50:53]
	v_mfma_f32_16x16x32_bf16 v[38:41], v[160:163], v[196:199], v[38:41]
	v_mfma_f32_16x16x32_bf16 v[34:37], v[168:171], v[196:199], v[34:37]
	v_mfma_f32_16x16x32_bf16 v[22:25], v[160:163], v[204:207], v[22:25]
	v_mfma_f32_16x16x32_bf16 v[18:21], v[168:171], v[204:207], v[18:21]
	v_mfma_f32_16x16x32_bf16 v[6:9], v[160:163], v[212:215], v[6:9]
	v_mfma_f32_16x16x32_bf16 v[2:5], v[168:171], v[212:215], v[2:5]
	v_mfma_f32_16x16x32_bf16 v[54:57], v[164:167], v[192:195], v[54:57]
	v_mfma_f32_16x16x32_bf16 v[50:53], v[172:175], v[192:195], v[50:53]
	v_mfma_f32_16x16x32_bf16 v[38:41], v[164:167], v[200:203], v[38:41]
	v_mfma_f32_16x16x32_bf16 v[34:37], v[172:175], v[200:203], v[34:37]
	v_mfma_f32_16x16x32_bf16 v[22:25], v[164:167], v[208:211], v[22:25]
	v_mfma_f32_16x16x32_bf16 v[18:21], v[172:175], v[208:211], v[18:21]
	v_mfma_f32_16x16x32_bf16 v[6:9], v[164:167], v[216:219], v[6:9]
	v_mfma_f32_16x16x32_bf16 v[2:5], v[172:175], v[216:219], v[2:5]
	s_setprio 0
	s_barrier
	s_add_i32 s64, 0, 0x18000
	v_add_u32_e32 v155, s64, v153
	s_add_i32 s66, 0, 0x1c000
	ds_read_b128 v[138:141], v155
	ds_read_b128 v[142:145], v155 offset:1024
	ds_read_b128 v[146:149], v155 offset:2048
	ds_read_b128 v[156:159], v155 offset:3072
	v_add_u32_e32 v155, s66, v153
	ds_read_b128 v[160:163], v155
	ds_read_b128 v[164:167], v155 offset:1024
	ds_read_b128 v[168:171], v155 offset:2048
	ds_read_b128 v[172:175], v155 offset:3072
	s_add_u32 s40, s40, 0x80000
	s_addc_u32 s41, s41, 0
	s_mov_b32 m0, s46
	v_lshl_add_u64 v[242:243], s[40:41], 0, v[132:133]
	ds_read_b128 v[176:179], v154 offset:32768
	ds_read_b128 v[192:195], v154 offset:33792
	ds_read_b128 v[196:199], v154 offset:34816
	ds_read_b128 v[200:203], v154 offset:35840
	ds_read_b128 v[204:207], v154 offset:36864
	ds_read_b128 v[208:211], v154 offset:37888
	ds_read_b128 v[212:215], v154 offset:38912
	ds_read_b128 v[216:219], v154 offset:39936
	global_load_lds_dwordx4 v[242:243], off
	v_lshl_add_u64 v[242:243], s[40:41], 0, v[130:131]
	s_mov_b32 m0, s47
	s_nop 0
	global_load_lds_dwordx4 v[242:243], off
	s_waitcnt vmcnt(8)
	s_waitcnt lgkmcnt(0)
	s_barrier
	s_setprio 1
	s_waitcnt lgkmcnt(0)
	v_mfma_f32_16x16x32_bf16 v[126:129], v[138:141], v[176:179], v[126:129]
	v_mfma_f32_16x16x32_bf16 v[122:125], v[146:149], v[176:179], v[122:125]
	v_mfma_f32_16x16x32_bf16 v[110:113], v[138:141], v[196:199], v[110:113]
	v_mfma_f32_16x16x32_bf16 v[106:109], v[146:149], v[196:199], v[106:109]
	v_mfma_f32_16x16x32_bf16 v[94:97], v[138:141], v[204:207], v[94:97]
	v_mfma_f32_16x16x32_bf16 v[90:93], v[146:149], v[204:207], v[90:93]
	v_mfma_f32_16x16x32_bf16 v[78:81], v[138:141], v[212:215], v[78:81]
	v_mfma_f32_16x16x32_bf16 v[74:77], v[146:149], v[212:215], v[74:77]
	v_mfma_f32_16x16x32_bf16 v[126:129], v[142:145], v[192:195], v[126:129]
	v_mfma_f32_16x16x32_bf16 v[122:125], v[156:159], v[192:195], v[122:125]
	v_mfma_f32_16x16x32_bf16 v[110:113], v[142:145], v[200:203], v[110:113]
	v_mfma_f32_16x16x32_bf16 v[106:109], v[156:159], v[200:203], v[106:109]
	v_mfma_f32_16x16x32_bf16 v[94:97], v[142:145], v[208:211], v[94:97]
	v_mfma_f32_16x16x32_bf16 v[90:93], v[156:159], v[208:211], v[90:93]
	v_mfma_f32_16x16x32_bf16 v[78:81], v[142:145], v[216:219], v[78:81]
	v_mfma_f32_16x16x32_bf16 v[74:77], v[156:159], v[216:219], v[74:77]
	v_mfma_f32_16x16x32_bf16 v[118:121], v[160:163], v[176:179], v[118:121]
	v_mfma_f32_16x16x32_bf16 v[114:117], v[168:171], v[176:179], v[114:117]
	v_mfma_f32_16x16x32_bf16 v[102:105], v[160:163], v[196:199], v[102:105]
	v_mfma_f32_16x16x32_bf16 v[98:101], v[168:171], v[196:199], v[98:101]
	v_mfma_f32_16x16x32_bf16 v[86:89], v[160:163], v[204:207], v[86:89]
	v_mfma_f32_16x16x32_bf16 v[82:85], v[168:171], v[204:207], v[82:85]
	v_mfma_f32_16x16x32_bf16 v[70:73], v[160:163], v[212:215], v[70:73]
	v_mfma_f32_16x16x32_bf16 v[66:69], v[168:171], v[212:215], v[66:69]
	v_mfma_f32_16x16x32_bf16 v[118:121], v[164:167], v[192:195], v[118:121]
	v_mfma_f32_16x16x32_bf16 v[114:117], v[172:175], v[192:195], v[114:117]
	v_mfma_f32_16x16x32_bf16 v[102:105], v[164:167], v[200:203], v[102:105]
	v_mfma_f32_16x16x32_bf16 v[98:101], v[172:175], v[200:203], v[98:101]
	v_mfma_f32_16x16x32_bf16 v[86:89], v[164:167], v[208:211], v[86:89]
	v_mfma_f32_16x16x32_bf16 v[82:85], v[172:175], v[208:211], v[82:85]
	v_mfma_f32_16x16x32_bf16 v[70:73], v[164:167], v[216:219], v[70:73]
	v_mfma_f32_16x16x32_bf16 v[66:69], v[172:175], v[216:219], v[66:69]
	s_setprio 0
	s_barrier
	s_add_i32 s40, s64, s43
	v_lshl_add_u64 v[220:221], v[220:221], 0, s[16:17]
	s_mov_b32 m0, s40
	ds_read_b128 v[176:179], v154 offset:49152
	ds_read_b128 v[192:195], v154 offset:50176
	ds_read_b128 v[196:199], v154 offset:51200
	ds_read_b128 v[200:203], v154 offset:52224
	ds_read_b128 v[204:207], v154 offset:53248
	ds_read_b128 v[208:211], v154 offset:54272
	ds_read_b128 v[212:215], v154 offset:55296
	ds_read_b128 v[216:219], v154 offset:56320
	global_load_lds_dwordx4 v[220:221], off
	s_add_i32 m0, s40, 0x2000
	s_add_u32 s26, s26, 0x80080
	v_lshl_add_u64 v[220:221], v[222:223], 0, s[16:17]
	s_addc_u32 s27, s27, 0
	s_add_i32 s40, s66, s43
	global_load_lds_dwordx4 v[220:221], off
	v_lshl_add_u64 v[220:221], s[26:27], 0, v[132:133]
	s_mov_b32 m0, s40
	s_nop 0
	global_load_lds_dwordx4 v[220:221], off
	v_lshl_add_u64 v[220:221], s[26:27], 0, v[130:131]
	s_add_i32 m0, s40, 0x2000
	s_nop 0
	global_load_lds_dwordx4 v[220:221], off
	v_lshl_add_u64 v[220:221], v[238:239], 0, s[16:17]
	s_mov_b32 m0, s50
	s_nop 0
	global_load_lds_dwordx4 v[220:221], off
	v_lshl_add_u64 v[220:221], v[240:241], 0, s[16:17]
	s_mov_b32 m0, s51
	s_nop 0
	global_load_lds_dwordx4 v[220:221], off
	s_waitcnt vmcnt(8)
	s_waitcnt lgkmcnt(0)
	s_barrier
	s_setprio 1
	s_waitcnt lgkmcnt(0)
	v_mfma_f32_16x16x32_bf16 v[62:65], v[138:141], v[176:179], v[62:65]
	v_mfma_f32_16x16x32_bf16 v[58:61], v[146:149], v[176:179], v[58:61]
	v_mfma_f32_16x16x32_bf16 v[46:49], v[138:141], v[196:199], v[46:49]
	v_mfma_f32_16x16x32_bf16 v[42:45], v[146:149], v[196:199], v[42:45]
	v_mfma_f32_16x16x32_bf16 v[30:33], v[138:141], v[204:207], v[30:33]
	v_mfma_f32_16x16x32_bf16 v[26:29], v[146:149], v[204:207], v[26:29]
	v_mfma_f32_16x16x32_bf16 v[14:17], v[138:141], v[212:215], v[14:17]
	v_mfma_f32_16x16x32_bf16 v[10:13], v[146:149], v[212:215], v[10:13]
	v_mfma_f32_16x16x32_bf16 v[62:65], v[142:145], v[192:195], v[62:65]
	v_mfma_f32_16x16x32_bf16 v[58:61], v[156:159], v[192:195], v[58:61]
	v_mfma_f32_16x16x32_bf16 v[46:49], v[142:145], v[200:203], v[46:49]
	v_mfma_f32_16x16x32_bf16 v[42:45], v[156:159], v[200:203], v[42:45]
	v_mfma_f32_16x16x32_bf16 v[30:33], v[142:145], v[208:211], v[30:33]
	v_mfma_f32_16x16x32_bf16 v[26:29], v[156:159], v[208:211], v[26:29]
	v_mfma_f32_16x16x32_bf16 v[14:17], v[142:145], v[216:219], v[14:17]
	v_mfma_f32_16x16x32_bf16 v[10:13], v[156:159], v[216:219], v[10:13]
	v_mfma_f32_16x16x32_bf16 v[54:57], v[160:163], v[176:179], v[54:57]
	v_mfma_f32_16x16x32_bf16 v[50:53], v[168:171], v[176:179], v[50:53]
	v_mfma_f32_16x16x32_bf16 v[38:41], v[160:163], v[196:199], v[38:41]
	v_mfma_f32_16x16x32_bf16 v[34:37], v[168:171], v[196:199], v[34:37]
	v_mfma_f32_16x16x32_bf16 v[22:25], v[160:163], v[204:207], v[22:25]
	v_mfma_f32_16x16x32_bf16 v[18:21], v[168:171], v[204:207], v[18:21]
	v_mfma_f32_16x16x32_bf16 v[6:9], v[160:163], v[212:215], v[6:9]
	v_mfma_f32_16x16x32_bf16 v[2:5], v[168:171], v[212:215], v[2:5]
	v_mfma_f32_16x16x32_bf16 v[54:57], v[164:167], v[192:195], v[54:57]
	v_mfma_f32_16x16x32_bf16 v[50:53], v[172:175], v[192:195], v[50:53]
	v_mfma_f32_16x16x32_bf16 v[38:41], v[164:167], v[200:203], v[38:41]
	v_mfma_f32_16x16x32_bf16 v[34:37], v[172:175], v[200:203], v[34:37]
	v_mfma_f32_16x16x32_bf16 v[22:25], v[164:167], v[208:211], v[22:25]
	v_mfma_f32_16x16x32_bf16 v[18:21], v[172:175], v[208:211], v[18:21]
	v_mfma_f32_16x16x32_bf16 v[6:9], v[164:167], v[216:219], v[6:9]
	v_mfma_f32_16x16x32_bf16 v[2:5], v[172:175], v[216:219], v[2:5]
	s_setprio 0
	s_barrier
	s_add_i32 s63, s63, 2
	s_add_u32 s38, s38, 0x100
	s_addc_u32 s39, s39, 0
	s_add_u32 s61, s61, 0x100
	s_addc_u32 s62, s62, 0
	s_cmp_gt_u32 s63, 29
	s_cbranch_scc0 .LBB0_1761
	s_and_b64 vcc, exec, s[34:35]
	s_cbranch_vccz .LBB0_1764
	s_barrier

.LBB0_2241:
	s_add_u32 s28, s26, 0x100
	s_addc_u32 s29, s27, 0
	s_add_i32 s58, 0, 0x10000
	s_cmpk_eq_i32 s57, 0x52
	s_cselect_b32 s35, s23, s29
	s_cselect_b32 s34, s22, s28
	s_cselect_b32 s31, s25, s39
	s_cselect_b32 s30, s24, s38
	s_add_i32 s59, 0, 0x14000
	v_add_u32_e32 v166, s58, v156
	v_add_u32_e32 v178, s59, v156
	ds_read_b128 v[148:151], v166
	ds_read_b128 v[158:161], v166 offset:1024
	ds_read_b128 v[162:165], v166 offset:2048
	ds_read_b128 v[166:169], v166 offset:3072
	ds_read_b128 v[170:173], v178
	ds_read_b128 v[174:177], v178 offset:1024
	ds_read_b128 v[190:193], v178 offset:2048
	ds_read_b128 v[194:197], v178 offset:3072
	v_lshl_add_u64 v[178:179], s[26:27], 0, v[144:145]
	s_add_i32 m0, s43, 0xc000
	ds_read_b128 v[198:201], v157
	ds_read_b128 v[202:205], v157 offset:1024
	ds_read_b128 v[206:209], v157 offset:2048
	ds_read_b128 v[210:213], v157 offset:3072
	ds_read_b128 v[214:217], v157 offset:4096
	ds_read_b128 v[218:221], v157 offset:5120
	ds_read_b128 v[238:241], v157 offset:6144
	ds_read_b128 v[242:245], v157 offset:7168
	global_load_lds_dwordx4 v[178:179], off
	v_lshl_add_u64 v[178:179], s[26:27], 0, v[146:147]
	s_add_i32 m0, s43, 0xe000
	s_nop 0
	global_load_lds_dwordx4 v[178:179], off
	s_waitcnt vmcnt(8)
	s_waitcnt lgkmcnt(0)
	s_barrier
	s_setprio 1
	s_waitcnt lgkmcnt(0)
	v_mfma_f32_16x16x32_bf16 v[126:129], v[148:151], v[198:201], v[126:129]
	v_mfma_f32_16x16x32_bf16 v[114:117], v[162:165], v[198:201], v[114:117]
	v_mfma_f32_16x16x32_bf16 v[106:109], v[148:151], v[206:209], v[106:109]
	v_mfma_f32_16x16x32_bf16 v[98:101], v[162:165], v[206:209], v[98:101]
	v_mfma_f32_16x16x32_bf16 v[90:93], v[148:151], v[214:217], v[90:93]
	v_mfma_f32_16x16x32_bf16 v[82:85], v[162:165], v[214:217], v[82:85]
	v_mfma_f32_16x16x32_bf16 v[74:77], v[148:151], v[238:241], v[74:77]
	v_mfma_f32_16x16x32_bf16 v[54:57], v[162:165], v[238:241], v[54:57]
	v_mfma_f32_16x16x32_bf16 v[126:129], v[158:161], v[202:205], v[126:129]
	v_mfma_f32_16x16x32_bf16 v[114:117], v[166:169], v[202:205], v[114:117]
	v_mfma_f32_16x16x32_bf16 v[106:109], v[158:161], v[210:213], v[106:109]
	v_mfma_f32_16x16x32_bf16 v[98:101], v[166:169], v[210:213], v[98:101]
	v_mfma_f32_16x16x32_bf16 v[90:93], v[158:161], v[218:221], v[90:93]
	v_mfma_f32_16x16x32_bf16 v[82:85], v[166:169], v[218:221], v[82:85]
	v_mfma_f32_16x16x32_bf16 v[74:77], v[158:161], v[242:245], v[74:77]
	v_mfma_f32_16x16x32_bf16 v[54:57], v[166:169], v[242:245], v[54:57]
	v_mfma_f32_16x16x32_bf16 v[118:121], v[170:173], v[198:201], v[118:121]
	v_mfma_f32_16x16x32_bf16 v[122:125], v[190:193], v[198:201], v[122:125]
	v_mfma_f32_16x16x32_bf16 v[102:105], v[170:173], v[206:209], v[102:105]
	v_mfma_f32_16x16x32_bf16 v[110:113], v[190:193], v[206:209], v[110:113]
	v_mfma_f32_16x16x32_bf16 v[86:89], v[170:173], v[214:217], v[86:89]
	v_mfma_f32_16x16x32_bf16 v[94:97], v[190:193], v[214:217], v[94:97]
	v_mfma_f32_16x16x32_bf16 v[70:73], v[170:173], v[238:241], v[70:73]
	v_mfma_f32_16x16x32_bf16 v[78:81], v[190:193], v[238:241], v[78:81]
	v_mfma_f32_16x16x32_bf16 v[118:121], v[174:177], v[202:205], v[118:121]
	v_mfma_f32_16x16x32_bf16 v[122:125], v[194:197], v[202:205], v[122:125]
	v_mfma_f32_16x16x32_bf16 v[102:105], v[174:177], v[210:213], v[102:105]
	v_mfma_f32_16x16x32_bf16 v[110:113], v[194:197], v[210:213], v[110:113]
	v_mfma_f32_16x16x32_bf16 v[86:89], v[174:177], v[218:221], v[86:89]
	v_mfma_f32_16x16x32_bf16 v[94:97], v[194:197], v[218:221], v[94:97]
	v_mfma_f32_16x16x32_bf16 v[70:73], v[174:177], v[242:245], v[70:73]
	v_mfma_f32_16x16x32_bf16 v[78:81], v[194:197], v[242:245], v[78:81]
	s_setprio 0
	s_barrier
	s_add_i32 s26, s58, s40
	v_lshl_add_u64 v[178:179], s[30:31], 0, v[136:137]
	s_mov_b32 m0, s26
	ds_read_b128 v[198:201], v157 offset:16384
	ds_read_b128 v[202:205], v157 offset:17408
	ds_read_b128 v[206:209], v157 offset:18432
	ds_read_b128 v[210:213], v157 offset:19456
	ds_read_b128 v[214:217], v157 offset:20480
	ds_read_b128 v[218:221], v157 offset:21504
	ds_read_b128 v[238:241], v157 offset:22528
	ds_read_b128 v[242:245], v157 offset:23552
	global_load_lds_dwordx4 v[178:179], off
	s_add_i32 m0, s26, 0x2000
	s_add_u32 s26, s30, 0x158000
	v_lshl_add_u64 v[222:223], s[30:31], 0, v[140:141]
	s_addc_u32 s27, s31, 0
	s_add_i32 s58, s59, s40
	global_load_lds_dwordx4 v[222:223], off
	v_lshl_add_u64 v[246:247], s[26:27], 0, v[136:137]
	s_mov_b32 m0, s58
	v_lshl_add_u64 v[248:249], s[34:35], 0, v[138:139]
	global_load_lds_dwordx4 v[246:247], off
	v_lshl_add_u64 v[246:247], s[26:27], 0, v[140:141]
	s_add_i32 m0, s58, 0x2000
	s_nop 0
	global_load_lds_dwordx4 v[246:247], off
	v_lshl_add_u64 v[246:247], s[34:35], 0, v[134:135]
	s_mov_b32 m0, s43
	s_nop 0
	global_load_lds_dwordx4 v[246:247], off
	s_mov_b32 m0, s44
	s_nop 0
	global_load_lds_dwordx4 v[248:249], off
	s_waitcnt vmcnt(8)
	s_waitcnt lgkmcnt(0)
	s_barrier
	s_setprio 1
	s_waitcnt lgkmcnt(0)
	v_mfma_f32_16x16x32_bf16 v[50:53], v[148:151], v[198:201], v[50:53]
	v_mfma_f32_16x16x32_bf16 v[38:41], v[162:165], v[198:201], v[38:41]
	v_mfma_f32_16x16x32_bf16 v[22:25], v[148:151], v[206:209], v[22:25]
	v_mfma_f32_16x16x32_bf16 v[42:45], v[162:165], v[206:209], v[42:45]
	v_mfma_f32_16x16x32_bf16 v[30:33], v[148:151], v[214:217], v[30:33]
	v_mfma_f32_16x16x32_bf16 v[18:21], v[162:165], v[214:217], v[18:21]
	v_mfma_f32_16x16x32_bf16 v[10:13], v[148:151], v[238:241], v[10:13]
	v_mfma_f32_16x16x32_bf16 v[2:5], v[162:165], v[238:241], v[2:5]
	v_mfma_f32_16x16x32_bf16 v[50:53], v[158:161], v[202:205], v[50:53]
	v_mfma_f32_16x16x32_bf16 v[38:41], v[166:169], v[202:205], v[38:41]
	v_mfma_f32_16x16x32_bf16 v[22:25], v[158:161], v[210:213], v[22:25]
	v_mfma_f32_16x16x32_bf16 v[42:45], v[166:169], v[210:213], v[42:45]
	v_mfma_f32_16x16x32_bf16 v[30:33], v[158:161], v[218:221], v[30:33]
	v_mfma_f32_16x16x32_bf16 v[18:21], v[166:169], v[218:221], v[18:21]
	v_mfma_f32_16x16x32_bf16 v[10:13], v[158:161], v[242:245], v[10:13]
	v_mfma_f32_16x16x32_bf16 v[2:5], v[166:169], v[242:245], v[2:5]
	v_mfma_f32_16x16x32_bf16 v[46:49], v[170:173], v[198:201], v[46:49]
	v_mfma_f32_16x16x32_bf16 v[58:61], v[190:193], v[198:201], v[58:61]
	v_mfma_f32_16x16x32_bf16 v[62:65], v[170:173], v[206:209], v[62:65]
	v_mfma_f32_16x16x32_bf16 v[66:69], v[190:193], v[206:209], v[66:69]
	v_mfma_f32_16x16x32_bf16 v[26:29], v[170:173], v[214:217], v[26:29]
	v_mfma_f32_16x16x32_bf16 v[34:37], v[190:193], v[214:217], v[34:37]
	v_mfma_f32_16x16x32_bf16 v[6:9], v[170:173], v[238:241], v[6:9]
	v_mfma_f32_16x16x32_bf16 v[14:17], v[190:193], v[238:241], v[14:17]
	v_mfma_f32_16x16x32_bf16 v[46:49], v[174:177], v[202:205], v[46:49]
	v_mfma_f32_16x16x32_bf16 v[58:61], v[194:197], v[202:205], v[58:61]
	v_mfma_f32_16x16x32_bf16 v[62:65], v[174:177], v[210:213], v[62:65]
	v_mfma_f32_16x16x32_bf16 v[66:69], v[194:197], v[210:213], v[66:69]
	v_mfma_f32_16x16x32_bf16 v[26:29], v[174:177], v[218:221], v[26:29]
	v_mfma_f32_16x16x32_bf16 v[34:37], v[194:197], v[218:221], v[34:37]
	v_mfma_f32_16x16x32_bf16 v[6:9], v[174:177], v[242:245], v[6:9]
	v_mfma_f32_16x16x32_bf16 v[14:17], v[194:197], v[242:245], v[14:17]
	s_setprio 0
	s_barrier
	s_add_i32 s58, 0, 0x18000
	s_add_i32 s59, 0, 0x1c000
	v_add_u32_e32 v166, s58, v156
	v_add_u32_e32 v194, s59, v156
	ds_read_b128 v[148:151], v166
	ds_read_b128 v[158:161], v166 offset:1024
	ds_read_b128 v[162:165], v166 offset:2048
	ds_read_b128 v[166:169], v166 offset:3072
	ds_read_b128 v[170:173], v194
	ds_read_b128 v[174:177], v194 offset:1024
	ds_read_b128 v[190:193], v194 offset:2048
	ds_read_b128 v[194:197], v194 offset:3072
	s_add_u32 s26, s34, 0x158000
	s_addc_u32 s27, s35, 0
	s_mov_b32 m0, s45
	v_lshl_add_u64 v[250:251], s[26:27], 0, v[134:135]
	ds_read_b128 v[198:201], v157 offset:32768
	ds_read_b128 v[202:205], v157 offset:33792
	ds_read_b128 v[206:209], v157 offset:34816
	ds_read_b128 v[210:213], v157 offset:35840
	ds_read_b128 v[214:217], v157 offset:36864
	ds_read_b128 v[218:221], v157 offset:37888
	ds_read_b128 v[238:241], v157 offset:38912
	ds_read_b128 v[242:245], v157 offset:39936
	global_load_lds_dwordx4 v[250:251], off
	v_lshl_add_u64 v[250:251], s[26:27], 0, v[138:139]
	s_mov_b32 m0, s47
	s_nop 0
	global_load_lds_dwordx4 v[250:251], off
	s_waitcnt vmcnt(8)
	s_waitcnt lgkmcnt(0)
	s_barrier
	s_setprio 1
	s_waitcnt lgkmcnt(0)
	v_mfma_f32_16x16x32_bf16 v[126:129], v[148:151], v[198:201], v[126:129]
	v_mfma_f32_16x16x32_bf16 v[114:117], v[162:165], v[198:201], v[114:117]
	v_mfma_f32_16x16x32_bf16 v[106:109], v[148:151], v[206:209], v[106:109]
	v_mfma_f32_16x16x32_bf16 v[98:101], v[162:165], v[206:209], v[98:101]
	v_mfma_f32_16x16x32_bf16 v[90:93], v[148:151], v[214:217], v[90:93]
	v_mfma_f32_16x16x32_bf16 v[82:85], v[162:165], v[214:217], v[82:85]
	v_mfma_f32_16x16x32_bf16 v[74:77], v[148:151], v[238:241], v[74:77]
	v_mfma_f32_16x16x32_bf16 v[54:57], v[162:165], v[238:241], v[54:57]
	v_mfma_f32_16x16x32_bf16 v[126:129], v[158:161], v[202:205], v[126:129]
	v_mfma_f32_16x16x32_bf16 v[114:117], v[166:169], v[202:205], v[114:117]
	v_mfma_f32_16x16x32_bf16 v[106:109], v[158:161], v[210:213], v[106:109]
	v_mfma_f32_16x16x32_bf16 v[98:101], v[166:169], v[210:213], v[98:101]
	v_mfma_f32_16x16x32_bf16 v[90:93], v[158:161], v[218:221], v[90:93]
	v_mfma_f32_16x16x32_bf16 v[82:85], v[166:169], v[218:221], v[82:85]
	v_mfma_f32_16x16x32_bf16 v[74:77], v[158:161], v[242:245], v[74:77]
	v_mfma_f32_16x16x32_bf16 v[54:57], v[166:169], v[242:245], v[54:57]
	v_mfma_f32_16x16x32_bf16 v[118:121], v[170:173], v[198:201], v[118:121]
	v_mfma_f32_16x16x32_bf16 v[122:125], v[190:193], v[198:201], v[122:125]
	v_mfma_f32_16x16x32_bf16 v[102:105], v[170:173], v[206:209], v[102:105]
	v_mfma_f32_16x16x32_bf16 v[110:113], v[190:193], v[206:209], v[110:113]
	v_mfma_f32_16x16x32_bf16 v[86:89], v[170:173], v[214:217], v[86:89]
	v_mfma_f32_16x16x32_bf16 v[94:97], v[190:193], v[214:217], v[94:97]
	v_mfma_f32_16x16x32_bf16 v[70:73], v[170:173], v[238:241], v[70:73]
	v_mfma_f32_16x16x32_bf16 v[78:81], v[190:193], v[238:241], v[78:81]
	v_mfma_f32_16x16x32_bf16 v[118:121], v[174:177], v[202:205], v[118:121]
	v_mfma_f32_16x16x32_bf16 v[122:125], v[194:197], v[202:205], v[122:125]
	v_mfma_f32_16x16x32_bf16 v[102:105], v[174:177], v[210:213], v[102:105]
	v_mfma_f32_16x16x32_bf16 v[110:113], v[194:197], v[210:213], v[110:113]
	v_mfma_f32_16x16x32_bf16 v[86:89], v[174:177], v[218:221], v[86:89]
	v_mfma_f32_16x16x32_bf16 v[94:97], v[194:197], v[218:221], v[94:97]
	v_mfma_f32_16x16x32_bf16 v[70:73], v[174:177], v[242:245], v[70:73]
	v_mfma_f32_16x16x32_bf16 v[78:81], v[194:197], v[242:245], v[78:81]
	s_setprio 0
	s_barrier
	s_add_i32 s26, s58, s40
	v_lshl_add_u64 v[178:179], v[178:179], 0, s[16:17]
	s_mov_b32 m0, s26
	ds_read_b128 v[198:201], v157 offset:49152
	ds_read_b128 v[202:205], v157 offset:50176
	ds_read_b128 v[206:209], v157 offset:51200
	ds_read_b128 v[210:213], v157 offset:52224
	ds_read_b128 v[214:217], v157 offset:53248
	ds_read_b128 v[218:221], v157 offset:54272
	ds_read_b128 v[238:241], v157 offset:55296
	ds_read_b128 v[242:245], v157 offset:56320
	global_load_lds_dwordx4 v[178:179], off
	s_add_i32 m0, s26, 0x2000
	s_add_u32 s26, s30, 0x158080
	v_lshl_add_u64 v[178:179], v[222:223], 0, s[16:17]
	s_addc_u32 s27, s31, 0
	s_add_i32 s30, s59, s40
	global_load_lds_dwordx4 v[178:179], off
	v_lshl_add_u64 v[178:179], s[26:27], 0, v[136:137]
	s_mov_b32 m0, s30
	s_nop 0
	global_load_lds_dwordx4 v[178:179], off
	v_lshl_add_u64 v[178:179], s[26:27], 0, v[140:141]
	s_add_i32 m0, s30, 0x2000
	s_nop 0
	global_load_lds_dwordx4 v[178:179], off
	v_lshl_add_u64 v[178:179], v[246:247], 0, s[16:17]
	s_mov_b32 m0, s48
	s_nop 0
	global_load_lds_dwordx4 v[178:179], off
	v_lshl_add_u64 v[178:179], v[248:249], 0, s[16:17]
	s_mov_b32 m0, s49
	s_nop 0
	global_load_lds_dwordx4 v[178:179], off
	s_waitcnt vmcnt(8)
	s_waitcnt lgkmcnt(0)
	s_barrier
	s_setprio 1
	s_waitcnt lgkmcnt(0)
	v_mfma_f32_16x16x32_bf16 v[50:53], v[148:151], v[198:201], v[50:53]
	v_mfma_f32_16x16x32_bf16 v[38:41], v[162:165], v[198:201], v[38:41]
	v_mfma_f32_16x16x32_bf16 v[22:25], v[148:151], v[206:209], v[22:25]
	v_mfma_f32_16x16x32_bf16 v[42:45], v[162:165], v[206:209], v[42:45]
	v_mfma_f32_16x16x32_bf16 v[30:33], v[148:151], v[214:217], v[30:33]
	v_mfma_f32_16x16x32_bf16 v[18:21], v[162:165], v[214:217], v[18:21]
	v_mfma_f32_16x16x32_bf16 v[10:13], v[148:151], v[238:241], v[10:13]
	v_mfma_f32_16x16x32_bf16 v[2:5], v[162:165], v[238:241], v[2:5]
	v_mfma_f32_16x16x32_bf16 v[50:53], v[158:161], v[202:205], v[50:53]
	v_mfma_f32_16x16x32_bf16 v[38:41], v[166:169], v[202:205], v[38:41]
	v_mfma_f32_16x16x32_bf16 v[22:25], v[158:161], v[210:213], v[22:25]
	v_mfma_f32_16x16x32_bf16 v[42:45], v[166:169], v[210:213], v[42:45]
	v_mfma_f32_16x16x32_bf16 v[30:33], v[158:161], v[218:221], v[30:33]
	v_mfma_f32_16x16x32_bf16 v[18:21], v[166:169], v[218:221], v[18:21]
	v_mfma_f32_16x16x32_bf16 v[10:13], v[158:161], v[242:245], v[10:13]
	v_mfma_f32_16x16x32_bf16 v[2:5], v[166:169], v[242:245], v[2:5]
	v_mfma_f32_16x16x32_bf16 v[46:49], v[170:173], v[198:201], v[46:49]
	v_mfma_f32_16x16x32_bf16 v[58:61], v[190:193], v[198:201], v[58:61]
	v_mfma_f32_16x16x32_bf16 v[62:65], v[170:173], v[206:209], v[62:65]
	v_mfma_f32_16x16x32_bf16 v[66:69], v[190:193], v[206:209], v[66:69]
	v_mfma_f32_16x16x32_bf16 v[26:29], v[170:173], v[214:217], v[26:29]
	v_mfma_f32_16x16x32_bf16 v[34:37], v[190:193], v[214:217], v[34:37]
	v_mfma_f32_16x16x32_bf16 v[6:9], v[170:173], v[238:241], v[6:9]
	v_mfma_f32_16x16x32_bf16 v[14:17], v[190:193], v[238:241], v[14:17]
	v_mfma_f32_16x16x32_bf16 v[46:49], v[174:177], v[202:205], v[46:49]
	v_mfma_f32_16x16x32_bf16 v[58:61], v[194:197], v[202:205], v[58:61]
	v_mfma_f32_16x16x32_bf16 v[62:65], v[174:177], v[210:213], v[62:65]
	v_mfma_f32_16x16x32_bf16 v[66:69], v[194:197], v[210:213], v[66:69]
	v_mfma_f32_16x16x32_bf16 v[26:29], v[174:177], v[218:221], v[26:29]
	v_mfma_f32_16x16x32_bf16 v[34:37], v[194:197], v[218:221], v[34:37]
	v_mfma_f32_16x16x32_bf16 v[6:9], v[174:177], v[242:245], v[6:9]
	v_mfma_f32_16x16x32_bf16 v[14:17], v[194:197], v[242:245], v[14:17]
	s_setprio 0
	s_barrier
	s_add_i32 s57, s57, 2
	s_add_u32 s38, s38, 0x100
	s_addc_u32 s39, s39, 0
	s_cmpk_gt_u32 s57, 0x53
	s_mov_b64 s[26:27], s[28:29]
	s_cbranch_scc0 .LBB0_2241
	s_and_b64 vcc, exec, s[18:19]
	s_cbranch_vccz .LBB0_2244
	s_barrier

.LBB0_2293:
	s_add_u32 s30, s28, 0x100
	s_addc_u32 s31, s29, 0
	s_add_i32 s46, 0, 0x10000
	s_cmpk_eq_i32 s45, 0x52
	s_cselect_b32 s39, s25, s31
	s_cselect_b32 s38, s24, s30
	s_cselect_b32 s35, s27, s44
	s_cselect_b32 s34, s26, s43
	s_add_i32 s47, 0, 0x14000
	v_add_u32_e32 v142, s46, v200
	v_add_u32_e32 v176, s47, v200
	ds_read_b128 v[130:133], v142
	ds_read_b128 v[134:137], v142 offset:1024
	ds_read_b128 v[138:141], v142 offset:2048
	ds_read_b128 v[142:145], v142 offset:3072
	ds_read_b128 v[164:167], v176
	ds_read_b128 v[168:171], v176 offset:1024
	ds_read_b128 v[172:175], v176 offset:2048
	ds_read_b128 v[176:179], v176 offset:3072
	v_lshl_add_u64 v[222:223], s[28:29], 0, v[160:161]
	s_add_i32 m0, s56, 0xc000
	ds_read_b128 v[190:193], v201
	ds_read_b128 v[202:205], v201 offset:1024
	ds_read_b128 v[206:209], v201 offset:2048
	ds_read_b128 v[210:213], v201 offset:3072
	ds_read_b128 v[214:217], v201 offset:4096
	ds_read_b128 v[218:221], v201 offset:5120
	ds_read_b128 v[238:241], v201 offset:6144
	ds_read_b128 v[242:245], v201 offset:7168
	global_load_lds_dwordx4 v[222:223], off
	v_lshl_add_u64 v[222:223], s[28:29], 0, v[162:163]
	s_add_i32 m0, s56, 0xe000
	s_nop 0
	global_load_lds_dwordx4 v[222:223], off
	s_waitcnt vmcnt(8)
	s_waitcnt lgkmcnt(0)
	s_barrier
	s_setprio 1
	s_waitcnt lgkmcnt(0)
	v_mfma_f32_16x16x32_bf16 v[118:121], v[130:133], v[190:193], v[118:121]
	v_mfma_f32_16x16x32_bf16 v[114:117], v[138:141], v[190:193], v[114:117]
	v_mfma_f32_16x16x32_bf16 v[98:101], v[130:133], v[206:209], v[98:101]
	v_mfma_f32_16x16x32_bf16 v[102:105], v[138:141], v[206:209], v[102:105]
	v_mfma_f32_16x16x32_bf16 v[70:73], v[130:133], v[214:217], v[70:73]
	v_mfma_f32_16x16x32_bf16 v[74:77], v[138:141], v[214:217], v[74:77]
	v_mfma_f32_16x16x32_bf16 v[30:33], v[130:133], v[238:241], v[30:33]
	v_mfma_f32_16x16x32_bf16 v[34:37], v[138:141], v[238:241], v[34:37]
	v_mfma_f32_16x16x32_bf16 v[118:121], v[134:137], v[202:205], v[118:121]
	v_mfma_f32_16x16x32_bf16 v[114:117], v[142:145], v[202:205], v[114:117]
	v_mfma_f32_16x16x32_bf16 v[98:101], v[134:137], v[210:213], v[98:101]
	v_mfma_f32_16x16x32_bf16 v[102:105], v[142:145], v[210:213], v[102:105]
	v_mfma_f32_16x16x32_bf16 v[70:73], v[134:137], v[218:221], v[70:73]
	v_mfma_f32_16x16x32_bf16 v[74:77], v[142:145], v[218:221], v[74:77]
	v_mfma_f32_16x16x32_bf16 v[30:33], v[134:137], v[242:245], v[30:33]
	v_mfma_f32_16x16x32_bf16 v[34:37], v[142:145], v[242:245], v[34:37]
	v_mfma_f32_16x16x32_bf16 v[126:129], v[164:167], v[190:193], v[126:129]
	v_mfma_f32_16x16x32_bf16 v[122:125], v[172:175], v[190:193], v[122:125]
	v_mfma_f32_16x16x32_bf16 v[106:109], v[164:167], v[206:209], v[106:109]
	v_mfma_f32_16x16x32_bf16 v[110:113], v[172:175], v[206:209], v[110:113]
	v_mfma_f32_16x16x32_bf16 v[82:85], v[164:167], v[214:217], v[82:85]
	v_mfma_f32_16x16x32_bf16 v[86:89], v[172:175], v[214:217], v[86:89]
	v_mfma_f32_16x16x32_bf16 v[54:57], v[164:167], v[238:241], v[54:57]
	v_mfma_f32_16x16x32_bf16 v[58:61], v[172:175], v[238:241], v[58:61]
	v_mfma_f32_16x16x32_bf16 v[126:129], v[168:171], v[202:205], v[126:129]
	v_mfma_f32_16x16x32_bf16 v[122:125], v[176:179], v[202:205], v[122:125]
	v_mfma_f32_16x16x32_bf16 v[106:109], v[168:171], v[210:213], v[106:109]
	v_mfma_f32_16x16x32_bf16 v[110:113], v[176:179], v[210:213], v[110:113]
	v_mfma_f32_16x16x32_bf16 v[82:85], v[168:171], v[218:221], v[82:85]
	v_mfma_f32_16x16x32_bf16 v[86:89], v[176:179], v[218:221], v[86:89]
	v_mfma_f32_16x16x32_bf16 v[54:57], v[168:171], v[242:245], v[54:57]
	v_mfma_f32_16x16x32_bf16 v[58:61], v[176:179], v[242:245], v[58:61]
	s_setprio 0
	s_barrier
	s_add_i32 s28, s46, s21
	v_lshl_add_u64 v[222:223], s[34:35], 0, v[150:151]
	s_mov_b32 m0, s28
	ds_read_b128 v[190:193], v201 offset:16384
	ds_read_b128 v[202:205], v201 offset:17408
	ds_read_b128 v[206:209], v201 offset:18432
	ds_read_b128 v[210:213], v201 offset:19456
	ds_read_b128 v[214:217], v201 offset:20480
	ds_read_b128 v[218:221], v201 offset:21504
	ds_read_b128 v[238:241], v201 offset:22528
	ds_read_b128 v[242:245], v201 offset:23552
	global_load_lds_dwordx4 v[222:223], off
	s_add_i32 m0, s28, 0x2000
	s_add_u32 s28, s34, 0x158000
	v_lshl_add_u64 v[246:247], s[34:35], 0, v[154:155]
	s_addc_u32 s29, s35, 0
	s_add_i32 s46, s47, s21
	global_load_lds_dwordx4 v[246:247], off
	v_lshl_add_u64 v[248:249], s[28:29], 0, v[150:151]
	s_mov_b32 m0, s46
	v_lshl_add_u64 v[250:251], s[38:39], 0, v[152:153]
	global_load_lds_dwordx4 v[248:249], off
	v_lshl_add_u64 v[248:249], s[28:29], 0, v[154:155]
	s_add_i32 m0, s46, 0x2000
	s_nop 0
	global_load_lds_dwordx4 v[248:249], off
	v_lshl_add_u64 v[248:249], s[38:39], 0, v[148:149]
	s_mov_b32 m0, s56
	s_nop 0
	global_load_lds_dwordx4 v[248:249], off
	s_mov_b32 m0, s57
	s_nop 0
	global_load_lds_dwordx4 v[250:251], off
	s_waitcnt vmcnt(8)
	s_waitcnt lgkmcnt(0)
	s_barrier
	s_setprio 1
	s_waitcnt lgkmcnt(0)
	v_mfma_f32_16x16x32_bf16 v[22:25], v[130:133], v[190:193], v[22:25]
	v_mfma_f32_16x16x32_bf16 v[26:29], v[138:141], v[190:193], v[26:29]
	v_mfma_f32_16x16x32_bf16 v[10:13], v[130:133], v[206:209], v[10:13]
	v_mfma_f32_16x16x32_bf16 v[78:81], v[138:141], v[206:209], v[78:81]
	v_mfma_f32_16x16x32_bf16 v[38:41], v[130:133], v[214:217], v[38:41]
	v_mfma_f32_16x16x32_bf16 v[42:45], v[138:141], v[214:217], v[42:45]
	v_mfma_f32_16x16x32_bf16 v[2:5], v[130:133], v[238:241], v[2:5]
	v_mfma_f32_16x16x32_bf16 v[6:9], v[138:141], v[238:241], v[6:9]
	v_mfma_f32_16x16x32_bf16 v[22:25], v[134:137], v[202:205], v[22:25]
	v_mfma_f32_16x16x32_bf16 v[26:29], v[142:145], v[202:205], v[26:29]
	v_mfma_f32_16x16x32_bf16 v[10:13], v[134:137], v[210:213], v[10:13]
	v_mfma_f32_16x16x32_bf16 v[78:81], v[142:145], v[210:213], v[78:81]
	v_mfma_f32_16x16x32_bf16 v[38:41], v[134:137], v[218:221], v[38:41]
	v_mfma_f32_16x16x32_bf16 v[42:45], v[142:145], v[218:221], v[42:45]
	v_mfma_f32_16x16x32_bf16 v[2:5], v[134:137], v[242:245], v[2:5]
	v_mfma_f32_16x16x32_bf16 v[6:9], v[142:145], v[242:245], v[6:9]
	v_mfma_f32_16x16x32_bf16 v[46:49], v[164:167], v[190:193], v[46:49]
	v_mfma_f32_16x16x32_bf16 v[50:53], v[172:175], v[190:193], v[50:53]
	v_mfma_f32_16x16x32_bf16 v[90:93], v[164:167], v[206:209], v[90:93]
	v_mfma_f32_16x16x32_bf16 v[94:97], v[172:175], v[206:209], v[94:97]
	v_mfma_f32_16x16x32_bf16 v[62:65], v[164:167], v[214:217], v[62:65]
	v_mfma_f32_16x16x32_bf16 v[66:69], v[172:175], v[214:217], v[66:69]
	v_mfma_f32_16x16x32_bf16 v[14:17], v[164:167], v[238:241], v[14:17]
	v_mfma_f32_16x16x32_bf16 v[18:21], v[172:175], v[238:241], v[18:21]
	v_mfma_f32_16x16x32_bf16 v[46:49], v[168:171], v[202:205], v[46:49]
	v_mfma_f32_16x16x32_bf16 v[50:53], v[176:179], v[202:205], v[50:53]
	v_mfma_f32_16x16x32_bf16 v[90:93], v[168:171], v[210:213], v[90:93]
	v_mfma_f32_16x16x32_bf16 v[94:97], v[176:179], v[210:213], v[94:97]
	v_mfma_f32_16x16x32_bf16 v[62:65], v[168:171], v[218:221], v[62:65]
	v_mfma_f32_16x16x32_bf16 v[66:69], v[176:179], v[218:221], v[66:69]
	v_mfma_f32_16x16x32_bf16 v[14:17], v[168:171], v[242:245], v[14:17]
	v_mfma_f32_16x16x32_bf16 v[18:21], v[176:179], v[242:245], v[18:21]
	s_setprio 0
	s_barrier
	s_add_i32 s46, 0, 0x18000
	s_add_i32 s47, 0, 0x1c000
	v_add_u32_e32 v142, s46, v200
	v_add_u32_e32 v176, s47, v200
	ds_read_b128 v[130:133], v142
	ds_read_b128 v[134:137], v142 offset:1024
	ds_read_b128 v[138:141], v142 offset:2048
	ds_read_b128 v[142:145], v142 offset:3072
	ds_read_b128 v[164:167], v176
	ds_read_b128 v[168:171], v176 offset:1024
	ds_read_b128 v[172:175], v176 offset:2048
	ds_read_b128 v[176:179], v176 offset:3072
	s_add_u32 s28, s38, 0x158000
	s_addc_u32 s29, s39, 0
	s_mov_b32 m0, s58
	v_lshl_add_u64 v[252:253], s[28:29], 0, v[148:149]
	ds_read_b128 v[190:193], v201 offset:32768
	ds_read_b128 v[202:205], v201 offset:33792
	ds_read_b128 v[206:209], v201 offset:34816
	ds_read_b128 v[210:213], v201 offset:35840
	ds_read_b128 v[214:217], v201 offset:36864
	ds_read_b128 v[218:221], v201 offset:37888
	ds_read_b128 v[238:241], v201 offset:38912
	ds_read_b128 v[242:245], v201 offset:39936
	global_load_lds_dwordx4 v[252:253], off
	v_lshl_add_u64 v[252:253], s[28:29], 0, v[152:153]
	s_mov_b32 m0, s59
	s_nop 0
	global_load_lds_dwordx4 v[252:253], off
	s_waitcnt vmcnt(8)
	s_waitcnt lgkmcnt(0)
	s_barrier
	s_setprio 1
	s_waitcnt lgkmcnt(0)
	v_mfma_f32_16x16x32_bf16 v[118:121], v[130:133], v[190:193], v[118:121]
	v_mfma_f32_16x16x32_bf16 v[114:117], v[138:141], v[190:193], v[114:117]
	v_mfma_f32_16x16x32_bf16 v[98:101], v[130:133], v[206:209], v[98:101]
	v_mfma_f32_16x16x32_bf16 v[102:105], v[138:141], v[206:209], v[102:105]
	v_mfma_f32_16x16x32_bf16 v[70:73], v[130:133], v[214:217], v[70:73]
	v_mfma_f32_16x16x32_bf16 v[74:77], v[138:141], v[214:217], v[74:77]
	v_mfma_f32_16x16x32_bf16 v[30:33], v[130:133], v[238:241], v[30:33]
	v_mfma_f32_16x16x32_bf16 v[34:37], v[138:141], v[238:241], v[34:37]
	v_mfma_f32_16x16x32_bf16 v[118:121], v[134:137], v[202:205], v[118:121]
	v_mfma_f32_16x16x32_bf16 v[114:117], v[142:145], v[202:205], v[114:117]
	v_mfma_f32_16x16x32_bf16 v[98:101], v[134:137], v[210:213], v[98:101]
	v_mfma_f32_16x16x32_bf16 v[102:105], v[142:145], v[210:213], v[102:105]
	v_mfma_f32_16x16x32_bf16 v[70:73], v[134:137], v[218:221], v[70:73]
	v_mfma_f32_16x16x32_bf16 v[74:77], v[142:145], v[218:221], v[74:77]
	v_mfma_f32_16x16x32_bf16 v[30:33], v[134:137], v[242:245], v[30:33]
	v_mfma_f32_16x16x32_bf16 v[34:37], v[142:145], v[242:245], v[34:37]
	v_mfma_f32_16x16x32_bf16 v[126:129], v[164:167], v[190:193], v[126:129]
	v_mfma_f32_16x16x32_bf16 v[122:125], v[172:175], v[190:193], v[122:125]
	v_mfma_f32_16x16x32_bf16 v[106:109], v[164:167], v[206:209], v[106:109]
	v_mfma_f32_16x16x32_bf16 v[110:113], v[172:175], v[206:209], v[110:113]
	v_mfma_f32_16x16x32_bf16 v[82:85], v[164:167], v[214:217], v[82:85]
	v_mfma_f32_16x16x32_bf16 v[86:89], v[172:175], v[214:217], v[86:89]
	v_mfma_f32_16x16x32_bf16 v[54:57], v[164:167], v[238:241], v[54:57]
	v_mfma_f32_16x16x32_bf16 v[58:61], v[172:175], v[238:241], v[58:61]
	v_mfma_f32_16x16x32_bf16 v[126:129], v[168:171], v[202:205], v[126:129]
	v_mfma_f32_16x16x32_bf16 v[122:125], v[176:179], v[202:205], v[122:125]
	v_mfma_f32_16x16x32_bf16 v[106:109], v[168:171], v[210:213], v[106:109]
	v_mfma_f32_16x16x32_bf16 v[110:113], v[176:179], v[210:213], v[110:113]
	v_mfma_f32_16x16x32_bf16 v[82:85], v[168:171], v[218:221], v[82:85]
	v_mfma_f32_16x16x32_bf16 v[86:89], v[176:179], v[218:221], v[86:89]
	v_mfma_f32_16x16x32_bf16 v[54:57], v[168:171], v[242:245], v[54:57]
	v_mfma_f32_16x16x32_bf16 v[58:61], v[176:179], v[242:245], v[58:61]
	s_setprio 0
	s_barrier
	s_add_i32 s28, s46, s21
	v_lshl_add_u64 v[222:223], v[222:223], 0, s[16:17]
	s_mov_b32 m0, s28
	ds_read_b128 v[190:193], v201 offset:49152
	ds_read_b128 v[202:205], v201 offset:50176
	ds_read_b128 v[206:209], v201 offset:51200
	ds_read_b128 v[210:213], v201 offset:52224
	ds_read_b128 v[214:217], v201 offset:53248
	ds_read_b128 v[218:221], v201 offset:54272
	ds_read_b128 v[238:241], v201 offset:55296
	ds_read_b128 v[242:245], v201 offset:56320
	global_load_lds_dwordx4 v[222:223], off
	s_add_i32 m0, s28, 0x2000
	s_add_u32 s28, s34, 0x158080
	v_lshl_add_u64 v[222:223], v[246:247], 0, s[16:17]
	s_addc_u32 s29, s35, 0
	s_add_i32 s34, s47, s21
	global_load_lds_dwordx4 v[222:223], off
	v_lshl_add_u64 v[222:223], s[28:29], 0, v[150:151]
	s_mov_b32 m0, s34
	s_nop 0
	global_load_lds_dwordx4 v[222:223], off
	v_lshl_add_u64 v[222:223], s[28:29], 0, v[154:155]
	s_add_i32 m0, s34, 0x2000
	s_nop 0
	global_load_lds_dwordx4 v[222:223], off
	v_lshl_add_u64 v[222:223], v[248:249], 0, s[16:17]
	s_mov_b32 m0, s60
	s_nop 0
	global_load_lds_dwordx4 v[222:223], off
	v_lshl_add_u64 v[222:223], v[250:251], 0, s[16:17]
	s_mov_b32 m0, s61
	s_nop 0
	global_load_lds_dwordx4 v[222:223], off
	s_waitcnt vmcnt(8)
	s_waitcnt lgkmcnt(0)
	s_barrier
	s_setprio 1
	s_waitcnt lgkmcnt(0)
	v_mfma_f32_16x16x32_bf16 v[22:25], v[130:133], v[190:193], v[22:25]
	v_mfma_f32_16x16x32_bf16 v[26:29], v[138:141], v[190:193], v[26:29]
	v_mfma_f32_16x16x32_bf16 v[10:13], v[130:133], v[206:209], v[10:13]
	v_mfma_f32_16x16x32_bf16 v[78:81], v[138:141], v[206:209], v[78:81]
	v_mfma_f32_16x16x32_bf16 v[38:41], v[130:133], v[214:217], v[38:41]
	v_mfma_f32_16x16x32_bf16 v[42:45], v[138:141], v[214:217], v[42:45]
	v_mfma_f32_16x16x32_bf16 v[2:5], v[130:133], v[238:241], v[2:5]
	v_mfma_f32_16x16x32_bf16 v[6:9], v[138:141], v[238:241], v[6:9]
	v_mfma_f32_16x16x32_bf16 v[22:25], v[134:137], v[202:205], v[22:25]
	v_mfma_f32_16x16x32_bf16 v[26:29], v[142:145], v[202:205], v[26:29]
	v_mfma_f32_16x16x32_bf16 v[10:13], v[134:137], v[210:213], v[10:13]
	v_mfma_f32_16x16x32_bf16 v[78:81], v[142:145], v[210:213], v[78:81]
	v_mfma_f32_16x16x32_bf16 v[38:41], v[134:137], v[218:221], v[38:41]
	v_mfma_f32_16x16x32_bf16 v[42:45], v[142:145], v[218:221], v[42:45]
	v_mfma_f32_16x16x32_bf16 v[2:5], v[134:137], v[242:245], v[2:5]
	v_mfma_f32_16x16x32_bf16 v[6:9], v[142:145], v[242:245], v[6:9]
	v_mfma_f32_16x16x32_bf16 v[46:49], v[164:167], v[190:193], v[46:49]
	v_mfma_f32_16x16x32_bf16 v[50:53], v[172:175], v[190:193], v[50:53]
	v_mfma_f32_16x16x32_bf16 v[90:93], v[164:167], v[206:209], v[90:93]
	v_mfma_f32_16x16x32_bf16 v[94:97], v[172:175], v[206:209], v[94:97]
	v_mfma_f32_16x16x32_bf16 v[62:65], v[164:167], v[214:217], v[62:65]
	v_mfma_f32_16x16x32_bf16 v[66:69], v[172:175], v[214:217], v[66:69]
	v_mfma_f32_16x16x32_bf16 v[14:17], v[164:167], v[238:241], v[14:17]
	v_mfma_f32_16x16x32_bf16 v[18:21], v[172:175], v[238:241], v[18:21]
	v_mfma_f32_16x16x32_bf16 v[46:49], v[168:171], v[202:205], v[46:49]
	v_mfma_f32_16x16x32_bf16 v[50:53], v[176:179], v[202:205], v[50:53]
	v_mfma_f32_16x16x32_bf16 v[90:93], v[168:171], v[210:213], v[90:93]
	v_mfma_f32_16x16x32_bf16 v[94:97], v[176:179], v[210:213], v[94:97]
	v_mfma_f32_16x16x32_bf16 v[62:65], v[168:171], v[218:221], v[62:65]
	v_mfma_f32_16x16x32_bf16 v[66:69], v[176:179], v[218:221], v[66:69]
	v_mfma_f32_16x16x32_bf16 v[14:17], v[168:171], v[242:245], v[14:17]
	v_mfma_f32_16x16x32_bf16 v[18:21], v[176:179], v[242:245], v[18:21]
	s_setprio 0
	s_barrier
	s_add_i32 s45, s45, 2
	s_add_u32 s43, s43, 0x100
	s_addc_u32 s44, s44, 0
	s_cmpk_gt_u32 s45, 0x53
	s_mov_b64 s[28:29], s[30:31]
	s_cbranch_scc0 .LBB0_2293
	s_and_b64 vcc, exec, s[22:23]
	s_cbranch_vccz .LBB0_2296
	s_barrier
